# GEMM epilogues (SwiGLU, LRU-in): per-row rs loads hoisted to epilogue start, vmcnt(0) per row replaced by counted waits so stores stay in flight; attention: first PV tr-read group issued at end of QK
# speedup vs baseline: 1.0228x; 1.0076x over previous
; __device__ __forceinline__ void partialSM(f32x16& p0, f32x16& p1, float& m_reg, float& mn, float& alpha) {
;     ...
;   for (int r = 0; r < 16; ++r) p0[r] = __builtin_amdgcn_exp2f(p0[r]);
; }
; __device__ __forceinline__ void partialSM_fixed(f32x16& p0) {
;   for (int r = 0; r < 16; ++r) p0[r] = __builtin_amdgcn_exp2f(p0[r]);
; }
; __device__ __forceinline__ void finishSM(f32x16& p0, f32x16& p1, float alpha, float& l_reg, bf16x8& pa0, bf16x8& pa1, bf16x8& pa2, bf16x8& pa3) {
;   for (int r = 0; r < 16; ++r) p1[r] = __builtin_amdgcn_exp2f(p1[r]);
;   float ps = 0; for (int r = 0; r < 16; ++r) ps += p0[r]; for (int r = 0; r < 16; ++r) ps += p1[r];
; template <int BOFF> __device__ __forceinline__ void qkt_i(f32x16& p0, f32x16& p1, const int (&kb)[4], const bf16x8* qr) {
;   p0 = f32x16{}; p1 = f32x16{};
; #pragma unroll
;   for (int d0 = 0; d0 < 8; ++d0) { const int off = BOFF + (d0 >> 2) * 128;
;     const bf16x8 b0 = LDSV(kb[d0 & 3] + off), b1 = LDSV(kb[d0 & 3] + off + 8192);
;     p0 = __builtin_amdgcn_mfma_f32_32x32x16_bf16(b0, qr[d0], p0, 0, 0, 0);
;     p1 = __builtin_amdgcn_mfma_f32_32x32x16_bf16(b1, qr[d0], p1, 0, 0, 0); }
; }
; template <int D0, int BOFF> __device__ __forceinline__ void pv_one_i(f32x16& od, int vb, bf16x8 pa0, bf16x8 pa1, bf16x8 pa2, bf16x8 pa3) {
;   const s16x4 l0 = tr_read<BOFF + v_rd_off(D0, 0, 0)>(vb), h0 = tr_read<BOFF + v_rd_off(D0, 0, 1)>(vb), l1 = tr_read<BOFF + v_rd_off(D0, 1, 0)>(vb), h1 = tr_read<BOFF + v_rd_off(D0, 1, 1)>(vb);
;   const s16x4 l2 = tr_read<BOFF + v_rd_off(D0, 2, 0)>(vb), h2 = tr_read<BOFF + v_rd_off(D0, 2, 1)>(vb), l3 = tr_read<BOFF + v_rd_off(D0, 3, 0)>(vb), h3 = tr_read<BOFF + v_rd_off(D0, 3, 1)>(vb);
;   asm volatile("s_waitcnt lgkmcnt(0)" ::: "memory"); SBAR();
;     ...
;   od = __builtin_amdgcn_mfma_f32_32x32x16_bf16(pa0, PK(l0, h0), od, 0, 0, 0);
;   od = __builtin_amdgcn_mfma_f32_32x32x16_bf16(pa1, PK(l1, h1), od, 0, 0, 0);
;   od = __builtin_amdgcn_mfma_f32_32x32x16_bf16(pa2, PK(l2, h2), od, 0, 0, 0);
;   od = __builtin_amdgcn_mfma_f32_32x32x16_bf16(pa3, PK(l3, h3), od, 0, 0, 0);
;     ...
; }
; template <int BOFF> __device__ __forceinline__ void pv_i(f32x16* o, int vb, bf16x8 pa0, bf16x8 pa1, bf16x8 pa2, bf16x8 pa3) {
;   pv_one_i<0, BOFF>(o[0], vb, pa0, pa1, pa2, pa3); pv_one_i<1, BOFF>(o[1], vb, pa0, pa1, pa2, pa3); pv_one_i<2, BOFF>(o[2], vb, pa0, pa1, pa2, pa3); pv_one_i<3, BOFF>(o[3], vb, pa0, pa1, pa2, pa3);
; }
.LBB0_352:
	s_waitcnt lgkmcnt(0)
	s_barrier
	ds_read_b128 v[80:83], v207 offset:16384
	ds_read_b128 v[84:87], v207 offset:24576
	ds_read_b128 v[162:165], v208 offset:16384
	ds_read_b128 v[166:169], v208 offset:24576
	v_exp_f32_e32 v170, v72
	v_exp_f32_e32 v171, v73
	v_exp_f32_e32 v172, v74
	v_exp_f32_e32 v173, v75
	v_exp_f32_e32 v174, v76
	v_exp_f32_e32 v175, v77
	v_exp_f32_e32 v176, v78
	v_exp_f32_e32 v79, v79
	s_waitcnt lgkmcnt(3)
	v_mfma_f32_32x32x16_bf16 v[96:111], v[80:83], v[142:145], 0
	v_exp_f32_e32 v236, v64
	v_add_f32_e32 v64, 0, v229
	v_add_f32_e32 v64, v243, v64
	v_add_f32_e32 v64, v244, v64
	s_waitcnt lgkmcnt(2)
	v_mfma_f32_32x32x16_bf16 v[80:95], v[84:87], v[142:145], 0
	v_add_f32_e32 v64, v246, v64
	v_add_f32_e32 v64, v242, v64
	v_add_f32_e32 v64, v245, v64
	s_waitcnt lgkmcnt(1)
	v_mfma_f32_32x32x16_bf16 v[96:111], v[162:165], v[138:141], v[96:111]
	v_add_f32_e32 v64, v227, v64
	v_add_f32_e32 v64, v228, v64
	v_add_f32_e32 v64, v223, v64
	s_waitcnt lgkmcnt(0)
	v_mfma_f32_32x32x16_bf16 v[80:95], v[166:169], v[138:141], v[80:95]
	ds_read_b128 v[162:165], v209 offset:16384
	ds_read_b128 v[166:169], v209 offset:24576
	v_add_f32_e32 v64, v226, v64
	v_add_f32_e32 v64, v224, v64
	v_add_f32_e32 v64, v225, v64
	v_add_f32_e32 v64, v220, v64
	v_exp_f32_e32 v237, v65
	s_waitcnt lgkmcnt(1)
	v_mfma_f32_32x32x16_bf16 v[96:111], v[162:165], v[112:115], v[96:111]
	v_add_f32_e32 v64, v222, v64
	v_exp_f32_e32 v238, v66
	v_add_f32_e32 v64, v219, v64
	v_exp_f32_e32 v239, v67
	s_waitcnt lgkmcnt(0)
	v_mfma_f32_32x32x16_bf16 v[80:95], v[166:169], v[112:115], v[80:95]
	ds_read_b128 v[162:165], v210 offset:16384
	ds_read_b128 v[166:169], v210 offset:24576
	v_add_f32_e32 v64, v221, v64
	v_exp_f32_e32 v247, v68
	v_add_f32_e32 v64, v236, v64
	v_exp_f32_e32 v248, v69
	s_waitcnt lgkmcnt(1)
	v_mfma_f32_32x32x16_bf16 v[96:111], v[162:165], v[116:119], v[96:111]
	v_add_f32_e32 v64, v237, v64
	v_exp_f32_e32 v249, v70
	v_add_f32_e32 v64, v238, v64
	v_exp_f32_e32 v252, v71
	s_waitcnt lgkmcnt(0)
	v_mfma_f32_32x32x16_bf16 v[80:95], v[166:169], v[116:119], v[80:95]
	ds_read_b128 v[162:165], v190 offset:16384
	ds_read_b128 v[166:169], v190 offset:24576
	v_add_f32_e32 v64, v239, v64
	v_add_f32_e32 v64, v247, v64
	v_add_f32_e32 v64, v248, v64
	v_add_f32_e32 v64, v249, v64
	v_add_f32_e32 v64, v252, v64
	v_add_f32_e32 v64, v170, v64
	s_waitcnt lgkmcnt(1)
	v_mfma_f32_32x32x16_bf16 v[96:111], v[162:165], v[120:123], v[96:111]
	v_add_f32_e32 v64, v171, v64
	v_add_f32_e32 v64, v172, v64
	v_add_f32_e32 v64, v173, v64
	v_add_f32_e32 v64, v174, v64
	v_add_f32_e32 v64, v175, v64
	s_waitcnt lgkmcnt(0)
	v_mfma_f32_32x32x16_bf16 v[80:95], v[166:169], v[120:123], v[80:95]
	ds_read_b128 v[162:165], v191 offset:16384
	ds_read_b128 v[166:169], v191 offset:24576
	v_add_f32_e32 v64, v176, v64
	v_add_f32_e32 v64, v79, v64
	v_mov_b32_e32 v65, v64
	s_nop 1
	v_permlane32_swap_b32_e32 v64, v65
	v_add_f32_e32 v64, v64, v65
	s_waitcnt lgkmcnt(1)
	v_mfma_f32_32x32x16_bf16 v[96:111], v[162:165], v[124:127], v[96:111]
	v_add_f32_e32 v128, v215, v64
	v_cvt_pk_bf16_f32 v64, v229, v243
	v_cvt_pk_bf16_f32 v65, v244, v246
	v_cvt_pk_bf16_f32 v66, v242, v245
	v_cvt_pk_bf16_f32 v67, v227, v228
	s_waitcnt lgkmcnt(0)
	v_mfma_f32_32x32x16_bf16 v[80:95], v[166:169], v[124:127], v[80:95]
	ds_read_b128 v[162:165], v192 offset:16384
	ds_read_b128 v[166:169], v192 offset:24576
	v_cvt_pk_bf16_f32 v68, v223, v226
	v_cvt_pk_bf16_f32 v69, v224, v225
	v_cvt_pk_bf16_f32 v70, v220, v222
	v_cvt_pk_bf16_f32 v71, v219, v221
	v_cvt_pk_bf16_f32 v72, v236, v237
	v_cvt_pk_bf16_f32 v73, v238, v239
	s_waitcnt lgkmcnt(1)
	v_mfma_f32_32x32x16_bf16 v[96:111], v[162:165], v[130:133], v[96:111]
	v_cvt_pk_bf16_f32 v74, v247, v248
	v_cvt_pk_bf16_f32 v75, v249, v252
	v_cvt_pk_bf16_f32 v76, v170, v171
	v_cvt_pk_bf16_f32 v77, v172, v173
	v_cvt_pk_bf16_f32 v78, v174, v175
	s_waitcnt lgkmcnt(0)
	v_mfma_f32_32x32x16_bf16 v[80:95], v[166:169], v[130:133], v[80:95]
	ds_read_b128 v[162:165], v193 offset:16384
	ds_read_b128 v[166:169], v193 offset:24576
	ds_read_b64_tr_b16 v[180:181], v206 offset:0
	ds_read_b64_tr_b16 v[182:183], v206 offset:0x800
	ds_read_b64_tr_b16 v[184:185], v206 offset:0x1000
	ds_read_b64_tr_b16 v[186:187], v206 offset:0x1800
	ds_read_b64_tr_b16 v[216:217], v206 offset:0x2000
	ds_read_b64_tr_b16 v[218:219], v206 offset:0x2800
	ds_read_b64_tr_b16 v[220:221], v206 offset:0x3000
	ds_read_b64_tr_b16 v[222:223], v206 offset:0x3800
	v_cvt_pk_bf16_f32 v79, v176, v79
	s_nop 0
	v_permlane32_swap_b32_e32 v64, v66
	v_permlane32_swap_b32_e32 v65, v67
	v_permlane32_swap_b32_e32 v68, v70
	v_permlane32_swap_b32_e32 v69, v71
	s_waitcnt lgkmcnt(9)
	v_mfma_f32_32x32x16_bf16 v[96:111], v[162:165], v[134:137], v[96:111]
	v_permlane32_swap_b32_e32 v72, v74
	v_permlane32_swap_b32_e32 v73, v75
	v_permlane32_swap_b32_e32 v76, v78
	v_permlane32_swap_b32_e32 v77, v79
	s_waitcnt lgkmcnt(8)
	v_mfma_f32_32x32x16_bf16 v[80:95], v[166:169], v[134:137], v[80:95]
	v_add_co_u32_e32 v166, vcc, s19, v178
	s_nop 1
	v_addc_co_u32_e32 v167, vcc, -1, v179, vcc
	v_add_co_u32_e32 v170, vcc, s20, v178
	s_nop 1
	v_addc_co_u32_e32 v171, vcc, -1, v179, vcc
	global_load_dwordx4 v[162:165], v[166:167], off
	s_nop 0
	global_load_dwordx4 v[166:169], v[166:167], off offset:-512
	s_nop 0
	global_load_dwordx4 v[174:177], v[170:171], off
	s_nop 0
	global_load_dwordx4 v[170:173], v[170:171], off offset:-512
	s_waitcnt lgkmcnt(0)
	s_waitcnt vmcnt(4)
; __device__ __forceinline__ void partialSM(f32x16& p0, f32x16& p1, float& m_reg, float& mn, float& alpha) {
;     ...
;   for (int r = 0; r < 16; ++r) p0[r] = __builtin_amdgcn_exp2f(p0[r]);
; }
; __device__ __forceinline__ void partialSM_fixed(f32x16& p0) {
;   for (int r = 0; r < 16; ++r) p0[r] = __builtin_amdgcn_exp2f(p0[r]);
; }
; __device__ __forceinline__ void finishSM(f32x16& p0, f32x16& p1, float alpha, float& l_reg, bf16x8& pa0, bf16x8& pa1, bf16x8& pa2, bf16x8& pa3) {
;   for (int r = 0; r < 16; ++r) p1[r] = __builtin_amdgcn_exp2f(p1[r]);
;   float ps = 0; for (int r = 0; r < 16; ++r) ps += p0[r]; for (int r = 0; r < 16; ++r) ps += p1[r];
; template <int BOFF> __device__ __forceinline__ void qkt_i(f32x16& p0, f32x16& p1, const int (&kb)[4], const bf16x8* qr) {
;   p0 = f32x16{}; p1 = f32x16{};
; #pragma unroll
;   for (int d0 = 0; d0 < 8; ++d0) { const int off = BOFF + (d0 >> 2) * 128;
;     const bf16x8 b0 = LDSV(kb[d0 & 3] + off), b1 = LDSV(kb[d0 & 3] + off + 8192);
;     p0 = __builtin_amdgcn_mfma_f32_32x32x16_bf16(b0, qr[d0], p0, 0, 0, 0);
;     p1 = __builtin_amdgcn_mfma_f32_32x32x16_bf16(b1, qr[d0], p1, 0, 0, 0); }
; }
; template <int D0, int BOFF> __device__ __forceinline__ void pv_one_i(f32x16& od, int vb, bf16x8 pa0, bf16x8 pa1, bf16x8 pa2, bf16x8 pa3) {
;   const s16x4 l0 = tr_read<BOFF + v_rd_off(D0, 0, 0)>(vb), h0 = tr_read<BOFF + v_rd_off(D0, 0, 1)>(vb), l1 = tr_read<BOFF + v_rd_off(D0, 1, 0)>(vb), h1 = tr_read<BOFF + v_rd_off(D0, 1, 1)>(vb);
;   const s16x4 l2 = tr_read<BOFF + v_rd_off(D0, 2, 0)>(vb), h2 = tr_read<BOFF + v_rd_off(D0, 2, 1)>(vb), l3 = tr_read<BOFF + v_rd_off(D0, 3, 0)>(vb), h3 = tr_read<BOFF + v_rd_off(D0, 3, 1)>(vb);
;   asm volatile("s_waitcnt lgkmcnt(0)" ::: "memory"); SBAR();
;     ...
;   od = __builtin_amdgcn_mfma_f32_32x32x16_bf16(pa0, PK(l0, h0), od, 0, 0, 0);
;   od = __builtin_amdgcn_mfma_f32_32x32x16_bf16(pa1, PK(l1, h1), od, 0, 0, 0);
;   od = __builtin_amdgcn_mfma_f32_32x32x16_bf16(pa2, PK(l2, h2), od, 0, 0, 0);
;   od = __builtin_amdgcn_mfma_f32_32x32x16_bf16(pa3, PK(l3, h3), od, 0, 0, 0);
;     ...
; }
; template <int BOFF> __device__ __forceinline__ void pv_i(f32x16* o, int vb, bf16x8 pa0, bf16x8 pa1, bf16x8 pa2, bf16x8 pa3) {
;   pv_one_i<0, BOFF>(o[0], vb, pa0, pa1, pa2, pa3); pv_one_i<1, BOFF>(o[1], vb, pa0, pa1, pa2, pa3); pv_one_i<2, BOFF>(o[2], vb, pa0, pa1, pa2, pa3); pv_one_i<3, BOFF>(o[3], vb, pa0, pa1, pa2, pa3);
; }
	ds_write_b128 v211, v[146:149] offset:32768
	s_nop 0
	v_mfma_f32_32x32x16_bf16 v[0:15], v[64:67], v[180:183], v[0:15]
	ds_read_b64_tr_b16 v[180:181], v206 offset:0x200
	ds_read_b64_tr_b16 v[182:183], v206 offset:0xa00
	v_mfma_f32_32x32x16_bf16 v[0:15], v[68:71], v[184:187], v[0:15]
	ds_read_b64_tr_b16 v[184:185], v206 offset:0x1200
	ds_read_b64_tr_b16 v[186:187], v206 offset:0x1a00
	v_mfma_f32_32x32x16_bf16 v[0:15], v[72:75], v[216:219], v[0:15]
	ds_read_b64_tr_b16 v[216:217], v206 offset:0x2200
	ds_read_b64_tr_b16 v[218:219], v206 offset:0x2a00
	v_mfma_f32_32x32x16_bf16 v[0:15], v[76:79], v[220:223], v[0:15]
	ds_read_b64_tr_b16 v[220:221], v206 offset:0x3200
	ds_read_b64_tr_b16 v[222:223], v206 offset:0x3a00
	s_waitcnt lgkmcnt(0)
	ds_write_b128 v212, v[150:153] offset:32768
	v_mfma_f32_32x32x16_bf16 v[16:31], v[64:67], v[180:183], v[16:31]
	ds_read_b64_tr_b16 v[180:181], v206 offset:0x400
	ds_read_b64_tr_b16 v[182:183], v206 offset:0xc00
	v_mfma_f32_32x32x16_bf16 v[16:31], v[68:71], v[184:187], v[16:31]
	ds_read_b64_tr_b16 v[184:185], v206 offset:0x1400
	ds_read_b64_tr_b16 v[186:187], v206 offset:0x1c00
	v_mfma_f32_32x32x16_bf16 v[16:31], v[72:75], v[216:219], v[16:31]
	ds_read_b64_tr_b16 v[216:217], v206 offset:0x2400
	ds_read_b64_tr_b16 v[218:219], v206 offset:0x2c00
	v_mfma_f32_32x32x16_bf16 v[16:31], v[76:79], v[220:223], v[16:31]
	ds_read_b64_tr_b16 v[220:221], v206 offset:0x3400
	ds_read_b64_tr_b16 v[222:223], v206 offset:0x3c00
	s_waitcnt lgkmcnt(0)
	ds_write_b128 v213, v[154:157] offset:32768
	v_mfma_f32_32x32x16_bf16 v[32:47], v[64:67], v[180:183], v[32:47]
	ds_read_b64_tr_b16 v[180:181], v206 offset:0x600
	ds_read_b64_tr_b16 v[182:183], v206 offset:0xe00
	v_mfma_f32_32x32x16_bf16 v[32:47], v[68:71], v[184:187], v[32:47]
	ds_read_b64_tr_b16 v[184:185], v206 offset:0x1600
	ds_read_b64_tr_b16 v[186:187], v206 offset:0x1e00
	v_mfma_f32_32x32x16_bf16 v[32:47], v[72:75], v[216:219], v[32:47]
	ds_read_b64_tr_b16 v[216:217], v206 offset:0x2600
	ds_read_b64_tr_b16 v[218:219], v206 offset:0x2e00
	v_mfma_f32_32x32x16_bf16 v[32:47], v[76:79], v[220:223], v[32:47]
	ds_read_b64_tr_b16 v[220:221], v206 offset:0x3600
	ds_read_b64_tr_b16 v[222:223], v206 offset:0x3e00
	s_waitcnt lgkmcnt(0)
	ds_write_b128 v214, v[158:161] offset:32768
	v_mfma_f32_32x32x16_bf16 v[48:63], v[64:67], v[180:183], v[48:63]
	v_exp_f32_e32 v215, v108
	s_waitcnt vmcnt(4)
	v_exp_f32_e32 v181, v96
	v_exp_f32_e32 v183, v97
	v_exp_f32_e32 v188, v102
	v_exp_f32_e32 v189, v103
	v_exp_f32_e32 v196, v104
	v_mfma_f32_32x32x16_bf16 v[48:63], v[68:71], v[184:187], v[48:63]
	v_exp_f32_e32 v184, v98
	v_exp_f32_e32 v185, v99
	v_exp_f32_e32 v186, v100
	v_exp_f32_e32 v187, v101
	v_exp_f32_e32 v197, v105
	v_exp_f32_e32 v198, v106
	v_exp_f32_e32 v199, v107
	v_mfma_f32_32x32x16_bf16 v[48:63], v[72:75], v[216:219], v[48:63]
	v_exp_f32_e32 v216, v109
	v_exp_f32_e32 v217, v110
	v_exp_f32_e32 v218, v111
	s_waitcnt lgkmcnt(0)
	s_barrier
	v_mfma_f32_32x32x16_bf16 v[48:63], v[76:79], v[220:223], v[48:63]
	ds_read_b128 v[64:67], v207 offset:32768
	ds_read_b128 v[96:99], v207 offset:40960
	ds_read_b128 v[146:149], v208 offset:32768
	ds_read_b128 v[150:153], v208 offset:40960
	v_exp_f32_e32 v154, v88
	v_exp_f32_e32 v155, v89
	v_exp_f32_e32 v156, v90
	v_exp_f32_e32 v157, v91
	v_exp_f32_e32 v158, v92
	v_exp_f32_e32 v159, v93
	v_exp_f32_e32 v160, v94
	v_exp_f32_e32 v95, v95
	s_waitcnt lgkmcnt(3)
	v_mfma_f32_32x32x16_bf16 v[64:79], v[64:67], v[142:145], 0
	v_exp_f32_e32 v236, v80
	v_add_f32_e32 v80, 0, v181
	v_add_f32_e32 v80, v183, v80
	v_add_f32_e32 v80, v184, v80
	s_waitcnt lgkmcnt(2)
	v_mfma_f32_32x32x16_bf16 v[96:111], v[96:99], v[142:145], 0
	v_add_f32_e32 v80, v185, v80
	v_add_f32_e32 v80, v186, v80
	v_add_f32_e32 v80, v187, v80
	s_waitcnt lgkmcnt(1)
	v_mfma_f32_32x32x16_bf16 v[64:79], v[146:149], v[138:141], v[64:79]
	v_add_f32_e32 v80, v188, v80
	v_add_f32_e32 v80, v189, v80
	v_add_f32_e32 v80, v196, v80
	s_waitcnt lgkmcnt(0)
	v_mfma_f32_32x32x16_bf16 v[96:111], v[150:153], v[138:141], v[96:111]
	ds_read_b128 v[146:149], v209 offset:32768
	ds_read_b128 v[150:153], v209 offset:40960
	v_add_f32_e32 v80, v197, v80
	v_add_f32_e32 v80, v198, v80
	v_add_f32_e32 v80, v199, v80
	v_add_f32_e32 v80, v215, v80
	v_exp_f32_e32 v237, v81
	s_waitcnt lgkmcnt(1)
	v_mfma_f32_32x32x16_bf16 v[64:79], v[146:149], v[112:115], v[64:79]
	v_add_f32_e32 v80, v216, v80
	v_exp_f32_e32 v238, v82
	v_add_f32_e32 v80, v217, v80
	v_exp_f32_e32 v239, v83
	s_waitcnt lgkmcnt(0)
	v_mfma_f32_32x32x16_bf16 v[96:111], v[150:153], v[112:115], v[96:111]
	ds_read_b128 v[146:149], v210 offset:32768
	ds_read_b128 v[150:153], v210 offset:40960
	v_add_f32_e32 v80, v218, v80
	v_exp_f32_e32 v247, v84
	v_add_f32_e32 v80, v236, v80
	v_exp_f32_e32 v248, v85
	s_waitcnt lgkmcnt(1)
	v_mfma_f32_32x32x16_bf16 v[64:79], v[146:149], v[116:119], v[64:79]
	v_add_f32_e32 v80, v237, v80
	v_exp_f32_e32 v249, v86
	v_add_f32_e32 v80, v238, v80
	v_exp_f32_e32 v252, v87
	s_waitcnt lgkmcnt(0)
	v_mfma_f32_32x32x16_bf16 v[96:111], v[150:153], v[116:119], v[96:111]
	ds_read_b128 v[146:149], v190 offset:32768
	ds_read_b128 v[150:153], v190 offset:40960
	v_add_f32_e32 v80, v239, v80
	v_add_f32_e32 v80, v247, v80
	v_add_f32_e32 v80, v248, v80
	v_add_f32_e32 v80, v249, v80
	v_add_f32_e32 v80, v252, v80
	v_add_f32_e32 v80, v154, v80
	s_waitcnt lgkmcnt(1)
	v_mfma_f32_32x32x16_bf16 v[64:79], v[146:149], v[120:123], v[64:79]
	v_add_f32_e32 v80, v155, v80
	v_add_f32_e32 v80, v156, v80
	v_add_f32_e32 v80, v157, v80
	v_add_f32_e32 v80, v158, v80
	v_add_f32_e32 v80, v159, v80
	s_waitcnt lgkmcnt(0)
; __device__ __forceinline__ void partialSM(f32x16& p0, f32x16& p1, float& m_reg, float& mn, float& alpha) {
;     ...
;   for (int r = 0; r < 16; ++r) p0[r] = __builtin_amdgcn_exp2f(p0[r]);
; }
; __device__ __forceinline__ void partialSM_fixed(f32x16& p0) {
;   for (int r = 0; r < 16; ++r) p0[r] = __builtin_amdgcn_exp2f(p0[r]);
; }
; __device__ __forceinline__ void finishSM(f32x16& p0, f32x16& p1, float alpha, float& l_reg, bf16x8& pa0, bf16x8& pa1, bf16x8& pa2, bf16x8& pa3) {
;   for (int r = 0; r < 16; ++r) p1[r] = __builtin_amdgcn_exp2f(p1[r]);
;   float ps = 0; for (int r = 0; r < 16; ++r) ps += p0[r]; for (int r = 0; r < 16; ++r) ps += p1[r];
; template <int BOFF> __device__ __forceinline__ void qkt_i(f32x16& p0, f32x16& p1, const int (&kb)[4], const bf16x8* qr) {
;   p0 = f32x16{}; p1 = f32x16{};
; #pragma unroll
;   for (int d0 = 0; d0 < 8; ++d0) { const int off = BOFF + (d0 >> 2) * 128;
;     const bf16x8 b0 = LDSV(kb[d0 & 3] + off), b1 = LDSV(kb[d0 & 3] + off + 8192);
;     p0 = __builtin_amdgcn_mfma_f32_32x32x16_bf16(b0, qr[d0], p0, 0, 0, 0);
;     p1 = __builtin_amdgcn_mfma_f32_32x32x16_bf16(b1, qr[d0], p1, 0, 0, 0); }
; }
; template <int D0, int BOFF> __device__ __forceinline__ void pv_one_i(f32x16& od, int vb, bf16x8 pa0, bf16x8 pa1, bf16x8 pa2, bf16x8 pa3) {
;   const s16x4 l0 = tr_read<BOFF + v_rd_off(D0, 0, 0)>(vb), h0 = tr_read<BOFF + v_rd_off(D0, 0, 1)>(vb), l1 = tr_read<BOFF + v_rd_off(D0, 1, 0)>(vb), h1 = tr_read<BOFF + v_rd_off(D0, 1, 1)>(vb);
;   const s16x4 l2 = tr_read<BOFF + v_rd_off(D0, 2, 0)>(vb), h2 = tr_read<BOFF + v_rd_off(D0, 2, 1)>(vb), l3 = tr_read<BOFF + v_rd_off(D0, 3, 0)>(vb), h3 = tr_read<BOFF + v_rd_off(D0, 3, 1)>(vb);
;   asm volatile("s_waitcnt lgkmcnt(0)" ::: "memory"); SBAR();
;     ...
;   od = __builtin_amdgcn_mfma_f32_32x32x16_bf16(pa0, PK(l0, h0), od, 0, 0, 0);
;   od = __builtin_amdgcn_mfma_f32_32x32x16_bf16(pa1, PK(l1, h1), od, 0, 0, 0);
;   od = __builtin_amdgcn_mfma_f32_32x32x16_bf16(pa2, PK(l2, h2), od, 0, 0, 0);
;   od = __builtin_amdgcn_mfma_f32_32x32x16_bf16(pa3, PK(l3, h3), od, 0, 0, 0);
;     ...
; }
; template <int BOFF> __device__ __forceinline__ void pv_i(f32x16* o, int vb, bf16x8 pa0, bf16x8 pa1, bf16x8 pa2, bf16x8 pa3) {
;   pv_one_i<0, BOFF>(o[0], vb, pa0, pa1, pa2, pa3); pv_one_i<1, BOFF>(o[1], vb, pa0, pa1, pa2, pa3); pv_one_i<2, BOFF>(o[2], vb, pa0, pa1, pa2, pa3); pv_one_i<3, BOFF>(o[3], vb, pa0, pa1, pa2, pa3);
; }
	v_mfma_f32_32x32x16_bf16 v[96:111], v[150:153], v[120:123], v[96:111]
	ds_read_b128 v[146:149], v191 offset:32768
	ds_read_b128 v[150:153], v191 offset:40960
	v_add_f32_e32 v80, v160, v80
	v_add_f32_e32 v180, v95, v80
	v_mov_b32_e32 v182, v180
	v_cvt_pk_bf16_f32 v80, v181, v183
	v_cvt_pk_bf16_f32 v81, v184, v185
	v_cvt_pk_bf16_f32 v82, v186, v187
	s_waitcnt lgkmcnt(1)
	v_mfma_f32_32x32x16_bf16 v[64:79], v[146:149], v[124:127], v[64:79]
	v_cvt_pk_bf16_f32 v83, v188, v189
	v_cvt_pk_bf16_f32 v84, v196, v197
	v_cvt_pk_bf16_f32 v85, v198, v199
	v_cvt_pk_bf16_f32 v86, v215, v216
	v_cvt_pk_bf16_f32 v87, v217, v218
	s_waitcnt lgkmcnt(0)
	v_mfma_f32_32x32x16_bf16 v[96:111], v[150:153], v[124:127], v[96:111]
	ds_read_b128 v[146:149], v192 offset:32768
	ds_read_b128 v[150:153], v192 offset:40960
	v_cvt_pk_bf16_f32 v88, v236, v237
	v_cvt_pk_bf16_f32 v89, v238, v239
	v_cvt_pk_bf16_f32 v90, v247, v248
	v_cvt_pk_bf16_f32 v91, v249, v252
	v_cvt_pk_bf16_f32 v92, v154, v155
	v_cvt_pk_bf16_f32 v93, v156, v157
	s_waitcnt lgkmcnt(1)
	v_mfma_f32_32x32x16_bf16 v[64:79], v[146:149], v[130:133], v[64:79]
	v_cvt_pk_bf16_f32 v94, v158, v159
	v_cvt_pk_bf16_f32 v95, v160, v95
	s_nop 1
	v_permlane32_swap_b32_e32 v180, v182
	v_permlane32_swap_b32_e32 v80, v82
	s_waitcnt lgkmcnt(0)
	v_mfma_f32_32x32x16_bf16 v[96:111], v[150:153], v[130:133], v[96:111]
	ds_read_b128 v[146:149], v193 offset:32768
	ds_read_b128 v[150:153], v193 offset:40960
	ds_read_b64_tr_b16 v[184:185], v206 offset:0x4000
	ds_read_b64_tr_b16 v[186:187], v206 offset:0x4800
	ds_read_b64_tr_b16 v[216:217], v206 offset:0x5000
	ds_read_b64_tr_b16 v[218:219], v206 offset:0x5800
	ds_read_b64_tr_b16 v[220:221], v206 offset:0x6000
	ds_read_b64_tr_b16 v[222:223], v206 offset:0x6800
	ds_read_b64_tr_b16 v[224:225], v206 offset:0x7000
	ds_read_b64_tr_b16 v[226:227], v206 offset:0x7800
	v_permlane32_swap_b32_e32 v81, v83
	v_permlane32_swap_b32_e32 v84, v86
	v_permlane32_swap_b32_e32 v85, v87
	v_permlane32_swap_b32_e32 v88, v90
	v_permlane32_swap_b32_e32 v89, v91
	v_permlane32_swap_b32_e32 v92, v94
	s_waitcnt lgkmcnt(9)
	v_mfma_f32_32x32x16_bf16 v[64:79], v[146:149], v[134:137], v[64:79]
	v_permlane32_swap_b32_e32 v93, v95
	s_waitcnt lgkmcnt(8)
	v_mfma_f32_32x32x16_bf16 v[96:111], v[150:153], v[134:137], v[96:111]
	v_add_co_u32_e32 v150, vcc, s21, v178
	s_nop 1
	v_addc_co_u32_e32 v151, vcc, -1, v179, vcc
	v_add_co_u32_e32 v154, vcc, s22, v178
	s_nop 1
	v_addc_co_u32_e32 v155, vcc, -1, v179, vcc
	global_load_dwordx4 v[146:149], v[150:151], off
	s_nop 0
	global_load_dwordx4 v[150:153], v[150:151], off offset:-512
	s_nop 0
	global_load_dwordx4 v[158:161], v[154:155], off
	s_nop 0
	global_load_dwordx4 v[154:157], v[154:155], off offset:-512
	s_waitcnt lgkmcnt(0)
	s_waitcnt vmcnt(4)
	ds_write_b128 v211, v[162:165]
	s_nop 0
	v_mfma_f32_32x32x16_bf16 v[0:15], v[80:83], v[184:187], v[0:15]
	ds_read_b64_tr_b16 v[184:185], v206 offset:0x4200
	ds_read_b64_tr_b16 v[186:187], v206 offset:0x4a00
	v_mfma_f32_32x32x16_bf16 v[0:15], v[84:87], v[216:219], v[0:15]
	ds_read_b64_tr_b16 v[216:217], v206 offset:0x5200
	ds_read_b64_tr_b16 v[218:219], v206 offset:0x5a00
	v_mfma_f32_32x32x16_bf16 v[0:15], v[88:91], v[220:223], v[0:15]
	ds_read_b64_tr_b16 v[220:221], v206 offset:0x6200
	ds_read_b64_tr_b16 v[222:223], v206 offset:0x6a00
	v_mfma_f32_32x32x16_bf16 v[0:15], v[92:95], v[224:227], v[0:15]
	ds_read_b64_tr_b16 v[224:225], v206 offset:0x7200
	ds_read_b64_tr_b16 v[226:227], v206 offset:0x7a00
	s_waitcnt lgkmcnt(0)
	ds_write_b128 v212, v[174:177]
	v_mfma_f32_32x32x16_bf16 v[16:31], v[80:83], v[184:187], v[16:31]
	ds_read_b64_tr_b16 v[184:185], v206 offset:0x4400
	ds_read_b64_tr_b16 v[186:187], v206 offset:0x4c00
	v_mfma_f32_32x32x16_bf16 v[16:31], v[84:87], v[216:219], v[16:31]
	ds_read_b64_tr_b16 v[216:217], v206 offset:0x5400
	ds_read_b64_tr_b16 v[218:219], v206 offset:0x5c00
	v_mfma_f32_32x32x16_bf16 v[16:31], v[88:91], v[220:223], v[16:31]
	ds_read_b64_tr_b16 v[220:221], v206 offset:0x6400
	ds_read_b64_tr_b16 v[222:223], v206 offset:0x6c00
	v_mfma_f32_32x32x16_bf16 v[16:31], v[92:95], v[224:227], v[16:31]
	ds_read_b64_tr_b16 v[224:225], v206 offset:0x7400
	ds_read_b64_tr_b16 v[226:227], v206 offset:0x7c00
	s_waitcnt lgkmcnt(0)
	ds_write_b128 v213, v[166:169]
	v_mfma_f32_32x32x16_bf16 v[32:47], v[80:83], v[184:187], v[32:47]
	ds_read_b64_tr_b16 v[184:185], v206 offset:0x4600
	ds_read_b64_tr_b16 v[186:187], v206 offset:0x4e00
	v_mfma_f32_32x32x16_bf16 v[32:47], v[84:87], v[216:219], v[32:47]
	ds_read_b64_tr_b16 v[216:217], v206 offset:0x5600
	ds_read_b64_tr_b16 v[218:219], v206 offset:0x5e00
	v_mfma_f32_32x32x16_bf16 v[32:47], v[88:91], v[220:223], v[32:47]
	ds_read_b64_tr_b16 v[220:221], v206 offset:0x6600
	ds_read_b64_tr_b16 v[222:223], v206 offset:0x6e00
	v_mfma_f32_32x32x16_bf16 v[32:47], v[92:95], v[224:227], v[32:47]
	ds_read_b64_tr_b16 v[224:225], v206 offset:0x7600
	ds_read_b64_tr_b16 v[226:227], v206 offset:0x7e00
	s_waitcnt lgkmcnt(0)
	ds_write_b128 v214, v[170:173]
	v_mfma_f32_32x32x16_bf16 v[48:63], v[80:83], v[184:187], v[48:63]
	v_exp_f32_e32 v215, v74
	s_waitcnt vmcnt(4)
	v_exp_f32_e32 v184, v64
	v_exp_f32_e32 v185, v65
	v_exp_f32_e32 v186, v66
	v_exp_f32_e32 v187, v67
	v_exp_f32_e32 v188, v68
	v_mfma_f32_32x32x16_bf16 v[48:63], v[84:87], v[216:219], v[48:63]
	v_exp_f32_e32 v219, v78
	v_exp_f32_e32 v189, v69
	v_exp_f32_e32 v196, v70
	v_exp_f32_e32 v197, v71
	v_exp_f32_e32 v198, v72
	v_exp_f32_e32 v199, v73
	v_exp_f32_e32 v216, v75
	v_mfma_f32_32x32x16_bf16 v[48:63], v[88:91], v[220:223], v[48:63]
	v_exp_f32_e32 v220, v79
	v_exp_f32_e32 v217, v76
	v_exp_f32_e32 v218, v77
	s_waitcnt lgkmcnt(0)
	s_barrier
; #define SBAR() __builtin_amdgcn_sched_barrier(0)
; __device__ __forceinline__ void finishSM(f32x16& p0, f32x16& p1, float alpha, float& l_reg, bf16x8& pa0, bf16x8& pa1, bf16x8& pa2, bf16x8& pa3) {
;   for (int r = 0; r < 16; ++r) p1[r] = __builtin_amdgcn_exp2f(p1[r]);
;   float ps = 0; for (int r = 0; r < 16; ++r) ps += p0[r]; for (int r = 0; r < 16; ++r) ps += p1[r];
;   { auto rr = __builtin_amdgcn_permlane32_swap(__float_as_uint(ps), __float_as_uint(ps), false, false);
;     ps = __uint_as_float(rr[0]) + __uint_as_float(rr[1]); }
;   l_reg = l_reg * alpha + ps;
;     ...
;   PK4(p0, 0, pa0); PK4(p0, 8, pa1); PK4(p1, 0, pa2); PK4(p1, 8, pa3);
; template <int BOFF> __device__ __forceinline__ void qkt_i(f32x16& p0, f32x16& p1, const int (&kb)[4], const bf16x8* qr) {
;   p0 = f32x16{}; p1 = f32x16{};
; #pragma unroll
;   for (int d0 = 0; d0 < 8; ++d0) { const int off = BOFF + (d0 >> 2) * 128;
;     const bf16x8 b0 = LDSV(kb[d0 & 3] + off), b1 = LDSV(kb[d0 & 3] + off + 8192);
;     p0 = __builtin_amdgcn_mfma_f32_32x32x16_bf16(b0, qr[d0], p0, 0, 0, 0);
;     p1 = __builtin_amdgcn_mfma_f32_32x32x16_bf16(b1, qr[d0], p1, 0, 0, 0); }
; }
; template <int D0, int BOFF> __device__ __forceinline__ void pv_one_i(f32x16& od, int vb, bf16x8 pa0, bf16x8 pa1, bf16x8 pa2, bf16x8 pa3) {
;   const s16x4 l0 = tr_read<BOFF + v_rd_off(D0, 0, 0)>(vb), h0 = tr_read<BOFF + v_rd_off(D0, 0, 1)>(vb), l1 = tr_read<BOFF + v_rd_off(D0, 1, 0)>(vb), h1 = tr_read<BOFF + v_rd_off(D0, 1, 1)>(vb);
;   const s16x4 l2 = tr_read<BOFF + v_rd_off(D0, 2, 0)>(vb), h2 = tr_read<BOFF + v_rd_off(D0, 2, 1)>(vb), l3 = tr_read<BOFF + v_rd_off(D0, 3, 0)>(vb), h3 = tr_read<BOFF + v_rd_off(D0, 3, 1)>(vb);
;   asm volatile("s_waitcnt lgkmcnt(0)" ::: "memory"); SBAR();
;     ...
;   od = __builtin_amdgcn_mfma_f32_32x32x16_bf16(pa0, PK(l0, h0), od, 0, 0, 0);
;   od = __builtin_amdgcn_mfma_f32_32x32x16_bf16(pa1, PK(l1, h1), od, 0, 0, 0);
;   od = __builtin_amdgcn_mfma_f32_32x32x16_bf16(pa2, PK(l2, h2), od, 0, 0, 0);
;   od = __builtin_amdgcn_mfma_f32_32x32x16_bf16(pa3, PK(l3, h3), od, 0, 0, 0);
	v_mfma_f32_32x32x16_bf16 v[48:63], v[92:95], v[224:227], v[48:63]
	ds_read_b128 v[64:67], v207
	ds_read_b128 v[68:71], v207 offset:8192
	ds_read_b128 v[162:165], v208
	ds_read_b128 v[166:169], v208 offset:8192
	v_exp_f32_e32 v170, v104
	v_exp_f32_e32 v171, v105
	v_exp_f32_e32 v172, v106
	v_exp_f32_e32 v173, v107
	v_exp_f32_e32 v174, v108
	v_exp_f32_e32 v175, v109
	v_exp_f32_e32 v176, v110
	v_exp_f32_e32 v111, v111
	s_waitcnt lgkmcnt(3)
	v_mfma_f32_32x32x16_bf16 v[80:95], v[64:67], v[142:145], 0
	v_exp_f32_e32 v236, v96
	v_add_f32_e32 v96, 0, v184
	v_add_f32_e32 v96, v185, v96
	v_add_f32_e32 v96, v186, v96
	s_waitcnt lgkmcnt(2)
	v_mfma_f32_32x32x16_bf16 v[64:79], v[68:71], v[142:145], 0
	v_add_f32_e32 v96, v187, v96
	v_add_f32_e32 v96, v188, v96
	v_add_f32_e32 v96, v189, v96
	s_waitcnt lgkmcnt(1)
	v_mfma_f32_32x32x16_bf16 v[80:95], v[162:165], v[138:141], v[80:95]
	v_add_f32_e32 v96, v196, v96
	v_add_f32_e32 v96, v197, v96
	v_add_f32_e32 v96, v198, v96
	s_waitcnt lgkmcnt(0)
	v_mfma_f32_32x32x16_bf16 v[64:79], v[166:169], v[138:141], v[64:79]
	ds_read_b128 v[162:165], v209
	ds_read_b128 v[166:169], v209 offset:8192
	v_add_f32_e32 v96, v199, v96
	v_add_f32_e32 v96, v215, v96
	v_add_f32_e32 v96, v216, v96
	v_add_f32_e32 v96, v217, v96
	v_exp_f32_e32 v237, v97
	s_waitcnt lgkmcnt(1)
	v_mfma_f32_32x32x16_bf16 v[80:95], v[162:165], v[112:115], v[80:95]
	v_add_f32_e32 v96, v218, v96
	v_exp_f32_e32 v238, v98
	v_add_f32_e32 v96, v219, v96
	v_exp_f32_e32 v239, v99
	s_waitcnt lgkmcnt(0)
	v_mfma_f32_32x32x16_bf16 v[64:79], v[166:169], v[112:115], v[64:79]
	ds_read_b128 v[162:165], v210
	ds_read_b128 v[166:169], v210 offset:8192
	v_add_f32_e32 v96, v220, v96
	v_exp_f32_e32 v247, v100
	v_add_f32_e32 v96, v236, v96
	v_exp_f32_e32 v248, v101
	s_waitcnt lgkmcnt(1)
	v_mfma_f32_32x32x16_bf16 v[80:95], v[162:165], v[116:119], v[80:95]
	v_add_f32_e32 v96, v237, v96
	v_exp_f32_e32 v249, v102
	v_add_f32_e32 v96, v238, v96
	v_exp_f32_e32 v252, v103
	s_waitcnt lgkmcnt(0)
	v_mfma_f32_32x32x16_bf16 v[64:79], v[166:169], v[116:119], v[64:79]
	ds_read_b128 v[162:165], v190 offset:0
	ds_read_b128 v[166:169], v190 offset:8192
	v_add_f32_e32 v96, v239, v96
	v_add_f32_e32 v96, v247, v96
	v_add_f32_e32 v96, v248, v96
	v_add_f32_e32 v96, v249, v96
	v_add_f32_e32 v96, v252, v96
	v_add_f32_e32 v96, v170, v96
	s_waitcnt lgkmcnt(1)
	v_mfma_f32_32x32x16_bf16 v[80:95], v[162:165], v[120:123], v[80:95]
	v_add_f32_e32 v96, v171, v96
	v_add_f32_e32 v96, v172, v96
	v_add_f32_e32 v96, v173, v96
	v_add_f32_e32 v96, v174, v96
	v_add_f32_e32 v96, v175, v96
	s_waitcnt lgkmcnt(0)
	v_mfma_f32_32x32x16_bf16 v[64:79], v[166:169], v[120:123], v[64:79]
	ds_read_b128 v[162:165], v191 offset:0
	ds_read_b128 v[166:169], v191 offset:8192
	v_add_f32_e32 v96, v176, v96
	v_add_f32_e32 v181, v111, v96
	v_mov_b32_e32 v183, v181
	s_nop 1
	v_permlane32_swap_b32_e32 v181, v183
	v_pk_add_f32 v[96:97], v[180:181], v[182:183]
	s_waitcnt lgkmcnt(1)
	v_mfma_f32_32x32x16_bf16 v[80:95], v[162:165], v[124:127], v[80:95]
	s_nop 0
	v_add_f32_e32 v96, v128, v96
	v_add_f32_e32 v128, v96, v97
	v_cvt_pk_bf16_f32 v96, v184, v185
	v_cvt_pk_bf16_f32 v97, v186, v187
	s_waitcnt lgkmcnt(0)
	v_mfma_f32_32x32x16_bf16 v[64:79], v[166:169], v[124:127], v[64:79]
	ds_read_b128 v[162:165], v192 offset:0
	ds_read_b128 v[166:169], v192 offset:8192
	v_cvt_pk_bf16_f32 v98, v188, v189
	v_cvt_pk_bf16_f32 v99, v196, v197
	v_cvt_pk_bf16_f32 v100, v198, v199
	v_cvt_pk_bf16_f32 v101, v215, v216
	v_cvt_pk_bf16_f32 v102, v217, v218
	v_cvt_pk_bf16_f32 v103, v219, v220
	s_waitcnt lgkmcnt(1)
	v_mfma_f32_32x32x16_bf16 v[80:95], v[162:165], v[130:133], v[80:95]
	v_cvt_pk_bf16_f32 v104, v236, v237
	v_cvt_pk_bf16_f32 v105, v238, v239
	v_cvt_pk_bf16_f32 v106, v247, v248
	v_cvt_pk_bf16_f32 v107, v249, v252
	v_cvt_pk_bf16_f32 v108, v170, v171
	s_waitcnt lgkmcnt(0)
	v_mfma_f32_32x32x16_bf16 v[64:79], v[166:169], v[130:133], v[64:79]
	ds_read_b128 v[162:165], v193 offset:0
	ds_read_b128 v[166:169], v193 offset:8192
	ds_read_b64_tr_b16 v[180:181], v206 offset:0x8000
	ds_read_b64_tr_b16 v[182:183], v206 offset:0x8800
	ds_read_b64_tr_b16 v[184:185], v206 offset:0x9000
	ds_read_b64_tr_b16 v[186:187], v206 offset:0x9800
	ds_read_b64_tr_b16 v[216:217], v206 offset:0xa000
	ds_read_b64_tr_b16 v[218:219], v206 offset:0xa800
	ds_read_b64_tr_b16 v[220:221], v206 offset:0xb000
	ds_read_b64_tr_b16 v[222:223], v206 offset:0xb800
	v_cvt_pk_bf16_f32 v109, v172, v173
	v_cvt_pk_bf16_f32 v110, v174, v175
	v_cvt_pk_bf16_f32 v111, v176, v111
	s_nop 0
	v_permlane32_swap_b32_e32 v96, v98
	v_permlane32_swap_b32_e32 v97, v99
	s_waitcnt lgkmcnt(9)
	v_mfma_f32_32x32x16_bf16 v[80:95], v[162:165], v[134:137], v[80:95]
	v_permlane32_swap_b32_e32 v100, v102
	v_permlane32_swap_b32_e32 v101, v103
	v_permlane32_swap_b32_e32 v104, v106
	v_permlane32_swap_b32_e32 v105, v107
	v_permlane32_swap_b32_e32 v108, v110
	s_waitcnt lgkmcnt(8)
	v_mfma_f32_32x32x16_bf16 v[64:79], v[166:169], v[134:137], v[64:79]
	v_permlane32_swap_b32_e32 v109, v111
	v_add_co_u32_e32 v166, vcc, s23, v178
	s_nop 1
	v_addc_co_u32_e32 v167, vcc, -1, v179, vcc
	v_add_co_u32_e32 v170, vcc, s24, v178
	s_nop 1
	v_addc_co_u32_e32 v171, vcc, -1, v179, vcc
	global_load_dwordx4 v[162:165], v[166:167], off
	s_nop 0
	global_load_dwordx4 v[166:169], v[166:167], off offset:-512
	s_nop 0
	global_load_dwordx4 v[174:177], v[170:171], off
	s_nop 0
	global_load_dwordx4 v[170:173], v[170:171], off offset:-512
	s_waitcnt lgkmcnt(0)
	s_waitcnt vmcnt(4)
; #define SBAR() __builtin_amdgcn_sched_barrier(0)
; template <int D0, int BOFF> __device__ __forceinline__ void pv_one_i(f32x16& od, int vb, bf16x8 pa0, bf16x8 pa1, bf16x8 pa2, bf16x8 pa3) {
;   const s16x4 l0 = tr_read<BOFF + v_rd_off(D0, 0, 0)>(vb), h0 = tr_read<BOFF + v_rd_off(D0, 0, 1)>(vb), l1 = tr_read<BOFF + v_rd_off(D0, 1, 0)>(vb), h1 = tr_read<BOFF + v_rd_off(D0, 1, 1)>(vb);
;   const s16x4 l2 = tr_read<BOFF + v_rd_off(D0, 2, 0)>(vb), h2 = tr_read<BOFF + v_rd_off(D0, 2, 1)>(vb), l3 = tr_read<BOFF + v_rd_off(D0, 3, 0)>(vb), h3 = tr_read<BOFF + v_rd_off(D0, 3, 1)>(vb);
;   asm volatile("s_waitcnt lgkmcnt(0)" ::: "memory"); SBAR();
;     ...
;   od = __builtin_amdgcn_mfma_f32_32x32x16_bf16(pa0, PK(l0, h0), od, 0, 0, 0);
;   od = __builtin_amdgcn_mfma_f32_32x32x16_bf16(pa1, PK(l1, h1), od, 0, 0, 0);
;   od = __builtin_amdgcn_mfma_f32_32x32x16_bf16(pa2, PK(l2, h2), od, 0, 0, 0);
;   od = __builtin_amdgcn_mfma_f32_32x32x16_bf16(pa3, PK(l3, h3), od, 0, 0, 0);
;     ...
; }
; template <int BOFF> __device__ __forceinline__ void pv_i(f32x16* o, int vb, bf16x8 pa0, bf16x8 pa1, bf16x8 pa2, bf16x8 pa3) {
;   pv_one_i<0, BOFF>(o[0], vb, pa0, pa1, pa2, pa3); pv_one_i<1, BOFF>(o[1], vb, pa0, pa1, pa2, pa3); pv_one_i<2, BOFF>(o[2], vb, pa0, pa1, pa2, pa3); pv_one_i<3, BOFF>(o[3], vb, pa0, pa1, pa2, pa3);
	ds_write_b128 v211, v[146:149] offset:16384
	s_nop 0
	v_mfma_f32_32x32x16_bf16 v[0:15], v[96:99], v[180:183], v[0:15]
	ds_read_b64_tr_b16 v[180:181], v206 offset:0x8200
	ds_read_b64_tr_b16 v[182:183], v206 offset:0x8a00
	v_mfma_f32_32x32x16_bf16 v[0:15], v[100:103], v[184:187], v[0:15]
	ds_read_b64_tr_b16 v[184:185], v206 offset:0x9200
	ds_read_b64_tr_b16 v[186:187], v206 offset:0x9a00
	v_mfma_f32_32x32x16_bf16 v[0:15], v[104:107], v[216:219], v[0:15]
	ds_read_b64_tr_b16 v[216:217], v206 offset:0xa200
	ds_read_b64_tr_b16 v[218:219], v206 offset:0xaa00
	v_mfma_f32_32x32x16_bf16 v[0:15], v[108:111], v[220:223], v[0:15]
	ds_read_b64_tr_b16 v[220:221], v206 offset:0xb200
	ds_read_b64_tr_b16 v[222:223], v206 offset:0xba00
	s_waitcnt lgkmcnt(0)
	ds_write_b128 v212, v[158:161] offset:16384
	v_mfma_f32_32x32x16_bf16 v[16:31], v[96:99], v[180:183], v[16:31]
	ds_read_b64_tr_b16 v[180:181], v206 offset:0x8400
	ds_read_b64_tr_b16 v[182:183], v206 offset:0x8c00
	v_mfma_f32_32x32x16_bf16 v[16:31], v[100:103], v[184:187], v[16:31]
	ds_read_b64_tr_b16 v[184:185], v206 offset:0x9400
	ds_read_b64_tr_b16 v[186:187], v206 offset:0x9c00
	v_mfma_f32_32x32x16_bf16 v[16:31], v[104:107], v[216:219], v[16:31]
	ds_read_b64_tr_b16 v[216:217], v206 offset:0xa400
	ds_read_b64_tr_b16 v[218:219], v206 offset:0xac00
	v_mfma_f32_32x32x16_bf16 v[16:31], v[108:111], v[220:223], v[16:31]
	ds_read_b64_tr_b16 v[220:221], v206 offset:0xb400
	ds_read_b64_tr_b16 v[222:223], v206 offset:0xbc00
	s_waitcnt lgkmcnt(0)
	ds_write_b128 v213, v[150:153] offset:16384
	v_mfma_f32_32x32x16_bf16 v[32:47], v[96:99], v[180:183], v[32:47]
	ds_read_b64_tr_b16 v[180:181], v206 offset:0x8600
	ds_read_b64_tr_b16 v[182:183], v206 offset:0x8e00
	v_mfma_f32_32x32x16_bf16 v[32:47], v[100:103], v[184:187], v[32:47]
	ds_read_b64_tr_b16 v[184:185], v206 offset:0x9600
	ds_read_b64_tr_b16 v[186:187], v206 offset:0x9e00
	v_mfma_f32_32x32x16_bf16 v[32:47], v[104:107], v[216:219], v[32:47]
	ds_read_b64_tr_b16 v[216:217], v206 offset:0xa600
	ds_read_b64_tr_b16 v[218:219], v206 offset:0xae00
	v_mfma_f32_32x32x16_bf16 v[32:47], v[108:111], v[220:223], v[32:47]
	ds_read_b64_tr_b16 v[220:221], v206 offset:0xb600
	ds_read_b64_tr_b16 v[222:223], v206 offset:0xbe00
	s_waitcnt lgkmcnt(0)
	ds_write_b128 v214, v[154:157] offset:16384
	v_mfma_f32_32x32x16_bf16 v[48:63], v[96:99], v[180:183], v[48:63]
	v_exp_f32_e32 v215, v92
	s_waitcnt vmcnt(4)
	v_exp_f32_e32 v181, v80
	v_exp_f32_e32 v183, v81
	v_exp_f32_e32 v188, v86
	v_exp_f32_e32 v189, v87
	v_exp_f32_e32 v196, v88
	v_mfma_f32_32x32x16_bf16 v[48:63], v[100:103], v[184:187], v[48:63]
	v_exp_f32_e32 v184, v82
	v_exp_f32_e32 v185, v83
	v_exp_f32_e32 v186, v84
	v_exp_f32_e32 v187, v85
	v_exp_f32_e32 v197, v89
	v_exp_f32_e32 v198, v90
	v_exp_f32_e32 v199, v91
	v_mfma_f32_32x32x16_bf16 v[48:63], v[104:107], v[216:219], v[48:63]
	v_exp_f32_e32 v216, v93
	v_exp_f32_e32 v217, v94
	v_exp_f32_e32 v218, v95
	s_waitcnt lgkmcnt(0)
	s_barrier
	v_mfma_f32_32x32x16_bf16 v[48:63], v[108:111], v[220:223], v[48:63]
	ds_read_b128 v[80:83], v207 offset:16384
	ds_read_b128 v[96:99], v207 offset:24576
	ds_read_b128 v[146:149], v208 offset:16384
	ds_read_b128 v[150:153], v208 offset:24576
	v_exp_f32_e32 v154, v72
	v_exp_f32_e32 v155, v73
	v_exp_f32_e32 v156, v74
	v_exp_f32_e32 v157, v75
	v_exp_f32_e32 v158, v76
	v_exp_f32_e32 v159, v77
	v_exp_f32_e32 v160, v78
	v_exp_f32_e32 v79, v79
	s_waitcnt lgkmcnt(3)
	v_mfma_f32_32x32x16_bf16 v[80:95], v[80:83], v[142:145], 0
	v_exp_f32_e32 v236, v64
	v_add_f32_e32 v64, 0, v181
	v_add_f32_e32 v64, v183, v64
	v_add_f32_e32 v64, v184, v64
	s_waitcnt lgkmcnt(2)
	v_mfma_f32_32x32x16_bf16 v[96:111], v[96:99], v[142:145], 0
	v_add_f32_e32 v64, v185, v64
	v_add_f32_e32 v64, v186, v64
	v_add_f32_e32 v64, v187, v64
	s_waitcnt lgkmcnt(1)
	v_mfma_f32_32x32x16_bf16 v[80:95], v[146:149], v[138:141], v[80:95]
	v_add_f32_e32 v64, v188, v64
	v_add_f32_e32 v64, v189, v64
	v_add_f32_e32 v64, v196, v64
	s_waitcnt lgkmcnt(0)
	v_mfma_f32_32x32x16_bf16 v[96:111], v[150:153], v[138:141], v[96:111]
	ds_read_b128 v[146:149], v209 offset:16384
	ds_read_b128 v[150:153], v209 offset:24576
	v_add_f32_e32 v64, v197, v64
	v_add_f32_e32 v64, v198, v64
	v_add_f32_e32 v64, v199, v64
	v_add_f32_e32 v64, v215, v64
	v_exp_f32_e32 v237, v65
	s_waitcnt lgkmcnt(1)
	v_mfma_f32_32x32x16_bf16 v[80:95], v[146:149], v[112:115], v[80:95]
	v_add_f32_e32 v64, v216, v64
	v_exp_f32_e32 v238, v66
	v_add_f32_e32 v64, v217, v64
	v_exp_f32_e32 v239, v67
	s_waitcnt lgkmcnt(0)
	v_mfma_f32_32x32x16_bf16 v[96:111], v[150:153], v[112:115], v[96:111]
	ds_read_b128 v[146:149], v210 offset:16384
	ds_read_b128 v[150:153], v210 offset:24576
	v_add_f32_e32 v64, v218, v64
	v_exp_f32_e32 v247, v68
	v_add_f32_e32 v64, v236, v64
	v_exp_f32_e32 v248, v69
	s_waitcnt lgkmcnt(1)
	v_mfma_f32_32x32x16_bf16 v[80:95], v[146:149], v[116:119], v[80:95]
	v_add_f32_e32 v64, v237, v64
	v_exp_f32_e32 v249, v70
	v_add_f32_e32 v64, v238, v64
	v_exp_f32_e32 v252, v71
	s_waitcnt lgkmcnt(0)
	v_mfma_f32_32x32x16_bf16 v[96:111], v[150:153], v[116:119], v[96:111]
	ds_read_b128 v[146:149], v190 offset:16384
	ds_read_b128 v[150:153], v190 offset:24576
	v_add_f32_e32 v64, v239, v64
	v_add_f32_e32 v64, v247, v64
	v_add_f32_e32 v64, v248, v64
	v_add_f32_e32 v64, v249, v64
	v_add_f32_e32 v64, v252, v64
	v_add_f32_e32 v64, v154, v64
	s_waitcnt lgkmcnt(1)
	v_mfma_f32_32x32x16_bf16 v[80:95], v[146:149], v[120:123], v[80:95]
	v_add_f32_e32 v64, v155, v64
	v_add_f32_e32 v64, v156, v64
	v_add_f32_e32 v64, v157, v64
	v_add_f32_e32 v64, v158, v64
	v_add_f32_e32 v64, v159, v64
	s_waitcnt lgkmcnt(0)
; #define SBAR() __builtin_amdgcn_sched_barrier(0)
; __device__ __forceinline__ void finishSM(f32x16& p0, f32x16& p1, float alpha, float& l_reg, bf16x8& pa0, bf16x8& pa1, bf16x8& pa2, bf16x8& pa3) {
;   for (int r = 0; r < 16; ++r) p1[r] = __builtin_amdgcn_exp2f(p1[r]);
;   float ps = 0; for (int r = 0; r < 16; ++r) ps += p0[r]; for (int r = 0; r < 16; ++r) ps += p1[r];
;   { auto rr = __builtin_amdgcn_permlane32_swap(__float_as_uint(ps), __float_as_uint(ps), false, false);
;     ps = __uint_as_float(rr[0]) + __uint_as_float(rr[1]); }
;   l_reg = l_reg * alpha + ps;
;     ...
;   PK4(p0, 0, pa0); PK4(p0, 8, pa1); PK4(p1, 0, pa2); PK4(p1, 8, pa3);
; template <int BOFF> __device__ __forceinline__ void qkt_i(f32x16& p0, f32x16& p1, const int (&kb)[4], const bf16x8* qr) {
;   p0 = f32x16{}; p1 = f32x16{};
; #pragma unroll
;   for (int d0 = 0; d0 < 8; ++d0) { const int off = BOFF + (d0 >> 2) * 128;
;     const bf16x8 b0 = LDSV(kb[d0 & 3] + off), b1 = LDSV(kb[d0 & 3] + off + 8192);
;     p0 = __builtin_amdgcn_mfma_f32_32x32x16_bf16(b0, qr[d0], p0, 0, 0, 0);
;     p1 = __builtin_amdgcn_mfma_f32_32x32x16_bf16(b1, qr[d0], p1, 0, 0, 0); }
; }
; template <int D0, int BOFF> __device__ __forceinline__ void pv_one_i(f32x16& od, int vb, bf16x8 pa0, bf16x8 pa1, bf16x8 pa2, bf16x8 pa3) {
;   const s16x4 l0 = tr_read<BOFF + v_rd_off(D0, 0, 0)>(vb), h0 = tr_read<BOFF + v_rd_off(D0, 0, 1)>(vb), l1 = tr_read<BOFF + v_rd_off(D0, 1, 0)>(vb), h1 = tr_read<BOFF + v_rd_off(D0, 1, 1)>(vb);
;   const s16x4 l2 = tr_read<BOFF + v_rd_off(D0, 2, 0)>(vb), h2 = tr_read<BOFF + v_rd_off(D0, 2, 1)>(vb), l3 = tr_read<BOFF + v_rd_off(D0, 3, 0)>(vb), h3 = tr_read<BOFF + v_rd_off(D0, 3, 1)>(vb);
;   asm volatile("s_waitcnt lgkmcnt(0)" ::: "memory"); SBAR();
;     ...
;   od = __builtin_amdgcn_mfma_f32_32x32x16_bf16(pa0, PK(l0, h0), od, 0, 0, 0);
;   od = __builtin_amdgcn_mfma_f32_32x32x16_bf16(pa1, PK(l1, h1), od, 0, 0, 0);
;   od = __builtin_amdgcn_mfma_f32_32x32x16_bf16(pa2, PK(l2, h2), od, 0, 0, 0);
;   od = __builtin_amdgcn_mfma_f32_32x32x16_bf16(pa3, PK(l3, h3), od, 0, 0, 0);
	v_mfma_f32_32x32x16_bf16 v[96:111], v[150:153], v[120:123], v[96:111]
	ds_read_b128 v[146:149], v191 offset:16384
	ds_read_b128 v[150:153], v191 offset:24576
	v_add_f32_e32 v64, v160, v64
	v_add_f32_e32 v180, v79, v64
	v_cvt_pk_bf16_f32 v64, v181, v183
	v_cvt_pk_bf16_f32 v65, v184, v185
	v_cvt_pk_bf16_f32 v66, v186, v187
	v_cvt_pk_bf16_f32 v67, v188, v189
	s_waitcnt lgkmcnt(1)
	v_mfma_f32_32x32x16_bf16 v[80:95], v[146:149], v[124:127], v[80:95]
	v_cvt_pk_bf16_f32 v68, v196, v197
	v_cvt_pk_bf16_f32 v69, v198, v199
	v_cvt_pk_bf16_f32 v70, v215, v216
	v_cvt_pk_bf16_f32 v71, v217, v218
	v_cvt_pk_bf16_f32 v72, v236, v237
	s_waitcnt lgkmcnt(0)
	v_mfma_f32_32x32x16_bf16 v[96:111], v[150:153], v[124:127], v[96:111]
	ds_read_b128 v[146:149], v192 offset:16384
	ds_read_b128 v[150:153], v192 offset:24576
	v_cvt_pk_bf16_f32 v73, v238, v239
	v_cvt_pk_bf16_f32 v74, v247, v248
	v_cvt_pk_bf16_f32 v75, v249, v252
	v_cvt_pk_bf16_f32 v76, v154, v155
	v_cvt_pk_bf16_f32 v77, v156, v157
	v_cvt_pk_bf16_f32 v78, v158, v159
	s_waitcnt lgkmcnt(1)
	v_mfma_f32_32x32x16_bf16 v[80:95], v[146:149], v[130:133], v[80:95]
	v_cvt_pk_bf16_f32 v79, v160, v79
	v_mov_b32_e32 v182, v180
	v_permlane32_swap_b32_e32 v64, v66
	v_permlane32_swap_b32_e32 v65, v67
	v_permlane32_swap_b32_e32 v68, v70
	s_waitcnt lgkmcnt(0)
	v_mfma_f32_32x32x16_bf16 v[96:111], v[150:153], v[130:133], v[96:111]
	ds_read_b128 v[146:149], v193 offset:16384
	ds_read_b128 v[150:153], v193 offset:24576
	ds_read_b64_tr_b16 v[184:185], v206 offset:0
	ds_read_b64_tr_b16 v[186:187], v206 offset:0x800
	ds_read_b64_tr_b16 v[216:217], v206 offset:0x1000
	ds_read_b64_tr_b16 v[218:219], v206 offset:0x1800
	ds_read_b64_tr_b16 v[220:221], v206 offset:0x2000
	ds_read_b64_tr_b16 v[222:223], v206 offset:0x2800
	ds_read_b64_tr_b16 v[224:225], v206 offset:0x3000
	ds_read_b64_tr_b16 v[226:227], v206 offset:0x3800
	v_permlane32_swap_b32_e32 v69, v71
	v_permlane32_swap_b32_e32 v72, v74
	v_permlane32_swap_b32_e32 v73, v75
	v_permlane32_swap_b32_e32 v76, v78
	v_permlane32_swap_b32_e32 v77, v79
	v_permlane32_swap_b32_e32 v180, v182
	s_waitcnt lgkmcnt(9)
	v_mfma_f32_32x32x16_bf16 v[80:95], v[146:149], v[134:137], v[80:95]
	s_waitcnt lgkmcnt(8)
	v_mfma_f32_32x32x16_bf16 v[96:111], v[150:153], v[134:137], v[96:111]
	v_add_co_u32_e32 v150, vcc, s25, v178
	s_nop 1
	v_addc_co_u32_e32 v151, vcc, -1, v179, vcc
	v_add_co_u32_e32 v154, vcc, s45, v178
	s_nop 1
	v_addc_co_u32_e32 v155, vcc, -1, v179, vcc
	global_load_dwordx4 v[146:149], v[150:151], off
	s_nop 0
	global_load_dwordx4 v[150:153], v[150:151], off offset:-512
	s_nop 0
	global_load_dwordx4 v[158:161], v[154:155], off
	s_nop 0
	global_load_dwordx4 v[154:157], v[154:155], off offset:-512
	s_waitcnt lgkmcnt(0)
	s_waitcnt vmcnt(4)
	ds_write_b128 v211, v[162:165] offset:32768
	s_nop 0
	v_mfma_f32_32x32x16_bf16 v[0:15], v[64:67], v[184:187], v[0:15]
	ds_read_b64_tr_b16 v[184:185], v206 offset:0x200
	ds_read_b64_tr_b16 v[186:187], v206 offset:0xa00
	v_mfma_f32_32x32x16_bf16 v[0:15], v[68:71], v[216:219], v[0:15]
	ds_read_b64_tr_b16 v[216:217], v206 offset:0x1200
	ds_read_b64_tr_b16 v[218:219], v206 offset:0x1a00
	v_mfma_f32_32x32x16_bf16 v[0:15], v[72:75], v[220:223], v[0:15]
	ds_read_b64_tr_b16 v[220:221], v206 offset:0x2200
	ds_read_b64_tr_b16 v[222:223], v206 offset:0x2a00
	v_mfma_f32_32x32x16_bf16 v[0:15], v[76:79], v[224:227], v[0:15]
	ds_read_b64_tr_b16 v[224:225], v206 offset:0x3200
	ds_read_b64_tr_b16 v[226:227], v206 offset:0x3a00
	s_waitcnt lgkmcnt(0)
	ds_write_b128 v212, v[174:177] offset:32768
	v_mfma_f32_32x32x16_bf16 v[16:31], v[64:67], v[184:187], v[16:31]
	ds_read_b64_tr_b16 v[184:185], v206 offset:0x400
	ds_read_b64_tr_b16 v[186:187], v206 offset:0xc00
	v_mfma_f32_32x32x16_bf16 v[16:31], v[68:71], v[216:219], v[16:31]
	ds_read_b64_tr_b16 v[216:217], v206 offset:0x1400
	ds_read_b64_tr_b16 v[218:219], v206 offset:0x1c00
	v_mfma_f32_32x32x16_bf16 v[16:31], v[72:75], v[220:223], v[16:31]
	ds_read_b64_tr_b16 v[220:221], v206 offset:0x2400
	ds_read_b64_tr_b16 v[222:223], v206 offset:0x2c00
	v_mfma_f32_32x32x16_bf16 v[16:31], v[76:79], v[224:227], v[16:31]
	ds_read_b64_tr_b16 v[224:225], v206 offset:0x3400
	ds_read_b64_tr_b16 v[226:227], v206 offset:0x3c00
	s_waitcnt lgkmcnt(0)
	ds_write_b128 v213, v[166:169] offset:32768
	v_mfma_f32_32x32x16_bf16 v[32:47], v[64:67], v[184:187], v[32:47]
	ds_read_b64_tr_b16 v[184:185], v206 offset:0x600
	ds_read_b64_tr_b16 v[186:187], v206 offset:0xe00
	v_mfma_f32_32x32x16_bf16 v[32:47], v[68:71], v[216:219], v[32:47]
	ds_read_b64_tr_b16 v[216:217], v206 offset:0x1600
	ds_read_b64_tr_b16 v[218:219], v206 offset:0x1e00
	v_mfma_f32_32x32x16_bf16 v[32:47], v[72:75], v[220:223], v[32:47]
	ds_read_b64_tr_b16 v[220:221], v206 offset:0x2600
	ds_read_b64_tr_b16 v[222:223], v206 offset:0x2e00
	v_mfma_f32_32x32x16_bf16 v[32:47], v[76:79], v[224:227], v[32:47]
	ds_read_b64_tr_b16 v[224:225], v206 offset:0x3600
	ds_read_b64_tr_b16 v[226:227], v206 offset:0x3e00
	s_waitcnt lgkmcnt(0)
	ds_write_b128 v214, v[170:173] offset:32768
	v_mfma_f32_32x32x16_bf16 v[48:63], v[64:67], v[184:187], v[48:63]
	v_exp_f32_e32 v215, v90
	s_waitcnt vmcnt(4)
	v_exp_f32_e32 v184, v80
	v_exp_f32_e32 v185, v81
	v_exp_f32_e32 v186, v82
	v_exp_f32_e32 v187, v83
	v_exp_f32_e32 v188, v84
	v_mfma_f32_32x32x16_bf16 v[48:63], v[68:71], v[216:219], v[48:63]
	v_exp_f32_e32 v219, v94
	v_exp_f32_e32 v189, v85
	v_exp_f32_e32 v196, v86
	v_exp_f32_e32 v197, v87
	v_exp_f32_e32 v198, v88
	v_exp_f32_e32 v199, v89
	v_exp_f32_e32 v216, v91
	v_mfma_f32_32x32x16_bf16 v[48:63], v[72:75], v[220:223], v[48:63]
	v_exp_f32_e32 v220, v95
	v_exp_f32_e32 v217, v92
	v_exp_f32_e32 v218, v93
	s_waitcnt lgkmcnt(0)
	s_barrier
; #define SBAR() __builtin_amdgcn_sched_barrier(0)
; __device__ __forceinline__ void finishSM(f32x16& p0, f32x16& p1, float alpha, float& l_reg, bf16x8& pa0, bf16x8& pa1, bf16x8& pa2, bf16x8& pa3) {
;   for (int r = 0; r < 16; ++r) p1[r] = __builtin_amdgcn_exp2f(p1[r]);
;   float ps = 0; for (int r = 0; r < 16; ++r) ps += p0[r]; for (int r = 0; r < 16; ++r) ps += p1[r];
;   { auto rr = __builtin_amdgcn_permlane32_swap(__float_as_uint(ps), __float_as_uint(ps), false, false);
;     ps = __uint_as_float(rr[0]) + __uint_as_float(rr[1]); }
;   l_reg = l_reg * alpha + ps;
;     ...
;   PK4(p0, 0, pa0); PK4(p0, 8, pa1); PK4(p1, 0, pa2); PK4(p1, 8, pa3);
; template <int BOFF> __device__ __forceinline__ void qkt_i(f32x16& p0, f32x16& p1, const int (&kb)[4], const bf16x8* qr) {
;   p0 = f32x16{}; p1 = f32x16{};
; #pragma unroll
;   for (int d0 = 0; d0 < 8; ++d0) { const int off = BOFF + (d0 >> 2) * 128;
;     const bf16x8 b0 = LDSV(kb[d0 & 3] + off), b1 = LDSV(kb[d0 & 3] + off + 8192);
;     p0 = __builtin_amdgcn_mfma_f32_32x32x16_bf16(b0, qr[d0], p0, 0, 0, 0);
;     p1 = __builtin_amdgcn_mfma_f32_32x32x16_bf16(b1, qr[d0], p1, 0, 0, 0); }
; }
; template <int D0, int BOFF> __device__ __forceinline__ void pv_one_i(f32x16& od, int vb, bf16x8 pa0, bf16x8 pa1, bf16x8 pa2, bf16x8 pa3) {
;   const s16x4 l0 = tr_read<BOFF + v_rd_off(D0, 0, 0)>(vb), h0 = tr_read<BOFF + v_rd_off(D0, 0, 1)>(vb), l1 = tr_read<BOFF + v_rd_off(D0, 1, 0)>(vb), h1 = tr_read<BOFF + v_rd_off(D0, 1, 1)>(vb);
;   const s16x4 l2 = tr_read<BOFF + v_rd_off(D0, 2, 0)>(vb), h2 = tr_read<BOFF + v_rd_off(D0, 2, 1)>(vb), l3 = tr_read<BOFF + v_rd_off(D0, 3, 0)>(vb), h3 = tr_read<BOFF + v_rd_off(D0, 3, 1)>(vb);
;   asm volatile("s_waitcnt lgkmcnt(0)" ::: "memory"); SBAR();
;     ...
;   od = __builtin_amdgcn_mfma_f32_32x32x16_bf16(pa0, PK(l0, h0), od, 0, 0, 0);
;   od = __builtin_amdgcn_mfma_f32_32x32x16_bf16(pa1, PK(l1, h1), od, 0, 0, 0);
;   od = __builtin_amdgcn_mfma_f32_32x32x16_bf16(pa2, PK(l2, h2), od, 0, 0, 0);
;   od = __builtin_amdgcn_mfma_f32_32x32x16_bf16(pa3, PK(l3, h3), od, 0, 0, 0);
	v_mfma_f32_32x32x16_bf16 v[48:63], v[76:79], v[224:227], v[48:63]
	ds_read_b128 v[64:67], v207 offset:32768
	ds_read_b128 v[80:83], v207 offset:40960
	ds_read_b128 v[162:165], v208 offset:32768
	ds_read_b128 v[166:169], v208 offset:40960
	v_exp_f32_e32 v170, v104
	v_exp_f32_e32 v171, v105
	v_exp_f32_e32 v172, v106
	v_exp_f32_e32 v173, v107
	v_exp_f32_e32 v174, v108
	v_exp_f32_e32 v175, v109
	v_exp_f32_e32 v176, v110
	v_exp_f32_e32 v111, v111
	s_waitcnt lgkmcnt(3)
	v_mfma_f32_32x32x16_bf16 v[64:79], v[64:67], v[142:145], 0
	v_exp_f32_e32 v236, v96
	v_add_f32_e32 v96, 0, v184
	v_add_f32_e32 v96, v185, v96
	v_add_f32_e32 v96, v186, v96
	s_waitcnt lgkmcnt(2)
	v_mfma_f32_32x32x16_bf16 v[80:95], v[80:83], v[142:145], 0
	v_add_f32_e32 v96, v187, v96
	v_add_f32_e32 v96, v188, v96
	v_add_f32_e32 v96, v189, v96
	s_waitcnt lgkmcnt(1)
	v_mfma_f32_32x32x16_bf16 v[64:79], v[162:165], v[138:141], v[64:79]
	v_add_f32_e32 v96, v196, v96
	v_add_f32_e32 v96, v197, v96
	v_add_f32_e32 v96, v198, v96
	s_waitcnt lgkmcnt(0)
	v_mfma_f32_32x32x16_bf16 v[80:95], v[166:169], v[138:141], v[80:95]
	ds_read_b128 v[162:165], v209 offset:32768
	ds_read_b128 v[166:169], v209 offset:40960
	v_add_f32_e32 v96, v199, v96
	v_add_f32_e32 v96, v215, v96
	v_add_f32_e32 v96, v216, v96
	v_add_f32_e32 v96, v217, v96
	v_exp_f32_e32 v237, v97
	s_waitcnt lgkmcnt(1)
	v_mfma_f32_32x32x16_bf16 v[64:79], v[162:165], v[112:115], v[64:79]
	v_add_f32_e32 v96, v218, v96
	v_exp_f32_e32 v238, v98
	v_add_f32_e32 v96, v219, v96
	v_exp_f32_e32 v239, v99
	s_waitcnt lgkmcnt(0)
	v_mfma_f32_32x32x16_bf16 v[80:95], v[166:169], v[112:115], v[80:95]
	ds_read_b128 v[162:165], v210 offset:32768
	ds_read_b128 v[166:169], v210 offset:40960
	v_add_f32_e32 v96, v220, v96
	v_exp_f32_e32 v247, v100
	v_add_f32_e32 v96, v236, v96
	v_exp_f32_e32 v248, v101
	s_waitcnt lgkmcnt(1)
	v_mfma_f32_32x32x16_bf16 v[64:79], v[162:165], v[116:119], v[64:79]
	v_add_f32_e32 v96, v237, v96
	v_exp_f32_e32 v249, v102
	v_add_f32_e32 v96, v238, v96
	v_exp_f32_e32 v252, v103
	s_waitcnt lgkmcnt(0)
	v_mfma_f32_32x32x16_bf16 v[80:95], v[166:169], v[116:119], v[80:95]
	ds_read_b128 v[162:165], v190 offset:32768
	ds_read_b128 v[166:169], v190 offset:40960
	v_add_f32_e32 v96, v239, v96
	v_add_f32_e32 v96, v247, v96
	v_add_f32_e32 v96, v248, v96
	v_add_f32_e32 v96, v249, v96
	v_add_f32_e32 v96, v252, v96
	v_add_f32_e32 v96, v170, v96
	s_waitcnt lgkmcnt(1)
	v_mfma_f32_32x32x16_bf16 v[64:79], v[162:165], v[120:123], v[64:79]
	v_add_f32_e32 v96, v171, v96
	v_add_f32_e32 v96, v172, v96
	v_add_f32_e32 v96, v173, v96
	v_add_f32_e32 v96, v174, v96
	v_add_f32_e32 v96, v175, v96
	s_waitcnt lgkmcnt(0)
	v_mfma_f32_32x32x16_bf16 v[80:95], v[166:169], v[120:123], v[80:95]
	ds_read_b128 v[162:165], v191 offset:32768
	ds_read_b128 v[166:169], v191 offset:40960
	v_add_f32_e32 v96, v176, v96
	v_add_f32_e32 v181, v111, v96
	v_mov_b32_e32 v183, v181
	s_nop 1
	v_permlane32_swap_b32_e32 v181, v183
	v_pk_add_f32 v[96:97], v[180:181], v[182:183]
	s_waitcnt lgkmcnt(1)
	v_mfma_f32_32x32x16_bf16 v[64:79], v[162:165], v[124:127], v[64:79]
	s_nop 0
	v_add_f32_e32 v96, v128, v96
	v_add_f32_e32 v128, v96, v97
	v_cvt_pk_bf16_f32 v96, v184, v185
	v_cvt_pk_bf16_f32 v97, v186, v187
	s_waitcnt lgkmcnt(0)
	v_mfma_f32_32x32x16_bf16 v[80:95], v[166:169], v[124:127], v[80:95]
	ds_read_b128 v[162:165], v192 offset:32768
	ds_read_b128 v[166:169], v192 offset:40960
	v_cvt_pk_bf16_f32 v98, v188, v189
	v_cvt_pk_bf16_f32 v99, v196, v197
	v_cvt_pk_bf16_f32 v100, v198, v199
	v_cvt_pk_bf16_f32 v101, v215, v216
	v_cvt_pk_bf16_f32 v102, v217, v218
	v_cvt_pk_bf16_f32 v103, v219, v220
	s_waitcnt lgkmcnt(1)
	v_mfma_f32_32x32x16_bf16 v[64:79], v[162:165], v[130:133], v[64:79]
	v_cvt_pk_bf16_f32 v104, v236, v237
	v_cvt_pk_bf16_f32 v105, v238, v239
	v_cvt_pk_bf16_f32 v106, v247, v248
	v_cvt_pk_bf16_f32 v107, v249, v252
	v_cvt_pk_bf16_f32 v108, v170, v171
	s_waitcnt lgkmcnt(0)
	v_mfma_f32_32x32x16_bf16 v[80:95], v[166:169], v[130:133], v[80:95]
	ds_read_b128 v[162:165], v193 offset:32768
	ds_read_b128 v[166:169], v193 offset:40960
	ds_read_b64_tr_b16 v[180:181], v206 offset:0x4000
	ds_read_b64_tr_b16 v[182:183], v206 offset:0x4800
	ds_read_b64_tr_b16 v[184:185], v206 offset:0x5000
	ds_read_b64_tr_b16 v[186:187], v206 offset:0x5800
	ds_read_b64_tr_b16 v[216:217], v206 offset:0x6000
	ds_read_b64_tr_b16 v[218:219], v206 offset:0x6800
	ds_read_b64_tr_b16 v[220:221], v206 offset:0x7000
	ds_read_b64_tr_b16 v[222:223], v206 offset:0x7800
	v_cvt_pk_bf16_f32 v109, v172, v173
	v_cvt_pk_bf16_f32 v110, v174, v175
	v_cvt_pk_bf16_f32 v111, v176, v111
	s_nop 0
	v_permlane32_swap_b32_e32 v96, v98
	v_permlane32_swap_b32_e32 v97, v99
	s_waitcnt lgkmcnt(9)
	v_mfma_f32_32x32x16_bf16 v[64:79], v[162:165], v[134:137], v[64:79]
	v_permlane32_swap_b32_e32 v100, v102
	v_permlane32_swap_b32_e32 v101, v103
	v_permlane32_swap_b32_e32 v104, v106
	v_permlane32_swap_b32_e32 v105, v107
	v_permlane32_swap_b32_e32 v108, v110
	s_waitcnt lgkmcnt(8)
	v_mfma_f32_32x32x16_bf16 v[80:95], v[166:169], v[134:137], v[80:95]
	v_permlane32_swap_b32_e32 v109, v111
	v_add_co_u32_e32 v166, vcc, s52, v178
	s_nop 1
	v_addc_co_u32_e32 v167, vcc, -1, v179, vcc
	v_add_co_u32_e32 v170, vcc, s53, v178
	s_nop 1
	v_addc_co_u32_e32 v171, vcc, -1, v179, vcc
	global_load_dwordx4 v[162:165], v[166:167], off
	s_nop 0
	global_load_dwordx4 v[166:169], v[166:167], off offset:-512
	s_nop 0
	global_load_dwordx4 v[174:177], v[170:171], off
	s_nop 0
	global_load_dwordx4 v[170:173], v[170:171], off offset:-512
	s_waitcnt lgkmcnt(0)
	s_waitcnt vmcnt(4)
; #define SBAR() __builtin_amdgcn_sched_barrier(0)
; template <int D0, int BOFF> __device__ __forceinline__ void pv_one_i(f32x16& od, int vb, bf16x8 pa0, bf16x8 pa1, bf16x8 pa2, bf16x8 pa3) {
;   const s16x4 l0 = tr_read<BOFF + v_rd_off(D0, 0, 0)>(vb), h0 = tr_read<BOFF + v_rd_off(D0, 0, 1)>(vb), l1 = tr_read<BOFF + v_rd_off(D0, 1, 0)>(vb), h1 = tr_read<BOFF + v_rd_off(D0, 1, 1)>(vb);
;   const s16x4 l2 = tr_read<BOFF + v_rd_off(D0, 2, 0)>(vb), h2 = tr_read<BOFF + v_rd_off(D0, 2, 1)>(vb), l3 = tr_read<BOFF + v_rd_off(D0, 3, 0)>(vb), h3 = tr_read<BOFF + v_rd_off(D0, 3, 1)>(vb);
;   asm volatile("s_waitcnt lgkmcnt(0)" ::: "memory"); SBAR();
;     ...
;   od = __builtin_amdgcn_mfma_f32_32x32x16_bf16(pa0, PK(l0, h0), od, 0, 0, 0);
;   od = __builtin_amdgcn_mfma_f32_32x32x16_bf16(pa1, PK(l1, h1), od, 0, 0, 0);
;   od = __builtin_amdgcn_mfma_f32_32x32x16_bf16(pa2, PK(l2, h2), od, 0, 0, 0);
;   od = __builtin_amdgcn_mfma_f32_32x32x16_bf16(pa3, PK(l3, h3), od, 0, 0, 0);
;     ...
; }
; template <int BOFF> __device__ __forceinline__ void pv_i(f32x16* o, int vb, bf16x8 pa0, bf16x8 pa1, bf16x8 pa2, bf16x8 pa3) {
;   pv_one_i<0, BOFF>(o[0], vb, pa0, pa1, pa2, pa3); pv_one_i<1, BOFF>(o[1], vb, pa0, pa1, pa2, pa3); pv_one_i<2, BOFF>(o[2], vb, pa0, pa1, pa2, pa3); pv_one_i<3, BOFF>(o[3], vb, pa0, pa1, pa2, pa3);
	ds_write_b128 v211, v[146:149]
	s_nop 0
	v_mfma_f32_32x32x16_bf16 v[0:15], v[96:99], v[180:183], v[0:15]
	ds_read_b64_tr_b16 v[180:181], v206 offset:0x4200
	ds_read_b64_tr_b16 v[182:183], v206 offset:0x4a00
	v_mfma_f32_32x32x16_bf16 v[0:15], v[100:103], v[184:187], v[0:15]
	ds_read_b64_tr_b16 v[184:185], v206 offset:0x5200
	ds_read_b64_tr_b16 v[186:187], v206 offset:0x5a00
	v_mfma_f32_32x32x16_bf16 v[0:15], v[104:107], v[216:219], v[0:15]
	ds_read_b64_tr_b16 v[216:217], v206 offset:0x6200
	ds_read_b64_tr_b16 v[218:219], v206 offset:0x6a00
	v_mfma_f32_32x32x16_bf16 v[0:15], v[108:111], v[220:223], v[0:15]
	ds_read_b64_tr_b16 v[220:221], v206 offset:0x7200
	ds_read_b64_tr_b16 v[222:223], v206 offset:0x7a00
	s_waitcnt lgkmcnt(0)
	ds_write_b128 v212, v[158:161]
	v_mfma_f32_32x32x16_bf16 v[16:31], v[96:99], v[180:183], v[16:31]
	ds_read_b64_tr_b16 v[180:181], v206 offset:0x4400
	ds_read_b64_tr_b16 v[182:183], v206 offset:0x4c00
	v_mfma_f32_32x32x16_bf16 v[16:31], v[100:103], v[184:187], v[16:31]
	ds_read_b64_tr_b16 v[184:185], v206 offset:0x5400
	ds_read_b64_tr_b16 v[186:187], v206 offset:0x5c00
	v_mfma_f32_32x32x16_bf16 v[16:31], v[104:107], v[216:219], v[16:31]
	ds_read_b64_tr_b16 v[216:217], v206 offset:0x6400
	ds_read_b64_tr_b16 v[218:219], v206 offset:0x6c00
	v_mfma_f32_32x32x16_bf16 v[16:31], v[108:111], v[220:223], v[16:31]
	ds_read_b64_tr_b16 v[220:221], v206 offset:0x7400
	ds_read_b64_tr_b16 v[222:223], v206 offset:0x7c00
	s_waitcnt lgkmcnt(0)
	ds_write_b128 v213, v[150:153]
	v_mfma_f32_32x32x16_bf16 v[32:47], v[96:99], v[180:183], v[32:47]
	ds_read_b64_tr_b16 v[180:181], v206 offset:0x4600
	ds_read_b64_tr_b16 v[182:183], v206 offset:0x4e00
	v_mfma_f32_32x32x16_bf16 v[32:47], v[100:103], v[184:187], v[32:47]
	ds_read_b64_tr_b16 v[184:185], v206 offset:0x5600
	ds_read_b64_tr_b16 v[186:187], v206 offset:0x5e00
	v_mfma_f32_32x32x16_bf16 v[32:47], v[104:107], v[216:219], v[32:47]
	ds_read_b64_tr_b16 v[216:217], v206 offset:0x6600
	ds_read_b64_tr_b16 v[218:219], v206 offset:0x6e00
	v_mfma_f32_32x32x16_bf16 v[32:47], v[108:111], v[220:223], v[32:47]
	ds_read_b64_tr_b16 v[220:221], v206 offset:0x7600
	ds_read_b64_tr_b16 v[222:223], v206 offset:0x7e00
	s_waitcnt lgkmcnt(0)
	ds_write_b128 v214, v[154:157]
	v_mfma_f32_32x32x16_bf16 v[48:63], v[96:99], v[180:183], v[48:63]
	s_waitcnt vmcnt(4)
	v_exp_f32_e32 v180, v64
	v_exp_f32_e32 v181, v65
	v_exp_f32_e32 v182, v66
	v_exp_f32_e32 v183, v67
	v_exp_f32_e32 v188, v72
	v_exp_f32_e32 v189, v73
	v_mfma_f32_32x32x16_bf16 v[48:63], v[100:103], v[184:187], v[48:63]
	v_exp_f32_e32 v184, v68
	v_exp_f32_e32 v185, v69
	v_exp_f32_e32 v186, v70
	v_exp_f32_e32 v187, v71
	v_exp_f32_e32 v196, v74
	v_exp_f32_e32 v197, v75
	v_exp_f32_e32 v198, v76
	v_mfma_f32_32x32x16_bf16 v[48:63], v[104:107], v[216:219], v[48:63]
	v_exp_f32_e32 v199, v77
	v_exp_f32_e32 v216, v78
	v_exp_f32_e32 v217, v79
	s_waitcnt lgkmcnt(0)
	s_barrier
	v_mfma_f32_32x32x16_bf16 v[48:63], v[108:111], v[220:223], v[48:63]
	ds_read_b128 v[64:67], v207
	ds_read_b128 v[68:71], v207 offset:8192
	ds_read_b128 v[146:149], v208
	ds_read_b128 v[150:153], v208 offset:8192
	v_exp_f32_e32 v154, v88
	v_exp_f32_e32 v155, v89
	v_exp_f32_e32 v156, v90
	v_exp_f32_e32 v157, v91
	v_exp_f32_e32 v158, v92
	v_exp_f32_e32 v159, v93
	v_exp_f32_e32 v160, v94
	v_exp_f32_e32 v95, v95
	s_waitcnt lgkmcnt(3)
	v_mfma_f32_32x32x16_bf16 v[96:111], v[64:67], v[142:145], 0
	v_exp_f32_e32 v236, v80
	v_add_f32_e32 v80, 0, v180
	v_add_f32_e32 v80, v181, v80
	v_add_f32_e32 v80, v182, v80
	s_waitcnt lgkmcnt(2)
	v_mfma_f32_32x32x16_bf16 v[64:79], v[68:71], v[142:145], 0
	v_add_f32_e32 v80, v183, v80
	v_add_f32_e32 v80, v184, v80
	v_add_f32_e32 v80, v185, v80
	s_waitcnt lgkmcnt(1)
	v_mfma_f32_32x32x16_bf16 v[96:111], v[146:149], v[138:141], v[96:111]
	v_add_f32_e32 v80, v186, v80
	v_add_f32_e32 v80, v187, v80
	v_add_f32_e32 v80, v188, v80
	s_waitcnt lgkmcnt(0)
	v_mfma_f32_32x32x16_bf16 v[64:79], v[150:153], v[138:141], v[64:79]
	ds_read_b128 v[146:149], v209
	ds_read_b128 v[150:153], v209 offset:8192
	v_add_f32_e32 v80, v189, v80
	v_add_f32_e32 v80, v196, v80
	v_add_f32_e32 v80, v197, v80
	v_add_f32_e32 v80, v198, v80
	v_exp_f32_e32 v237, v81
	s_waitcnt lgkmcnt(1)
	v_mfma_f32_32x32x16_bf16 v[96:111], v[146:149], v[112:115], v[96:111]
	v_add_f32_e32 v80, v199, v80
	v_exp_f32_e32 v238, v82
	v_add_f32_e32 v80, v216, v80
	v_exp_f32_e32 v239, v83
	s_waitcnt lgkmcnt(0)
	v_mfma_f32_32x32x16_bf16 v[64:79], v[150:153], v[112:115], v[64:79]
	ds_read_b128 v[146:149], v210
	ds_read_b128 v[150:153], v210 offset:8192
	v_add_f32_e32 v80, v217, v80
	v_exp_f32_e32 v247, v84
	v_add_f32_e32 v80, v236, v80
	v_exp_f32_e32 v248, v85
	s_waitcnt lgkmcnt(1)
	v_mfma_f32_32x32x16_bf16 v[96:111], v[146:149], v[116:119], v[96:111]
	v_add_f32_e32 v80, v237, v80
	v_exp_f32_e32 v249, v86
	v_add_f32_e32 v80, v238, v80
	v_exp_f32_e32 v252, v87
	s_waitcnt lgkmcnt(0)
	v_mfma_f32_32x32x16_bf16 v[64:79], v[150:153], v[116:119], v[64:79]
	ds_read_b128 v[146:149], v190 offset:0
	ds_read_b128 v[150:153], v190 offset:8192
	v_add_f32_e32 v80, v239, v80
	v_add_f32_e32 v80, v247, v80
	v_add_f32_e32 v80, v248, v80
	v_add_f32_e32 v80, v249, v80
	v_add_f32_e32 v80, v252, v80
	v_add_f32_e32 v80, v154, v80
	s_waitcnt lgkmcnt(1)
	v_mfma_f32_32x32x16_bf16 v[96:111], v[146:149], v[120:123], v[96:111]
	v_add_f32_e32 v80, v155, v80
	v_add_f32_e32 v80, v156, v80
	v_add_f32_e32 v80, v157, v80
	v_add_f32_e32 v80, v158, v80
	v_add_f32_e32 v80, v159, v80
	s_waitcnt lgkmcnt(0)
	v_mfma_f32_32x32x16_bf16 v[64:79], v[150:153], v[120:123], v[64:79]
	ds_read_b128 v[146:149], v191 offset:0
	ds_read_b128 v[150:153], v191 offset:8192
	v_add_f32_e32 v80, v160, v80
	v_add_f32_e32 v80, v95, v80
	v_mov_b32_e32 v81, v80
	s_nop 1
	v_permlane32_swap_b32_e32 v80, v81
	v_add_f32_e32 v80, v80, v81
	s_waitcnt lgkmcnt(1)
; #define SBAR() __builtin_amdgcn_sched_barrier(0)
; #define SLOAD(i, k0) do { sr_[i].vs0 = ld8(&Vh[(long)((k0) + sr) * LDK + sc]); sr_[i].vs1 = ld8(&Vh[(long)((k0) + 32 + sr) * LDK + sc]); \
;     sr_[i].ks0 = ld8(&Kh[(long)((k0) + sr) * LDK + sc]); sr_[i].ks1 = ld8(&Kh[(long)((k0) + 32 + sr) * LDK + sc]); } while (0)
; #define SWAIT() asm volatile("s_waitcnt vmcnt(4)" ::: "memory")
; #define SWRITE_I(B, i) do { LDSV(wv0 + (B) * 16384) = sr_[i].vs0; LDSV(wv1 + (B) * 16384) = sr_[i].vs1; LDSV(wk0 + (B) * 16384) = sr_[i].ks0; LDSV(wk1 + (B) * 16384) = sr_[i].ks1; } while (0)
; template <int BOFF> __device__ __forceinline__ void qkt_i(f32x16& p0, f32x16& p1, const int (&kb)[4], const bf16x8* qr) {
;   p0 = f32x16{}; p1 = f32x16{};
; #pragma unroll
;   for (int d0 = 0; d0 < 8; ++d0) { const int off = BOFF + (d0 >> 2) * 128;
;     const bf16x8 b0 = LDSV(kb[d0 & 3] + off), b1 = LDSV(kb[d0 & 3] + off + 8192);
;     p0 = __builtin_amdgcn_mfma_f32_32x32x16_bf16(b0, qr[d0], p0, 0, 0, 0);
;     p1 = __builtin_amdgcn_mfma_f32_32x32x16_bf16(b1, qr[d0], p1, 0, 0, 0); }
; }
; template <int D0, int BOFF> __device__ __forceinline__ void pv_one_i(f32x16& od, int vb, bf16x8 pa0, bf16x8 pa1, bf16x8 pa2, bf16x8 pa3) {
;   const s16x4 l0 = tr_read<BOFF + v_rd_off(D0, 0, 0)>(vb), h0 = tr_read<BOFF + v_rd_off(D0, 0, 1)>(vb), l1 = tr_read<BOFF + v_rd_off(D0, 1, 0)>(vb), h1 = tr_read<BOFF + v_rd_off(D0, 1, 1)>(vb);
;   const s16x4 l2 = tr_read<BOFF + v_rd_off(D0, 2, 0)>(vb), h2 = tr_read<BOFF + v_rd_off(D0, 2, 1)>(vb), l3 = tr_read<BOFF + v_rd_off(D0, 3, 0)>(vb), h3 = tr_read<BOFF + v_rd_off(D0, 3, 1)>(vb);
;   asm volatile("s_waitcnt lgkmcnt(0)" ::: "memory"); SBAR();
;     ...
;   od = __builtin_amdgcn_mfma_f32_32x32x16_bf16(pa0, PK(l0, h0), od, 0, 0, 0);
;   od = __builtin_amdgcn_mfma_f32_32x32x16_bf16(pa1, PK(l1, h1), od, 0, 0, 0);
;   od = __builtin_amdgcn_mfma_f32_32x32x16_bf16(pa2, PK(l2, h2), od, 0, 0, 0);
;   od = __builtin_amdgcn_mfma_f32_32x32x16_bf16(pa3, PK(l3, h3), od, 0, 0, 0);
; template <bool PARTIAL, bool FIXED> ...
;     ...
;   int j = 1;
;   for (; j + 6 < NT; j += 6) {
;     HALF_B(1, 0, SLOAD(1, (j + 2) * KVBLK), do { SWAIT(); SWRITE_I(2, 0); } while (0));
	v_mfma_f32_32x32x16_bf16 v[96:111], v[146:149], v[124:127], v[96:111]
	v_add_f32_e32 v215, v128, v80
	v_cvt_pk_bf16_f32 v80, v180, v181
	v_cvt_pk_bf16_f32 v81, v182, v183
	v_cvt_pk_bf16_f32 v82, v184, v185
	v_cvt_pk_bf16_f32 v83, v186, v187
	s_waitcnt lgkmcnt(0)
	v_mfma_f32_32x32x16_bf16 v[64:79], v[150:153], v[124:127], v[64:79]
	ds_read_b128 v[146:149], v192 offset:0
	ds_read_b128 v[150:153], v192 offset:8192
	v_cvt_pk_bf16_f32 v84, v188, v189
	v_cvt_pk_bf16_f32 v85, v196, v197
	v_cvt_pk_bf16_f32 v86, v198, v199
	v_cvt_pk_bf16_f32 v87, v216, v217
	v_cvt_pk_bf16_f32 v88, v236, v237
	v_cvt_pk_bf16_f32 v89, v238, v239
	s_waitcnt lgkmcnt(1)
	v_mfma_f32_32x32x16_bf16 v[96:111], v[146:149], v[130:133], v[96:111]
	v_cvt_pk_bf16_f32 v90, v247, v248
	v_cvt_pk_bf16_f32 v91, v249, v252
	v_cvt_pk_bf16_f32 v92, v154, v155
	v_cvt_pk_bf16_f32 v93, v156, v157
	v_cvt_pk_bf16_f32 v94, v158, v159
	s_waitcnt lgkmcnt(0)
	v_mfma_f32_32x32x16_bf16 v[64:79], v[150:153], v[130:133], v[64:79]
	ds_read_b128 v[146:149], v193 offset:0
	ds_read_b128 v[150:153], v193 offset:8192
	ds_read_b64_tr_b16 v[180:181], v206 offset:0x8000
	ds_read_b64_tr_b16 v[182:183], v206 offset:0x8800
	ds_read_b64_tr_b16 v[184:185], v206 offset:0x9000
	ds_read_b64_tr_b16 v[186:187], v206 offset:0x9800
	ds_read_b64_tr_b16 v[216:217], v206 offset:0xa000
	ds_read_b64_tr_b16 v[218:219], v206 offset:0xa800
	ds_read_b64_tr_b16 v[220:221], v206 offset:0xb000
	ds_read_b64_tr_b16 v[222:223], v206 offset:0xb800
	v_cvt_pk_bf16_f32 v95, v160, v95
	s_nop 0
	v_permlane32_swap_b32_e32 v80, v82
	v_permlane32_swap_b32_e32 v81, v83
	v_permlane32_swap_b32_e32 v84, v86
	v_permlane32_swap_b32_e32 v85, v87
	s_waitcnt lgkmcnt(9)
	v_mfma_f32_32x32x16_bf16 v[96:111], v[146:149], v[134:137], v[96:111]
	v_permlane32_swap_b32_e32 v88, v90
	v_permlane32_swap_b32_e32 v89, v91
	v_permlane32_swap_b32_e32 v92, v94
	v_permlane32_swap_b32_e32 v93, v95
	s_waitcnt lgkmcnt(8)
	v_mfma_f32_32x32x16_bf16 v[64:79], v[150:153], v[134:137], v[64:79]
	v_add_co_u32_e32 v150, vcc, s58, v178
	s_nop 1
	v_addc_co_u32_e32 v151, vcc, -1, v179, vcc
	global_load_dwordx4 v[146:149], v[150:151], off
	global_load_dwordx4 v[154:157], v[150:151], off offset:-512
	s_nop 0
	global_load_dwordx4 v[150:153], v[178:179], off
	global_load_dwordx4 v[158:161], v[178:179], off offset:-512
	s_waitcnt lgkmcnt(0)
	s_waitcnt vmcnt(4)
	ds_write_b128 v211, v[162:165] offset:16384
	s_nop 0
	v_mfma_f32_32x32x16_bf16 v[0:15], v[80:83], v[180:183], v[0:15]
	ds_read_b64_tr_b16 v[180:181], v206 offset:0x8200
	ds_read_b64_tr_b16 v[182:183], v206 offset:0x8a00
	v_mfma_f32_32x32x16_bf16 v[0:15], v[84:87], v[184:187], v[0:15]
	ds_read_b64_tr_b16 v[184:185], v206 offset:0x9200
	ds_read_b64_tr_b16 v[186:187], v206 offset:0x9a00
	v_mfma_f32_32x32x16_bf16 v[0:15], v[88:91], v[216:219], v[0:15]
	ds_read_b64_tr_b16 v[216:217], v206 offset:0xa200
	ds_read_b64_tr_b16 v[218:219], v206 offset:0xaa00
	v_mfma_f32_32x32x16_bf16 v[0:15], v[92:95], v[220:223], v[0:15]
	ds_read_b64_tr_b16 v[220:221], v206 offset:0xb200
	ds_read_b64_tr_b16 v[222:223], v206 offset:0xba00
	s_waitcnt lgkmcnt(0)
	ds_write_b128 v212, v[174:177] offset:16384
	v_mfma_f32_32x32x16_bf16 v[16:31], v[80:83], v[180:183], v[16:31]
	ds_read_b64_tr_b16 v[180:181], v206 offset:0x8400
	ds_read_b64_tr_b16 v[182:183], v206 offset:0x8c00
	v_mfma_f32_32x32x16_bf16 v[16:31], v[84:87], v[184:187], v[16:31]
	ds_read_b64_tr_b16 v[184:185], v206 offset:0x9400
	ds_read_b64_tr_b16 v[186:187], v206 offset:0x9c00
	v_mfma_f32_32x32x16_bf16 v[16:31], v[88:91], v[216:219], v[16:31]
	ds_read_b64_tr_b16 v[216:217], v206 offset:0xa400
	ds_read_b64_tr_b16 v[218:219], v206 offset:0xac00
	v_mfma_f32_32x32x16_bf16 v[16:31], v[92:95], v[220:223], v[16:31]
	ds_read_b64_tr_b16 v[220:221], v206 offset:0xb400
	ds_read_b64_tr_b16 v[222:223], v206 offset:0xbc00
	s_waitcnt lgkmcnt(0)
	ds_write_b128 v213, v[166:169] offset:16384
	v_mfma_f32_32x32x16_bf16 v[32:47], v[80:83], v[180:183], v[32:47]
	ds_read_b64_tr_b16 v[180:181], v206 offset:0x8600
	ds_read_b64_tr_b16 v[182:183], v206 offset:0x8e00
	v_mfma_f32_32x32x16_bf16 v[32:47], v[84:87], v[184:187], v[32:47]
	ds_read_b64_tr_b16 v[184:185], v206 offset:0x9600
	ds_read_b64_tr_b16 v[186:187], v206 offset:0x9e00
	v_mfma_f32_32x32x16_bf16 v[32:47], v[88:91], v[216:219], v[32:47]
	ds_read_b64_tr_b16 v[216:217], v206 offset:0xa600
	ds_read_b64_tr_b16 v[218:219], v206 offset:0xae00
	v_mfma_f32_32x32x16_bf16 v[32:47], v[92:95], v[220:223], v[32:47]
	ds_read_b64_tr_b16 v[220:221], v206 offset:0xb600
	ds_read_b64_tr_b16 v[222:223], v206 offset:0xbe00
	s_waitcnt lgkmcnt(0)
	ds_write_b128 v214, v[170:173] offset:16384
	v_mfma_f32_32x32x16_bf16 v[48:63], v[80:83], v[180:183], v[48:63]
	v_exp_f32_e32 v229, v96
	v_exp_f32_e32 v243, v97
	v_exp_f32_e32 v244, v98
	v_exp_f32_e32 v246, v99
	v_exp_f32_e32 v242, v100
	v_exp_f32_e32 v245, v101
	v_exp_f32_e32 v227, v102
	v_mfma_f32_32x32x16_bf16 v[48:63], v[84:87], v[184:187], v[48:63]
	v_exp_f32_e32 v228, v103
	v_exp_f32_e32 v226, v105
	v_exp_f32_e32 v224, v106
	v_exp_f32_e32 v225, v107
	s_waitcnt vmcnt(4)
	s_add_i32 s28, s28, 6
	v_lshl_add_u64 v[178:179], v[178:179], 0, s[60:61]
	v_mfma_f32_32x32x16_bf16 v[48:63], v[88:91], v[216:219], v[48:63]
	v_exp_f32_e32 v219, v110
	s_cmpk_lt_u32 s28, 0x75
	v_mfma_f32_32x32x16_bf16 v[48:63], v[92:95], v[220:223], v[48:63]
	v_exp_f32_e32 v223, v104
	v_exp_f32_e32 v220, v108
	v_exp_f32_e32 v222, v109
	v_exp_f32_e32 v221, v111
	s_cbranch_scc1 .LBB0_352
; #define SWRITE_I(B, i) do { LDSV(wv0 + (B) * 16384) = sr_[i].vs0; LDSV(wv1 + (B) * 16384) = sr_[i].vs1; LDSV(wk0 + (B) * 16384) = sr_[i].ks0; LDSV(wk1 + (B) * 16384) = sr_[i].ks1; } while (0)
; #define NOP_() do { } while (0)
; template <bool PARTIAL, bool FIXED> ...
;     ...
;   if constexpr (!PARTIAL) { const int i1 = tid & 255;
;     warm0 = *(const unsigned*)(Qb_n + (long)(tid >> 1) * LDQ + (tid & 1) * 64);
;     warm1 = *(const unsigned*)((tid < 256 ? Kh_n : Vh_n) + (long)(i1 >> 1) * LDK + (i1 & 1) * 64); }
;   HALF_B(1, 0, NOP_(), SWRITE_I(2, 0));
	v_mov_b32_e32 v252, 0x7fc00000
	v_readlane_b32 s8, v255, 42
	v_readlane_b32 s9, v255, 43
	s_add_u32 s2, s8, s6
	s_addc_u32 s3, s9, s7
	s_lshl_b32 s4, s65, 1
	s_add_u32 s2, s2, s4
	s_addc_u32 s3, s3, 0
	v_ashrrev_i32_e32 v82, 1, v195
	v_mov_b64_e32 v[80:81], s[2:3]
	v_mad_i64_i32 v[80:81], s[2:3], v82, s17, v[80:81]
	v_lshlrev_b32_e32 v82, 7, v195
	v_and_b32_e32 v128, 0x80, v82
	v_lshl_add_u64 v[80:81], v[80:81], 0, v[128:129]
	s_add_u32 s4, s8, s64
	global_load_dword v216, v[80:81], off
	v_cmp_gt_i32_e32 vcc, s14, v195
	v_mov_b32_e32 v80, 0xa00
	v_mov_b32_e32 v81, 0x800
	s_addc_u32 s5, s9, s57
	v_cndmask_b32_e32 v80, v80, v81, vcc
	v_mov_b32_e32 v81, v129
	v_bfe_u32 v82, v195, 1, 7
	v_lshl_add_u64 v[80:81], s[4:5], 0, v[80:81]
	s_lshl_b32 s46, s56, 1
	v_mul_u32_u24_e32 v82, 0x600, v82
	v_lshl_add_u64 v[80:81], v[80:81], 0, s[46:47]
	v_lshlrev_b32_e32 v82, 1, v82
	v_mov_b32_e32 v83, v129
	v_lshl_add_u64 v[80:81], v[80:81], 0, v[82:83]
	v_lshl_add_u64 v[80:81], v[80:81], 0, v[128:129]
	global_load_dword v217, v[80:81], off
	v_and_b32_e32 v247, 0x3fffffc0, v195
	s_waitcnt lgkmcnt(0)
	s_barrier
	ds_read_b128 v[80:83], v207 offset:16384
	ds_read_b128 v[96:99], v207 offset:24576
	ds_read_b128 v[100:103], v208 offset:16384
	ds_read_b128 v[170:173], v208 offset:24576
	v_exp_f32_e32 v104, v68
	v_exp_f32_e32 v105, v69
	s_waitcnt lgkmcnt(3)
	v_mfma_f32_32x32x16_bf16 v[80:95], v[80:83], v[142:145], 0
	v_exp_f32_e32 v106, v70
	v_exp_f32_e32 v107, v71
	v_exp_f32_e32 v108, v72
	v_exp_f32_e32 v109, v73
	v_exp_f32_e32 v110, v74
	v_exp_f32_e32 v111, v75
	v_exp_f32_e32 v196, v76
	s_waitcnt lgkmcnt(1)
	v_mfma_f32_32x32x16_bf16 v[80:95], v[100:103], v[138:141], v[80:95]
	ds_read_b128 v[100:103], v209 offset:16384
	ds_read_b128 v[162:165], v209 offset:24576
	v_exp_f32_e32 v197, v77
	v_exp_f32_e32 v198, v78
	v_exp_f32_e32 v79, v79
	s_waitcnt lgkmcnt(1)
	v_mfma_f32_32x32x16_bf16 v[80:95], v[100:103], v[112:115], v[80:95]
	ds_read_b128 v[100:103], v210 offset:16384
	ds_read_b128 v[166:169], v210 offset:24576
	s_waitcnt lgkmcnt(1)
	v_mfma_f32_32x32x16_bf16 v[80:95], v[100:103], v[116:119], v[80:95]
	ds_read_b128 v[100:103], v190 offset:16384
	ds_read_b128 v[174:177], v190 offset:24576
	s_waitcnt lgkmcnt(1)
	v_mfma_f32_32x32x16_bf16 v[80:95], v[100:103], v[120:123], v[80:95]
	ds_read_b128 v[100:103], v191 offset:16384
	ds_read_b128 v[178:181], v191 offset:24576
	s_waitcnt lgkmcnt(1)
	v_mfma_f32_32x32x16_bf16 v[80:95], v[100:103], v[124:127], v[80:95]
	ds_read_b128 v[100:103], v192 offset:16384
	ds_read_b128 v[182:185], v192 offset:24576
	s_waitcnt lgkmcnt(1)
	v_mfma_f32_32x32x16_bf16 v[80:95], v[100:103], v[130:133], v[80:95]
	ds_read_b128 v[100:103], v193 offset:16384
	ds_read_b128 v[186:189], v193 offset:24576
	s_waitcnt lgkmcnt(1)
	v_mfma_f32_32x32x16_bf16 v[80:95], v[100:103], v[134:137], v[80:95]
	v_exp_f32_e32 v100, v64
	v_add_f32_e32 v64, 0, v229
	v_add_f32_e32 v64, v243, v64
	v_add_f32_e32 v64, v244, v64
	v_add_f32_e32 v64, v246, v64
	v_add_f32_e32 v64, v242, v64
	v_add_f32_e32 v64, v245, v64
	v_add_f32_e32 v64, v227, v64
	v_add_f32_e32 v64, v228, v64
	v_add_f32_e32 v64, v223, v64
	v_add_f32_e32 v64, v226, v64
	v_add_f32_e32 v64, v224, v64
	v_add_f32_e32 v64, v225, v64
	v_add_f32_e32 v64, v220, v64
	v_exp_f32_e32 v101, v65
	v_add_f32_e32 v64, v222, v64
	v_exp_f32_e32 v102, v66
	v_add_f32_e32 v64, v219, v64
	v_exp_f32_e32 v103, v67
	v_add_f32_e32 v64, v221, v64
	v_add_f32_e32 v64, v100, v64
	v_add_f32_e32 v64, v101, v64
	v_add_f32_e32 v64, v102, v64
	v_add_f32_e32 v64, v103, v64
	v_add_f32_e32 v64, v104, v64
	v_add_f32_e32 v64, v105, v64
	v_add_f32_e32 v64, v106, v64
	v_add_f32_e32 v64, v107, v64
	v_add_f32_e32 v64, v108, v64
	v_add_f32_e32 v64, v109, v64
	v_add_f32_e32 v64, v110, v64
	v_add_f32_e32 v64, v111, v64
	v_add_f32_e32 v64, v196, v64
	v_add_f32_e32 v64, v197, v64
	v_add_f32_e32 v64, v198, v64
	v_add_f32_e32 v128, v79, v64
	v_mov_b32_e32 v218, v128
	s_nop 1
	v_permlane32_swap_b32_e32 v128, v218
	v_cvt_pk_bf16_f32 v64, v229, v243
	v_cvt_pk_bf16_f32 v65, v244, v246
	v_cvt_pk_bf16_f32 v66, v242, v245
	v_cvt_pk_bf16_f32 v67, v227, v228
	v_cvt_pk_bf16_f32 v68, v223, v226
	v_cvt_pk_bf16_f32 v69, v224, v225
	v_cvt_pk_bf16_f32 v70, v220, v222
	v_cvt_pk_bf16_f32 v71, v219, v221
	v_cvt_pk_bf16_f32 v72, v100, v101
	v_cvt_pk_bf16_f32 v73, v102, v103
	v_cvt_pk_bf16_f32 v74, v104, v105
	v_cvt_pk_bf16_f32 v75, v106, v107
	v_cvt_pk_bf16_f32 v76, v108, v109
	v_cvt_pk_bf16_f32 v77, v110, v111
	v_cvt_pk_bf16_f32 v78, v196, v197
	v_cvt_pk_bf16_f32 v79, v198, v79
	s_nop 0
	v_permlane32_swap_b32_e32 v64, v66
	v_permlane32_swap_b32_e32 v65, v67
	v_permlane32_swap_b32_e32 v68, v70
	v_permlane32_swap_b32_e32 v69, v71
	v_permlane32_swap_b32_e32 v72, v74
	v_permlane32_swap_b32_e32 v73, v75
	v_permlane32_swap_b32_e32 v76, v78
	v_permlane32_swap_b32_e32 v77, v79
	ds_read_b64_tr_b16 v[100:101], v206 offset:0
	ds_read_b64_tr_b16 v[102:103], v206 offset:0x800
	ds_read_b64_tr_b16 v[104:105], v206 offset:0x1000
	ds_read_b64_tr_b16 v[106:107], v206 offset:0x1800
	ds_read_b64_tr_b16 v[108:109], v206 offset:0x2000
	ds_read_b64_tr_b16 v[110:111], v206 offset:0x2800
	ds_read_b64_tr_b16 v[220:221], v206 offset:0x3000
	ds_read_b64_tr_b16 v[222:223], v206 offset:0x3800
	s_waitcnt lgkmcnt(0)
	s_nop 0
	v_mfma_f32_32x32x16_bf16 v[0:15], v[64:67], v[100:103], v[0:15]
	ds_read_b64_tr_b16 v[100:101], v206 offset:0x200
	ds_read_b64_tr_b16 v[102:103], v206 offset:0xa00
	v_mfma_f32_32x32x16_bf16 v[0:15], v[68:71], v[104:107], v[0:15]
	ds_read_b64_tr_b16 v[104:105], v206 offset:0x1200
	ds_read_b64_tr_b16 v[106:107], v206 offset:0x1a00
	v_mfma_f32_32x32x16_bf16 v[0:15], v[72:75], v[108:111], v[0:15]
	ds_read_b64_tr_b16 v[108:109], v206 offset:0x2200
	ds_read_b64_tr_b16 v[110:111], v206 offset:0x2a00
	v_mfma_f32_32x32x16_bf16 v[0:15], v[76:79], v[220:223], v[0:15]
	ds_read_b64_tr_b16 v[220:221], v206 offset:0x3200
	ds_read_b64_tr_b16 v[222:223], v206 offset:0x3a00
	s_waitcnt lgkmcnt(0)
; #define SBAR() __builtin_amdgcn_sched_barrier(0)
; #define SWRITE_I(B, i) do { LDSV(wv0 + (B) * 16384) = sr_[i].vs0; LDSV(wv1 + (B) * 16384) = sr_[i].vs1; LDSV(wk0 + (B) * 16384) = sr_[i].ks0; LDSV(wk1 + (B) * 16384) = sr_[i].ks1; } while (0)
; #define NOP_() do { } while (0)
; template <bool PARTIAL, bool FIXED> ...
;     ...
;   HALF_B(1, 0, NOP_(), SWRITE_I(2, 0));
;   HALF_A(2, 1, do { if (mask_last) { asm volatile("; masked tail tile" ::: "memory"); const float NEG = -INFINITY; \
;       _Pragma("unroll") for (int r = 8; r < 16; ++r) pA0[r] = NEG; _Pragma("unroll") for (int r = 0; r < 16; ++r) pA1[r] = NEG; } } while (0), NOP_(), NOP_());
;     ...
;   SBAR(); finishSM(pA0, pA1, alA, l_reg, pa0, pa1, pa2, pa3); SBAR();
;   pv_i<2 * 16384>(o, vbi, pa0, pa1, pa2, pa3);
	v_mfma_f32_32x32x16_bf16 v[16:31], v[64:67], v[100:103], v[16:31]
	ds_read_b64_tr_b16 v[100:101], v206 offset:0x400
	ds_read_b64_tr_b16 v[102:103], v206 offset:0xc00
	v_mfma_f32_32x32x16_bf16 v[16:31], v[68:71], v[104:107], v[16:31]
	ds_read_b64_tr_b16 v[104:105], v206 offset:0x1400
	ds_read_b64_tr_b16 v[106:107], v206 offset:0x1c00
	v_mfma_f32_32x32x16_bf16 v[16:31], v[72:75], v[108:111], v[16:31]
	ds_read_b64_tr_b16 v[108:109], v206 offset:0x2400
	ds_read_b64_tr_b16 v[110:111], v206 offset:0x2c00
	v_mfma_f32_32x32x16_bf16 v[16:31], v[76:79], v[220:223], v[16:31]
	ds_read_b64_tr_b16 v[220:221], v206 offset:0x3400
	ds_read_b64_tr_b16 v[222:223], v206 offset:0x3c00
	s_waitcnt lgkmcnt(0)
	v_mfma_f32_32x32x16_bf16 v[32:47], v[64:67], v[100:103], v[32:47]
	ds_read_b64_tr_b16 v[100:101], v206 offset:0x600
	ds_read_b64_tr_b16 v[102:103], v206 offset:0xe00
	v_mfma_f32_32x32x16_bf16 v[32:47], v[68:71], v[104:107], v[32:47]
	ds_read_b64_tr_b16 v[104:105], v206 offset:0x1600
	ds_read_b64_tr_b16 v[106:107], v206 offset:0x1e00
	v_mfma_f32_32x32x16_bf16 v[32:47], v[72:75], v[108:111], v[32:47]
	ds_read_b64_tr_b16 v[108:109], v206 offset:0x2600
	ds_read_b64_tr_b16 v[110:111], v206 offset:0x2e00
	v_mfma_f32_32x32x16_bf16 v[32:47], v[76:79], v[220:223], v[32:47]
	ds_read_b64_tr_b16 v[220:221], v206 offset:0x3600
	ds_read_b64_tr_b16 v[222:223], v206 offset:0x3e00
	s_waitcnt lgkmcnt(0)
	v_mfma_f32_32x32x16_bf16 v[48:63], v[64:67], v[100:103], v[48:63]
	s_waitcnt vmcnt(5)
	ds_write_b128 v211, v[146:149] offset:32768
	s_waitcnt vmcnt(3)
	ds_write_b128 v212, v[150:153] offset:32768
	ds_write_b128 v213, v[154:157] offset:32768
	s_waitcnt vmcnt(2)
	ds_write_b128 v214, v[158:161] offset:32768
	s_waitcnt lgkmcnt(0)
	s_barrier
	v_mfma_f32_32x32x16_bf16 v[48:63], v[68:71], v[104:107], v[48:63]
	v_mfma_f32_32x32x16_bf16 v[48:63], v[72:75], v[108:111], v[48:63]
	v_mfma_f32_32x32x16_bf16 v[48:63], v[76:79], v[220:223], v[48:63]
	ds_read_b128 v[64:67], v207 offset:32768
	ds_read_b128 v[100:103], v208 offset:32768
	s_add_i32 s2, 0, 0x18000
	s_waitcnt lgkmcnt(1)
	v_mfma_f32_32x32x16_bf16 v[64:79], v[64:67], v[142:145], 0
	s_waitcnt lgkmcnt(0)
	v_mfma_f32_32x32x16_bf16 v[64:79], v[100:103], v[138:141], v[64:79]
	ds_read_b128 v[100:103], v209 offset:32768
	s_waitcnt lgkmcnt(0)
	v_mfma_f32_32x32x16_bf16 v[64:79], v[100:103], v[112:115], v[64:79]
	ds_read_b128 v[100:103], v210 offset:32768
	s_waitcnt lgkmcnt(0)
	v_mfma_f32_32x32x16_bf16 v[64:79], v[100:103], v[116:119], v[64:79]
	ds_read_b128 v[100:103], v190 offset:32768
	s_waitcnt lgkmcnt(0)
	v_mfma_f32_32x32x16_bf16 v[64:79], v[100:103], v[120:123], v[64:79]
	ds_read_b128 v[100:103], v191 offset:32768
	s_waitcnt lgkmcnt(0)
	v_mfma_f32_32x32x16_bf16 v[64:79], v[100:103], v[124:127], v[64:79]
	ds_read_b128 v[100:103], v192 offset:32768
	s_waitcnt lgkmcnt(0)
	v_mfma_f32_32x32x16_bf16 v[64:79], v[100:103], v[130:133], v[64:79]
	ds_read_b128 v[100:103], v193 offset:32768
	s_waitcnt lgkmcnt(0)
	v_and_b32_e32 v190, 63, v195
	v_lshlrev_b32_e32 v191, 4, v195
	v_and_b32_e32 v192, 31, v195
	v_bfe_u32 v193, v195, 5, 1
	v_mfma_f32_32x32x16_bf16 v[64:79], v[100:103], v[134:137], v[64:79]
	v_mfma_f32_32x32x16_bf16 v[96:111], v[96:99], v[142:145], 0
	s_nop 10
	v_exp_f32_e32 v72, v80
	v_exp_f32_e32 v80, v81
	v_exp_f32_e32 v73, v82
	v_exp_f32_e32 v81, v83
	v_exp_f32_e32 v74, v84
	v_add_f32_e32 v84, 0, v72
	v_exp_f32_e32 v82, v85
	v_mfma_f32_32x32x16_bf16 v[96:111], v[170:173], v[138:141], v[96:111]
	v_add_f32_e32 v84, v80, v84
	v_exp_f32_e32 v75, v86
	v_add_f32_e32 v84, v73, v84
	v_exp_f32_e32 v83, v87
	v_add_f32_e32 v84, v81, v84
	v_exp_f32_e32 v76, v88
	v_add_f32_e32 v84, v74, v84
	v_mfma_f32_32x32x16_bf16 v[96:111], v[162:165], v[112:115], v[96:111]
	v_exp_f32_e32 v85, v89
	v_add_f32_e32 v84, v82, v84
	v_exp_f32_e32 v77, v90
	v_add_f32_e32 v84, v75, v84
	v_exp_f32_e32 v87, v91
	v_add_f32_e32 v84, v83, v84
	v_exp_f32_e32 v78, v92
	v_mfma_f32_32x32x16_bf16 v[96:111], v[166:169], v[116:119], v[96:111]
	v_add_f32_e32 v84, v76, v84
	v_exp_f32_e32 v89, v93
	v_add_f32_e32 v84, v85, v84
	v_exp_f32_e32 v79, v94
	v_add_f32_e32 v84, v77, v84
	v_exp_f32_e32 v90, v95
	v_add_f32_e32 v84, v87, v84
	v_mfma_f32_32x32x16_bf16 v[96:111], v[174:177], v[120:123], v[96:111]
	v_add_f32_e32 v84, v78, v84
	v_add_f32_e32 v84, v89, v84
	v_add_f32_e32 v84, v79, v84
	v_add_f32_e32 v84, v90, v84
	v_lshl_add_u32 v88, v247, 2, s2
	v_cvt_pk_bf16_f32 v72, v72, v80
	v_cvt_pk_bf16_f32 v73, v73, v81
	v_mfma_f32_32x32x16_bf16 v[96:111], v[178:181], v[124:127], v[96:111]
	v_cvt_pk_bf16_f32 v74, v74, v82
	v_cvt_pk_bf16_f32 v75, v75, v83
	v_cvt_pk_bf16_f32 v76, v76, v85
	v_cvt_pk_bf16_f32 v77, v77, v87
	v_cvt_pk_bf16_f32 v78, v78, v89
	v_cvt_pk_bf16_f32 v79, v79, v90
	s_nop 0
	v_permlane32_swap_b32_e32 v72, v74
	v_mfma_f32_32x32x16_bf16 v[96:111], v[182:185], v[130:133], v[96:111]
	v_permlane32_swap_b32_e32 v73, v75
	v_permlane32_swap_b32_e32 v76, v78
	v_permlane32_swap_b32_e32 v77, v79
	v_mfma_f32_32x32x16_bf16 v[96:111], v[186:189], v[134:137], v[96:111]
	s_nop 11
	v_exp_f32_e32 v91, v96
	v_exp_f32_e32 v92, v97
	v_exp_f32_e32 v93, v98
	v_exp_f32_e32 v94, v99
	v_exp_f32_e32 v95, v100
	v_add_f32_e32 v84, v84, v91
	v_exp_f32_e32 v96, v101
	v_add_f32_e32 v84, v92, v84
	v_exp_f32_e32 v97, v102
	v_add_f32_e32 v84, v93, v84
	v_exp_f32_e32 v98, v103
	v_add_f32_e32 v84, v94, v84
	v_exp_f32_e32 v99, v104
	v_add_f32_e32 v84, v95, v84
	v_exp_f32_e32 v100, v105
	v_add_f32_e32 v84, v96, v84
	v_exp_f32_e32 v101, v106
	v_add_f32_e32 v84, v97, v84
	v_exp_f32_e32 v102, v107
	v_add_f32_e32 v84, v98, v84
	v_exp_f32_e32 v103, v108
	v_add_f32_e32 v84, v99, v84
	v_exp_f32_e32 v104, v109
	v_add_f32_e32 v84, v100, v84
	v_exp_f32_e32 v105, v110
	v_add_f32_e32 v84, v101, v84
	v_exp_f32_e32 v106, v111
	v_add_f32_e32 v84, v102, v84
	v_add_f32_e32 v84, v103, v84
	v_add_f32_e32 v84, v104, v84
	v_add_f32_e32 v84, v105, v84
	v_add_f32_e32 v84, v106, v84
	v_mov_b32_e32 v86, v84
	s_nop 1
	v_permlane32_swap_b32_e32 v84, v86
	v_cvt_pk_bf16_f32 v80, v91, v92
	v_cvt_pk_bf16_f32 v81, v93, v94
	v_cvt_pk_bf16_f32 v82, v95, v96
	v_cvt_pk_bf16_f32 v83, v97, v98
	v_cvt_pk_bf16_f32 v90, v99, v100
	v_cvt_pk_bf16_f32 v91, v101, v102
	v_cvt_pk_bf16_f32 v92, v103, v104
	v_cvt_pk_bf16_f32 v93, v105, v106
	s_nop 0
	v_permlane32_swap_b32_e32 v80, v82
	v_permlane32_swap_b32_e32 v81, v83
	v_permlane32_swap_b32_e32 v90, v92
	v_permlane32_swap_b32_e32 v91, v93
	ds_read_b64_tr_b16 v[94:95], v206 offset:0x4000
	ds_read_b64_tr_b16 v[96:97], v206 offset:0x4800
	ds_read_b64_tr_b16 v[98:99], v206 offset:0x5000
	ds_read_b64_tr_b16 v[100:101], v206 offset:0x5800
	ds_read_b64_tr_b16 v[102:103], v206 offset:0x6000
	ds_read_b64_tr_b16 v[104:105], v206 offset:0x6800
	ds_read_b64_tr_b16 v[106:107], v206 offset:0x7000
	ds_read_b64_tr_b16 v[108:109], v206 offset:0x7800
	s_waitcnt lgkmcnt(0)
; #define SBAR() __builtin_amdgcn_sched_barrier(0)
; #define NOP_() do { } while (0)
; template <bool PARTIAL, bool FIXED> ...
;     ...
;   HALF_A(2, 1, do { if (mask_last) { asm volatile("; masked tail tile" ::: "memory"); const float NEG = -INFINITY; \
;       _Pragma("unroll") for (int r = 8; r < 16; ++r) pA0[r] = NEG; _Pragma("unroll") for (int r = 0; r < 16; ++r) pA1[r] = NEG; } } while (0), NOP_(), NOP_());
;     ...
;   SBAR(); finishSM(pA0, pA1, alA, l_reg, pa0, pa1, pa2, pa3); SBAR();
;   pv_i<2 * 16384>(o, vbi, pa0, pa1, pa2, pa3);
;     ...
;   if (hi == 0) li_l[r32] = l_reg; asm volatile("s_waitcnt lgkmcnt(0)" ::: "memory");
	s_nop 0
	v_mfma_f32_32x32x16_bf16 v[0:15], v[72:75], v[94:97], v[0:15]
	ds_read_b64_tr_b16 v[94:95], v206 offset:0x4200
	ds_read_b64_tr_b16 v[96:97], v206 offset:0x4a00
	v_mfma_f32_32x32x16_bf16 v[0:15], v[76:79], v[98:101], v[0:15]
	ds_read_b64_tr_b16 v[98:99], v206 offset:0x5200
	ds_read_b64_tr_b16 v[100:101], v206 offset:0x5a00
	v_mfma_f32_32x32x16_bf16 v[0:15], v[80:83], v[102:105], v[0:15]
	ds_read_b64_tr_b16 v[102:103], v206 offset:0x6200
	ds_read_b64_tr_b16 v[104:105], v206 offset:0x6a00
	v_mfma_f32_32x32x16_bf16 v[0:15], v[90:93], v[106:109], v[0:15]
	ds_read_b64_tr_b16 v[106:107], v206 offset:0x7200
	ds_read_b64_tr_b16 v[108:109], v206 offset:0x7a00
	s_waitcnt lgkmcnt(0)
	v_mfma_f32_32x32x16_bf16 v[16:31], v[72:75], v[94:97], v[16:31]
	ds_read_b64_tr_b16 v[94:95], v206 offset:0x4400
	ds_read_b64_tr_b16 v[96:97], v206 offset:0x4c00
	v_mfma_f32_32x32x16_bf16 v[16:31], v[76:79], v[98:101], v[16:31]
	ds_read_b64_tr_b16 v[98:99], v206 offset:0x5400
	ds_read_b64_tr_b16 v[100:101], v206 offset:0x5c00
	v_mfma_f32_32x32x16_bf16 v[16:31], v[80:83], v[102:105], v[16:31]
	ds_read_b64_tr_b16 v[102:103], v206 offset:0x6400
	ds_read_b64_tr_b16 v[104:105], v206 offset:0x6c00
	v_mfma_f32_32x32x16_bf16 v[16:31], v[90:93], v[106:109], v[16:31]
	ds_read_b64_tr_b16 v[106:107], v206 offset:0x7400
	ds_read_b64_tr_b16 v[108:109], v206 offset:0x7c00
	s_waitcnt lgkmcnt(0)
	v_mfma_f32_32x32x16_bf16 v[32:47], v[72:75], v[94:97], v[32:47]
	ds_read_b64_tr_b16 v[94:95], v206 offset:0x4600
	ds_read_b64_tr_b16 v[96:97], v206 offset:0x4e00
	v_mfma_f32_32x32x16_bf16 v[32:47], v[76:79], v[98:101], v[32:47]
	ds_read_b64_tr_b16 v[98:99], v206 offset:0x5600
	ds_read_b64_tr_b16 v[100:101], v206 offset:0x5e00
	v_mfma_f32_32x32x16_bf16 v[32:47], v[80:83], v[102:105], v[32:47]
	ds_read_b64_tr_b16 v[102:103], v206 offset:0x6600
	ds_read_b64_tr_b16 v[104:105], v206 offset:0x6e00
	v_mfma_f32_32x32x16_bf16 v[32:47], v[90:93], v[106:109], v[32:47]
	ds_read_b64_tr_b16 v[106:107], v206 offset:0x7600
	ds_read_b64_tr_b16 v[108:109], v206 offset:0x7e00
	s_waitcnt lgkmcnt(0)
	v_mfma_f32_32x32x16_bf16 v[48:63], v[72:75], v[94:97], v[48:63]
	v_exp_f32_e32 v64, v64
	v_exp_f32_e32 v65, v65
	v_exp_f32_e32 v66, v66
	v_exp_f32_e32 v67, v67
	v_exp_f32_e32 v68, v68
	v_exp_f32_e32 v69, v69
	v_exp_f32_e32 v70, v70
	v_mfma_f32_32x32x16_bf16 v[48:63], v[76:79], v[98:101], v[48:63]
	v_exp_f32_e32 v71, v71
	v_mfma_f32_32x32x16_bf16 v[48:63], v[80:83], v[102:105], v[48:63]
	v_mfma_f32_32x32x16_bf16 v[48:63], v[90:93], v[106:109], v[48:63]
	v_add_f32_e32 v72, 0, v64
	v_add_f32_e32 v72, v65, v72
	v_add_f32_e32 v72, v66, v72
	v_add_f32_e32 v72, v67, v72
	v_add_f32_e32 v72, v68, v72
	v_add_f32_e32 v72, v69, v72
	v_add_f32_e32 v72, v70, v72
	v_add_f32_e32 v72, v71, v72
	v_add_f32_e32 v85, 0, v72
	v_mov_b32_e32 v87, v85
	s_nop 1
	v_permlane32_swap_b32_e32 v85, v87
	v_cvt_pk_bf16_f32 v64, v64, v65
	v_cvt_pk_bf16_f32 v65, v66, v67
	v_cvt_pk_bf16_f32 v66, v68, v69
	v_cvt_pk_bf16_f32 v67, v70, v71
	v_cvt_pk_bf16_f32 v68, v129, v129
	v_cvt_pk_bf16_f32 v69, v129, v129
	v_cvt_pk_bf16_f32 v70, v129, v129
	v_cvt_pk_bf16_f32 v71, v129, v129
	v_cvt_pk_bf16_f32 v72, v129, v129
	v_cvt_pk_bf16_f32 v73, v129, v129
	v_cvt_pk_bf16_f32 v74, v129, v129
	v_cvt_pk_bf16_f32 v75, v129, v129
	v_cvt_pk_bf16_f32 v76, v129, v129
	v_cvt_pk_bf16_f32 v77, v129, v129
	v_cvt_pk_bf16_f32 v78, v129, v129
	v_cvt_pk_bf16_f32 v79, v129, v129
	s_nop 0
	v_permlane32_swap_b32_e32 v64, v66
	v_permlane32_swap_b32_e32 v65, v67
	v_permlane32_swap_b32_e32 v68, v70
	v_permlane32_swap_b32_e32 v69, v71
	v_permlane32_swap_b32_e32 v72, v74
	v_permlane32_swap_b32_e32 v73, v75
	v_permlane32_swap_b32_e32 v76, v78
	v_permlane32_swap_b32_e32 v77, v79
	ds_read_b64_tr_b16 v[80:81], v206 offset:0x8000
	ds_read_b64_tr_b16 v[82:83], v206 offset:0x8800
	ds_read_b64_tr_b16 v[90:91], v206 offset:0x9000
	ds_read_b64_tr_b16 v[92:93], v206 offset:0x9800
	ds_read_b64_tr_b16 v[94:95], v206 offset:0xa000
	ds_read_b64_tr_b16 v[96:97], v206 offset:0xa800
	ds_read_b64_tr_b16 v[98:99], v206 offset:0xb000
	ds_read_b64_tr_b16 v[100:101], v206 offset:0xb800
	s_waitcnt lgkmcnt(0)
	s_nop 0
	v_mfma_f32_32x32x16_bf16 v[0:15], v[64:67], v[80:83], v[0:15]
	ds_read_b64_tr_b16 v[80:81], v206 offset:0x8200
	ds_read_b64_tr_b16 v[82:83], v206 offset:0x8a00
	v_mfma_f32_32x32x16_bf16 v[0:15], v[68:71], v[90:93], v[0:15]
	ds_read_b64_tr_b16 v[90:91], v206 offset:0x9200
	ds_read_b64_tr_b16 v[92:93], v206 offset:0x9a00
	v_mfma_f32_32x32x16_bf16 v[0:15], v[72:75], v[94:97], v[0:15]
	ds_read_b64_tr_b16 v[94:95], v206 offset:0xa200
	ds_read_b64_tr_b16 v[96:97], v206 offset:0xaa00
	v_mfma_f32_32x32x16_bf16 v[0:15], v[76:79], v[98:101], v[0:15]
	ds_read_b64_tr_b16 v[98:99], v206 offset:0xb200
	ds_read_b64_tr_b16 v[100:101], v206 offset:0xba00
	s_waitcnt lgkmcnt(0)
	v_mfma_f32_32x32x16_bf16 v[16:31], v[64:67], v[80:83], v[16:31]
	ds_read_b64_tr_b16 v[80:81], v206 offset:0x8400
	ds_read_b64_tr_b16 v[82:83], v206 offset:0x8c00
	v_mfma_f32_32x32x16_bf16 v[16:31], v[68:71], v[90:93], v[16:31]
	ds_read_b64_tr_b16 v[90:91], v206 offset:0x9400
	ds_read_b64_tr_b16 v[92:93], v206 offset:0x9c00
	v_mfma_f32_32x32x16_bf16 v[16:31], v[72:75], v[94:97], v[16:31]
	ds_read_b64_tr_b16 v[94:95], v206 offset:0xa400
	ds_read_b64_tr_b16 v[96:97], v206 offset:0xac00
	v_mfma_f32_32x32x16_bf16 v[16:31], v[76:79], v[98:101], v[16:31]
	ds_read_b64_tr_b16 v[98:99], v206 offset:0xb400
	ds_read_b64_tr_b16 v[100:101], v206 offset:0xbc00
	s_waitcnt lgkmcnt(0)
	v_mfma_f32_32x32x16_bf16 v[32:47], v[64:67], v[80:83], v[32:47]
	ds_read_b64_tr_b16 v[80:81], v206 offset:0x8600
	ds_read_b64_tr_b16 v[82:83], v206 offset:0x8e00
	v_mfma_f32_32x32x16_bf16 v[32:47], v[68:71], v[90:93], v[32:47]
	ds_read_b64_tr_b16 v[90:91], v206 offset:0x9600
	ds_read_b64_tr_b16 v[92:93], v206 offset:0x9e00
	v_mfma_f32_32x32x16_bf16 v[32:47], v[72:75], v[94:97], v[32:47]
	ds_read_b64_tr_b16 v[94:95], v206 offset:0xa600
	ds_read_b64_tr_b16 v[96:97], v206 offset:0xae00
	v_mfma_f32_32x32x16_bf16 v[32:47], v[76:79], v[98:101], v[32:47]
	ds_read_b64_tr_b16 v[98:99], v206 offset:0xb600
	ds_read_b64_tr_b16 v[100:101], v206 offset:0xbe00
	s_waitcnt lgkmcnt(0)
	v_mfma_f32_32x32x16_bf16 v[48:63], v[64:67], v[80:83], v[48:63]
	v_cmp_gt_u32_e32 vcc, 32, v190
	v_mfma_f32_32x32x16_bf16 v[48:63], v[68:71], v[90:93], v[48:63]
	v_mfma_f32_32x32x16_bf16 v[48:63], v[72:75], v[94:97], v[48:63]
	v_mfma_f32_32x32x16_bf16 v[48:63], v[76:79], v[98:101], v[48:63]
	s_and_saveexec_b64 s[28:29], vcc
	s_cbranch_execz .LBB0_309
	v_add_f32_e32 v64, v128, v218
	v_add_f32_e32 v66, v215, v64
	v_pk_add_f32 v[64:65], v[84:85], v[86:87]
	v_lshl_add_u32 v67, v192, 2, v88
	v_add_f32_e32 v64, v66, v64
	v_add_f32_e32 v64, v64, v65
	ds_write_b32 v67, v64
	s_branch .LBB0_309

; __device__ __forceinline__ unsigned cvt_pk(float lo, float hi) { unsigned r; asm volatile("v_cvt_pk_bf16_f32 %0, %1, %2" : "=v"(r) : "v"(lo), "v"(hi)); return r; }
;     __device__ __forceinline__ void operator()(const f32x4 (&acc)[2][2][4][2], const pg8::Unit& u, int wr, int wc, int fr, int fq) const {
;     ...
;             for (int m = 0; m < 4; ++m) { bf16raw* rowp = base + (size_t)(row0 + ai * 128 + m * 16) * DM + col0; const float sc = rs[row0 + ai * 128 + m * 16];
; #pragma unroll
;                 for (int bj = 0; bj < 2; ++bj) { f32x4 v0 = acc[ai][bj][m][0] * sc, v1 = acc[ai][bj][m][1] * sc;
;                     if (isy) {
; #pragma unroll
;                         for (int i = 0; i < 4; ++i) { v0[i] = gelu_tanh(v0[i]); v1[i] = gelu_tanh(v1[i]); } }
;                     u32x4 w; w.x = cvt_pk(v0[0], v0[1]); w.y = cvt_pk(v0[2], v0[3]); w.z = cvt_pk(v1[0], v1[1]); w.w = cvt_pk(v1[2], v1[3]);
.LBB0_506:
	v_add_u32_e32 v130, s34, v195
	v_ashrrev_i32_e32 v131, 31, v130
	v_lshl_add_u64 v[132:133], v[130:131], 2, s[52:53]
	global_load_dword v134, v[132:133], off
	global_load_dword v146, v[132:133], off offset:64
	global_load_dword v147, v[132:133], off offset:128
	global_load_dword v148, v[132:133], off offset:192
	global_load_dword v149, v[132:133], off offset:512
	global_load_dword v150, v[132:133], off offset:576
	global_load_dword v151, v[132:133], off offset:640
	global_load_dword v152, v[132:133], off offset:704
	s_cmp_lt_i32 s76, 4
	v_readlane_b32 s88, v255, 27
	s_cselect_b64 s[28:29], -1, 0
	s_cmp_gt_i32 s76, 3
	v_readlane_b32 s89, v255, 28
	s_waitcnt vmcnt(7)
	v_pk_mul_f32 v[126:127], v[126:127], v[134:135] op_sel_hi:[1,0]
	v_pk_mul_f32 v[136:137], v[124:125], v[134:135] op_sel_hi:[1,0]
	v_pk_mul_f32 v[124:125], v[122:123], v[134:135] op_sel_hi:[1,0]
	v_pk_mul_f32 v[138:139], v[120:121], v[134:135] op_sel_hi:[1,0]
	s_cbranch_scc1 .LBB0_508
	v_mul_f32_e32 v121, 0x3d372713, v138
	v_fma_f32 v121, v138, v121, 1.0
	v_mul_f32_e32 v121, v138, v121
	v_mul_f32_e32 v121, 0x3fcc422a, v121
	v_mul_f32_e32 v121, 0xbfb8aa3b, v121
	v_mul_f32_e32 v128, 0x3d372713, v126
	v_exp_f32_e32 v121, v121
	v_fma_f32 v128, v126, v128, 1.0
	v_mul_f32_e32 v128, v126, v128
	v_mul_f32_e32 v128, 0x3fcc422a, v128
	v_mul_f32_e32 v128, 0xbfb8aa3b, v128
	v_add_f32_e32 v121, 1.0, v121
	v_exp_f32_e32 v128, v128
	v_mul_f32_e32 v120, 0x3d372713, v136
	v_rcp_f32_e32 v122, v121
	v_mul_f32_e32 v121, 0x3d372713, v137
	v_fma_f32 v120, v136, v120, 1.0
	v_fma_f32 v121, v137, v121, 1.0
	v_mul_f32_e32 v120, v136, v120
	v_mul_f32_e32 v121, v137, v121
	v_mul_f32_e32 v120, 0x3fcc422a, v120
	v_mul_f32_e32 v121, 0x3fcc422a, v121
	v_add_f32_e32 v128, 1.0, v128
	v_mul_f32_e32 v120, 0xbfb8aa3b, v120
	v_mul_f32_e32 v121, 0xbfb8aa3b, v121
	v_rcp_f32_e32 v140, v128
	v_mul_f32_e32 v128, 0x3d372713, v124
	v_exp_f32_e32 v120, v120
	v_exp_f32_e32 v121, v121
	v_fma_f32 v128, v124, v128, 1.0
	v_mul_f32_e32 v128, v124, v128
	v_mul_f32_e32 v128, 0x3fcc422a, v128
	v_mul_f32_e32 v128, 0xbfb8aa3b, v128
	v_add_f32_e32 v120, 1.0, v120
	v_add_f32_e32 v121, 1.0, v121
	v_exp_f32_e32 v128, v128
	v_rcp_f32_e32 v120, v120
	v_rcp_f32_e32 v121, v121
	v_mul_f32_e32 v123, 0x3d372713, v139
	v_add_f32_e32 v128, 1.0, v128
	v_rcp_f32_e32 v142, v128
	v_mul_f32_e32 v128, 0x3d372713, v127
	v_pk_mul_f32 v[136:137], v[136:137], v[120:121]
	v_mul_f32_e32 v120, 0x3d372713, v125
	v_fma_f32 v123, v139, v123, 1.0
	v_fma_f32 v128, v127, v128, 1.0
	v_fma_f32 v120, v125, v120, 1.0
	v_mul_f32_e32 v123, v139, v123
	v_mul_f32_e32 v128, v127, v128
	v_mul_f32_e32 v120, v125, v120
	v_mul_f32_e32 v123, 0x3fcc422a, v123
	v_mul_f32_e32 v128, 0x3fcc422a, v128
	v_mul_f32_e32 v120, 0x3fcc422a, v120
	v_mul_f32_e32 v123, 0xbfb8aa3b, v123
	v_mul_f32_e32 v128, 0xbfb8aa3b, v128
	v_mul_f32_e32 v120, 0xbfb8aa3b, v120
	v_exp_f32_e32 v123, v123
	v_exp_f32_e32 v128, v128
	v_exp_f32_e32 v120, v120
	v_add_f32_e32 v123, 1.0, v123
	v_add_f32_e32 v128, 1.0, v128
	v_add_f32_e32 v120, 1.0, v120
	v_rcp_f32_e32 v123, v123
	v_rcp_f32_e32 v141, v128
	v_rcp_f32_e32 v143, v120
	v_pk_mul_f32 v[138:139], v[138:139], v[122:123]
	v_pk_mul_f32 v[126:127], v[126:127], v[140:141]
	v_pk_mul_f32 v[124:125], v[124:125], v[142:143]

; __device__ __forceinline__ unsigned cvt_pk(float lo, float hi) { unsigned r; asm volatile("v_cvt_pk_bf16_f32 %0, %1, %2" : "=v"(r) : "v"(lo), "v"(hi)); return r; }
;     __device__ __forceinline__ void operator()(const f32x4 (&acc)[2][2][4][2], const pg8::Unit& u, int wr, int wc, int fr, int fq) const {
;     ...
;             for (int m = 0; m < 4; ++m) { bf16raw* rowp = base + (size_t)(row0 + ai * 128 + m * 16) * DM + col0; const float sc = rs[row0 + ai * 128 + m * 16];
; #pragma unroll
;                 for (int bj = 0; bj < 2; ++bj) { f32x4 v0 = acc[ai][bj][m][0] * sc, v1 = acc[ai][bj][m][1] * sc;
;                     if (isy) {
; #pragma unroll
;                         for (int i = 0; i < 4; ++i) { v0[i] = gelu_tanh(v0[i]); v1[i] = gelu_tanh(v1[i]); } }
;                     u32x4 w; w.x = cvt_pk(v0[0], v0[1]); w.y = cvt_pk(v0[2], v0[3]); w.z = cvt_pk(v1[0], v1[1]); w.w = cvt_pk(v1[2], v1[3]);
;                     *(u32x4*)(rowp + bj * 128) = w; } }
.LBB0_510:
	v_cvt_pk_bf16_f32 v116, v116, v117
	v_cvt_pk_bf16_f32 v117, v118, v119
	v_cvt_pk_bf16_f32 v118, v112, v113
	s_nop 0
	v_cvt_pk_bf16_f32 v119, v114, v115
	global_store_dwordx4 v[122:123], v[116:119], off offset:256
	s_and_b64 vcc, exec, s[38:39]
	s_waitcnt vmcnt(8)
	v_mov_b32_e32 v112, v146
	v_pk_mul_f32 v[110:111], v[110:111], v[112:113] op_sel_hi:[1,0]
	v_pk_mul_f32 v[114:115], v[108:109], v[112:113] op_sel_hi:[1,0]
	v_pk_mul_f32 v[106:107], v[106:107], v[112:113] op_sel_hi:[1,0]
	v_pk_mul_f32 v[108:109], v[104:105], v[112:113] op_sel_hi:[1,0]
	s_cbranch_vccnz .LBB0_512
	v_mul_f32_e32 v113, 0x3d372713, v109
	v_fma_f32 v113, v109, v113, 1.0
	v_mul_f32_e32 v113, v109, v113
	v_mul_f32_e32 v113, 0x3fcc422a, v113
	v_mul_f32_e32 v113, 0xbfb8aa3b, v113
	v_exp_f32_e32 v113, v113
	v_mul_f32_e32 v105, 0x3d372713, v108
	v_fma_f32 v105, v108, v105, 1.0
	v_mul_f32_e32 v105, v108, v105
	v_mul_f32_e32 v105, 0x3fcc422a, v105
	v_add_f32_e32 v113, 1.0, v113
	v_mul_f32_e32 v105, 0xbfb8aa3b, v105
	v_rcp_f32_e32 v117, v113
	v_mul_f32_e32 v113, 0x3d372713, v110
	v_exp_f32_e32 v105, v105
	v_fma_f32 v113, v110, v113, 1.0
	v_mul_f32_e32 v113, v110, v113
	v_mul_f32_e32 v113, 0x3fcc422a, v113
	v_mul_f32_e32 v113, 0xbfb8aa3b, v113
	v_add_f32_e32 v105, 1.0, v105
	v_exp_f32_e32 v113, v113
	v_mul_f32_e32 v104, 0x3d372713, v114
	v_rcp_f32_e32 v116, v105
	v_mul_f32_e32 v105, 0x3d372713, v115
	v_fma_f32 v104, v114, v104, 1.0
	v_fma_f32 v105, v115, v105, 1.0
	v_mul_f32_e32 v104, v114, v104
	v_mul_f32_e32 v105, v115, v105
	v_mul_f32_e32 v104, 0x3fcc422a, v104
	v_mul_f32_e32 v105, 0x3fcc422a, v105
	v_add_f32_e32 v113, 1.0, v113
	v_mul_f32_e32 v104, 0xbfb8aa3b, v104
	v_mul_f32_e32 v105, 0xbfb8aa3b, v105
	v_rcp_f32_e32 v118, v113
	v_mul_f32_e32 v113, 0x3d372713, v106
	v_exp_f32_e32 v104, v104
	v_exp_f32_e32 v105, v105
	v_fma_f32 v113, v106, v113, 1.0
	v_mul_f32_e32 v113, v106, v113
	v_mul_f32_e32 v113, 0x3fcc422a, v113
	v_mul_f32_e32 v113, 0xbfb8aa3b, v113
	v_add_f32_e32 v104, 1.0, v104
	v_add_f32_e32 v105, 1.0, v105
	v_exp_f32_e32 v113, v113
	v_rcp_f32_e32 v104, v104
	v_rcp_f32_e32 v105, v105
	v_pk_mul_f32 v[108:109], v[108:109], v[116:117]
	v_add_f32_e32 v113, 1.0, v113
	v_rcp_f32_e32 v122, v113
	v_mul_f32_e32 v113, 0x3d372713, v111
	v_pk_mul_f32 v[114:115], v[114:115], v[104:105]
	v_mul_f32_e32 v104, 0x3d372713, v107
	v_fma_f32 v113, v111, v113, 1.0
	v_fma_f32 v104, v107, v104, 1.0
	v_mul_f32_e32 v113, v111, v113
	v_mul_f32_e32 v104, v107, v104
	v_mul_f32_e32 v113, 0x3fcc422a, v113
	v_mul_f32_e32 v104, 0x3fcc422a, v104
	v_mul_f32_e32 v113, 0xbfb8aa3b, v113
	v_mul_f32_e32 v104, 0xbfb8aa3b, v104
	v_exp_f32_e32 v113, v113
	v_exp_f32_e32 v104, v104
	v_add_f32_e32 v113, 1.0, v113
	v_add_f32_e32 v104, 1.0, v104
	v_rcp_f32_e32 v119, v113
	v_rcp_f32_e32 v123, v104
	v_pk_mul_f32 v[110:111], v[110:111], v[118:119]
	v_pk_mul_f32 v[106:107], v[106:107], v[122:123]

; __device__ __forceinline__ unsigned cvt_pk(float lo, float hi) { unsigned r; asm volatile("v_cvt_pk_bf16_f32 %0, %1, %2" : "=v"(r) : "v"(lo), "v"(hi)); return r; }
;     __device__ __forceinline__ void operator()(const f32x4 (&acc)[2][2][4][2], const pg8::Unit& u, int wr, int wc, int fr, int fq) const {
;     ...
;             for (int m = 0; m < 4; ++m) { bf16raw* rowp = base + (size_t)(row0 + ai * 128 + m * 16) * DM + col0; const float sc = rs[row0 + ai * 128 + m * 16];
; #pragma unroll
;                 for (int bj = 0; bj < 2; ++bj) { f32x4 v0 = acc[ai][bj][m][0] * sc, v1 = acc[ai][bj][m][1] * sc;
;                     if (isy) {
; #pragma unroll
;                         for (int i = 0; i < 4; ++i) { v0[i] = gelu_tanh(v0[i]); v1[i] = gelu_tanh(v1[i]); } }
;                     u32x4 w; w.x = cvt_pk(v0[0], v0[1]); w.y = cvt_pk(v0[2], v0[3]); w.z = cvt_pk(v1[0], v1[1]); w.w = cvt_pk(v1[2], v1[3]);
;                     *(u32x4*)(rowp + bj * 128) = w; } }
.LBB0_514:
	v_cvt_pk_bf16_f32 v100, v100, v101
	v_cvt_pk_bf16_f32 v101, v102, v103
	v_cvt_pk_bf16_f32 v102, v96, v97
	s_nop 0
	v_cvt_pk_bf16_f32 v103, v98, v99
	global_store_dwordx4 v[104:105], v[100:103], off offset:256
	s_and_b64 vcc, exec, s[38:39]
	s_waitcnt vmcnt(9)
	v_mov_b32_e32 v96, v147
	v_pk_mul_f32 v[94:95], v[94:95], v[96:97] op_sel_hi:[1,0]
	v_pk_mul_f32 v[98:99], v[92:93], v[96:97] op_sel_hi:[1,0]
	v_pk_mul_f32 v[90:91], v[90:91], v[96:97] op_sel_hi:[1,0]
	v_pk_mul_f32 v[92:93], v[88:89], v[96:97] op_sel_hi:[1,0]
	s_cbranch_vccnz .LBB0_516
	v_mul_f32_e32 v97, 0x3d372713, v93
	v_fma_f32 v97, v93, v97, 1.0
	v_mul_f32_e32 v97, v93, v97
	v_mul_f32_e32 v97, 0x3fcc422a, v97
	v_mul_f32_e32 v97, 0xbfb8aa3b, v97
	v_exp_f32_e32 v97, v97
	v_mul_f32_e32 v89, 0x3d372713, v92
	v_fma_f32 v89, v92, v89, 1.0
	v_mul_f32_e32 v89, v92, v89
	v_mul_f32_e32 v89, 0x3fcc422a, v89
	v_add_f32_e32 v97, 1.0, v97
	v_mul_f32_e32 v89, 0xbfb8aa3b, v89
	v_rcp_f32_e32 v101, v97
	v_mul_f32_e32 v97, 0x3d372713, v94
	v_exp_f32_e32 v89, v89
	v_fma_f32 v97, v94, v97, 1.0
	v_mul_f32_e32 v97, v94, v97
	v_mul_f32_e32 v97, 0x3fcc422a, v97
	v_mul_f32_e32 v97, 0xbfb8aa3b, v97
	v_add_f32_e32 v89, 1.0, v89
	v_exp_f32_e32 v97, v97
	v_mul_f32_e32 v88, 0x3d372713, v98
	v_rcp_f32_e32 v100, v89
	v_mul_f32_e32 v89, 0x3d372713, v99
	v_fma_f32 v88, v98, v88, 1.0
	v_fma_f32 v89, v99, v89, 1.0
	v_mul_f32_e32 v88, v98, v88
	v_mul_f32_e32 v89, v99, v89
	v_mul_f32_e32 v88, 0x3fcc422a, v88
	v_mul_f32_e32 v89, 0x3fcc422a, v89
	v_add_f32_e32 v97, 1.0, v97
	v_mul_f32_e32 v88, 0xbfb8aa3b, v88
	v_mul_f32_e32 v89, 0xbfb8aa3b, v89
	v_rcp_f32_e32 v102, v97
	v_mul_f32_e32 v97, 0x3d372713, v90
	v_exp_f32_e32 v88, v88
	v_exp_f32_e32 v89, v89
	v_fma_f32 v97, v90, v97, 1.0
	v_mul_f32_e32 v97, v90, v97
	v_mul_f32_e32 v97, 0x3fcc422a, v97
	v_mul_f32_e32 v97, 0xbfb8aa3b, v97
	v_add_f32_e32 v88, 1.0, v88
	v_add_f32_e32 v89, 1.0, v89
	v_exp_f32_e32 v97, v97
	v_rcp_f32_e32 v88, v88
	v_rcp_f32_e32 v89, v89
	v_pk_mul_f32 v[92:93], v[92:93], v[100:101]
	v_add_f32_e32 v97, 1.0, v97
	v_rcp_f32_e32 v104, v97
	v_mul_f32_e32 v97, 0x3d372713, v95
	v_pk_mul_f32 v[98:99], v[98:99], v[88:89]
	v_mul_f32_e32 v88, 0x3d372713, v91
	v_fma_f32 v97, v95, v97, 1.0
	v_fma_f32 v88, v91, v88, 1.0
	v_mul_f32_e32 v97, v95, v97
	v_mul_f32_e32 v88, v91, v88
	v_mul_f32_e32 v97, 0x3fcc422a, v97
	v_mul_f32_e32 v88, 0x3fcc422a, v88
	v_mul_f32_e32 v97, 0xbfb8aa3b, v97
	v_mul_f32_e32 v88, 0xbfb8aa3b, v88
	v_exp_f32_e32 v97, v97
	v_exp_f32_e32 v88, v88
	v_add_f32_e32 v97, 1.0, v97
	v_add_f32_e32 v88, 1.0, v88
	v_rcp_f32_e32 v103, v97
	v_rcp_f32_e32 v105, v88
	v_pk_mul_f32 v[94:95], v[94:95], v[102:103]
	v_pk_mul_f32 v[90:91], v[90:91], v[104:105]

; __device__ __forceinline__ unsigned cvt_pk(float lo, float hi) { unsigned r; asm volatile("v_cvt_pk_bf16_f32 %0, %1, %2" : "=v"(r) : "v"(lo), "v"(hi)); return r; }
;     __device__ __forceinline__ void operator()(const f32x4 (&acc)[2][2][4][2], const pg8::Unit& u, int wr, int wc, int fr, int fq) const {
;     ...
;             for (int m = 0; m < 4; ++m) { bf16raw* rowp = base + (size_t)(row0 + ai * 128 + m * 16) * DM + col0; const float sc = rs[row0 + ai * 128 + m * 16];
; #pragma unroll
;                 for (int bj = 0; bj < 2; ++bj) { f32x4 v0 = acc[ai][bj][m][0] * sc, v1 = acc[ai][bj][m][1] * sc;
;                     if (isy) {
; #pragma unroll
;                         for (int i = 0; i < 4; ++i) { v0[i] = gelu_tanh(v0[i]); v1[i] = gelu_tanh(v1[i]); } }
;                     u32x4 w; w.x = cvt_pk(v0[0], v0[1]); w.y = cvt_pk(v0[2], v0[3]); w.z = cvt_pk(v1[0], v1[1]); w.w = cvt_pk(v1[2], v1[3]);
;                     *(u32x4*)(rowp + bj * 128) = w; } }
.LBB0_518:
	v_cvt_pk_bf16_f32 v84, v84, v85
	v_cvt_pk_bf16_f32 v85, v86, v87
	v_cvt_pk_bf16_f32 v86, v80, v81
	s_nop 0
	v_cvt_pk_bf16_f32 v87, v82, v83
	global_store_dwordx4 v[88:89], v[84:87], off offset:256
	s_and_b64 vcc, exec, s[38:39]
	s_waitcnt vmcnt(10)
	v_mov_b32_e32 v80, v148
	v_pk_mul_f32 v[78:79], v[78:79], v[80:81] op_sel_hi:[1,0]
	v_pk_mul_f32 v[82:83], v[76:77], v[80:81] op_sel_hi:[1,0]
	v_pk_mul_f32 v[74:75], v[74:75], v[80:81] op_sel_hi:[1,0]
	v_pk_mul_f32 v[76:77], v[72:73], v[80:81] op_sel_hi:[1,0]
	s_cbranch_vccnz .LBB0_520
	v_mul_f32_e32 v81, 0x3d372713, v77
	v_fma_f32 v81, v77, v81, 1.0
	v_mul_f32_e32 v81, v77, v81
	v_mul_f32_e32 v81, 0x3fcc422a, v81
	v_mul_f32_e32 v81, 0xbfb8aa3b, v81
	v_exp_f32_e32 v81, v81
	v_mul_f32_e32 v73, 0x3d372713, v76
	v_fma_f32 v73, v76, v73, 1.0
	v_mul_f32_e32 v73, v76, v73
	v_mul_f32_e32 v73, 0x3fcc422a, v73
	v_add_f32_e32 v81, 1.0, v81
	v_mul_f32_e32 v73, 0xbfb8aa3b, v73
	v_rcp_f32_e32 v85, v81
	v_mul_f32_e32 v81, 0x3d372713, v78
	v_exp_f32_e32 v73, v73
	v_fma_f32 v81, v78, v81, 1.0
	v_mul_f32_e32 v81, v78, v81
	v_mul_f32_e32 v81, 0x3fcc422a, v81
	v_mul_f32_e32 v81, 0xbfb8aa3b, v81
	v_add_f32_e32 v73, 1.0, v73
	v_exp_f32_e32 v81, v81
	v_mul_f32_e32 v72, 0x3d372713, v82
	v_rcp_f32_e32 v84, v73
	v_mul_f32_e32 v73, 0x3d372713, v83
	v_fma_f32 v72, v82, v72, 1.0
	v_fma_f32 v73, v83, v73, 1.0
	v_mul_f32_e32 v72, v82, v72
	v_mul_f32_e32 v73, v83, v73
	v_mul_f32_e32 v72, 0x3fcc422a, v72
	v_mul_f32_e32 v73, 0x3fcc422a, v73
	v_add_f32_e32 v81, 1.0, v81
	v_mul_f32_e32 v72, 0xbfb8aa3b, v72
	v_mul_f32_e32 v73, 0xbfb8aa3b, v73
	v_rcp_f32_e32 v86, v81
	v_mul_f32_e32 v81, 0x3d372713, v74
	v_exp_f32_e32 v72, v72
	v_exp_f32_e32 v73, v73
	v_fma_f32 v81, v74, v81, 1.0
	v_mul_f32_e32 v81, v74, v81
	v_mul_f32_e32 v81, 0x3fcc422a, v81
	v_mul_f32_e32 v81, 0xbfb8aa3b, v81
	v_add_f32_e32 v72, 1.0, v72
	v_add_f32_e32 v73, 1.0, v73
	v_exp_f32_e32 v81, v81
	v_rcp_f32_e32 v72, v72
	v_rcp_f32_e32 v73, v73
	v_pk_mul_f32 v[76:77], v[76:77], v[84:85]
	v_add_f32_e32 v81, 1.0, v81
	v_rcp_f32_e32 v88, v81
	v_mul_f32_e32 v81, 0x3d372713, v79
	v_pk_mul_f32 v[82:83], v[82:83], v[72:73]
	v_mul_f32_e32 v72, 0x3d372713, v75
	v_fma_f32 v81, v79, v81, 1.0
	v_fma_f32 v72, v75, v72, 1.0
	v_mul_f32_e32 v81, v79, v81
	v_mul_f32_e32 v72, v75, v72
	v_mul_f32_e32 v81, 0x3fcc422a, v81
	v_mul_f32_e32 v72, 0x3fcc422a, v72
	v_mul_f32_e32 v81, 0xbfb8aa3b, v81
	v_mul_f32_e32 v72, 0xbfb8aa3b, v72
	v_exp_f32_e32 v81, v81
	v_exp_f32_e32 v72, v72
	v_add_f32_e32 v81, 1.0, v81
	v_add_f32_e32 v72, 1.0, v72
	v_rcp_f32_e32 v87, v81
	v_rcp_f32_e32 v89, v72
	v_pk_mul_f32 v[78:79], v[78:79], v[86:87]
	v_pk_mul_f32 v[74:75], v[74:75], v[88:89]

; __device__ __forceinline__ unsigned cvt_pk(float lo, float hi) { unsigned r; asm volatile("v_cvt_pk_bf16_f32 %0, %1, %2" : "=v"(r) : "v"(lo), "v"(hi)); return r; }
;     __device__ __forceinline__ void operator()(const f32x4 (&acc)[2][2][4][2], const pg8::Unit& u, int wr, int wc, int fr, int fq) const {
;     ...
;             for (int m = 0; m < 4; ++m) { bf16raw* rowp = base + (size_t)(row0 + ai * 128 + m * 16) * DM + col0; const float sc = rs[row0 + ai * 128 + m * 16];
; #pragma unroll
;                 for (int bj = 0; bj < 2; ++bj) { f32x4 v0 = acc[ai][bj][m][0] * sc, v1 = acc[ai][bj][m][1] * sc;
;                     if (isy) {
; #pragma unroll
;                         for (int i = 0; i < 4; ++i) { v0[i] = gelu_tanh(v0[i]); v1[i] = gelu_tanh(v1[i]); } }
;                     u32x4 w; w.x = cvt_pk(v0[0], v0[1]); w.y = cvt_pk(v0[2], v0[3]); w.z = cvt_pk(v1[0], v1[1]); w.w = cvt_pk(v1[2], v1[3]);
;                     *(u32x4*)(rowp + bj * 128) = w; } }
.LBB0_522:
	v_cvt_pk_bf16_f32 v68, v68, v69
	v_cvt_pk_bf16_f32 v69, v70, v71
	v_cvt_pk_bf16_f32 v70, v64, v65
	s_nop 0
	v_cvt_pk_bf16_f32 v71, v66, v67
	global_store_dwordx4 v[72:73], v[68:71], off offset:256
	s_and_b64 vcc, exec, s[38:39]
	s_waitcnt vmcnt(11)
	v_mov_b32_e32 v64, v149
	v_pk_mul_f32 v[62:63], v[62:63], v[64:65] op_sel_hi:[1,0]
	v_pk_mul_f32 v[66:67], v[60:61], v[64:65] op_sel_hi:[1,0]
	v_pk_mul_f32 v[58:59], v[58:59], v[64:65] op_sel_hi:[1,0]
	v_pk_mul_f32 v[60:61], v[56:57], v[64:65] op_sel_hi:[1,0]
	s_cbranch_vccnz .LBB0_524
	v_mul_f32_e32 v65, 0x3d372713, v61
	v_fma_f32 v65, v61, v65, 1.0
	v_mul_f32_e32 v65, v61, v65
	v_mul_f32_e32 v65, 0x3fcc422a, v65
	v_mul_f32_e32 v65, 0xbfb8aa3b, v65
	v_exp_f32_e32 v65, v65
	v_mul_f32_e32 v57, 0x3d372713, v60
	v_fma_f32 v57, v60, v57, 1.0
	v_mul_f32_e32 v57, v60, v57
	v_mul_f32_e32 v57, 0x3fcc422a, v57
	v_add_f32_e32 v65, 1.0, v65
	v_mul_f32_e32 v57, 0xbfb8aa3b, v57
	v_rcp_f32_e32 v69, v65
	v_mul_f32_e32 v65, 0x3d372713, v62
	v_exp_f32_e32 v57, v57
	v_fma_f32 v65, v62, v65, 1.0
	v_mul_f32_e32 v65, v62, v65
	v_mul_f32_e32 v65, 0x3fcc422a, v65
	v_mul_f32_e32 v65, 0xbfb8aa3b, v65
	v_add_f32_e32 v57, 1.0, v57
	v_exp_f32_e32 v65, v65
	v_mul_f32_e32 v56, 0x3d372713, v66
	v_rcp_f32_e32 v68, v57
	v_mul_f32_e32 v57, 0x3d372713, v67
	v_fma_f32 v56, v66, v56, 1.0
	v_fma_f32 v57, v67, v57, 1.0
	v_mul_f32_e32 v56, v66, v56
	v_mul_f32_e32 v57, v67, v57
	v_mul_f32_e32 v56, 0x3fcc422a, v56
	v_mul_f32_e32 v57, 0x3fcc422a, v57
	v_add_f32_e32 v65, 1.0, v65
	v_mul_f32_e32 v56, 0xbfb8aa3b, v56
	v_mul_f32_e32 v57, 0xbfb8aa3b, v57
	v_rcp_f32_e32 v70, v65
	v_mul_f32_e32 v65, 0x3d372713, v58
	v_exp_f32_e32 v56, v56
	v_exp_f32_e32 v57, v57
	v_fma_f32 v65, v58, v65, 1.0
	v_mul_f32_e32 v65, v58, v65
	v_mul_f32_e32 v65, 0x3fcc422a, v65
	v_mul_f32_e32 v65, 0xbfb8aa3b, v65
	v_add_f32_e32 v56, 1.0, v56
	v_add_f32_e32 v57, 1.0, v57
	v_exp_f32_e32 v65, v65
	v_rcp_f32_e32 v56, v56
	v_rcp_f32_e32 v57, v57
	v_pk_mul_f32 v[60:61], v[60:61], v[68:69]
	v_add_f32_e32 v65, 1.0, v65
	v_rcp_f32_e32 v72, v65
	v_mul_f32_e32 v65, 0x3d372713, v63
	v_pk_mul_f32 v[66:67], v[66:67], v[56:57]
	v_mul_f32_e32 v56, 0x3d372713, v59
	v_fma_f32 v65, v63, v65, 1.0
	v_fma_f32 v56, v59, v56, 1.0
	v_mul_f32_e32 v65, v63, v65
	v_mul_f32_e32 v56, v59, v56
	v_mul_f32_e32 v65, 0x3fcc422a, v65
	v_mul_f32_e32 v56, 0x3fcc422a, v56
	v_mul_f32_e32 v65, 0xbfb8aa3b, v65
	v_mul_f32_e32 v56, 0xbfb8aa3b, v56
	v_exp_f32_e32 v65, v65
	v_exp_f32_e32 v56, v56
	v_add_f32_e32 v65, 1.0, v65
	v_add_f32_e32 v56, 1.0, v56
	v_rcp_f32_e32 v71, v65
	v_rcp_f32_e32 v73, v56
	v_pk_mul_f32 v[62:63], v[62:63], v[70:71]
	v_pk_mul_f32 v[58:59], v[58:59], v[72:73]

; __device__ __forceinline__ unsigned cvt_pk(float lo, float hi) { unsigned r; asm volatile("v_cvt_pk_bf16_f32 %0, %1, %2" : "=v"(r) : "v"(lo), "v"(hi)); return r; }
;     __device__ __forceinline__ void operator()(const f32x4 (&acc)[2][2][4][2], const pg8::Unit& u, int wr, int wc, int fr, int fq) const {
;     ...
;             for (int m = 0; m < 4; ++m) { bf16raw* rowp = base + (size_t)(row0 + ai * 128 + m * 16) * DM + col0; const float sc = rs[row0 + ai * 128 + m * 16];
; #pragma unroll
;                 for (int bj = 0; bj < 2; ++bj) { f32x4 v0 = acc[ai][bj][m][0] * sc, v1 = acc[ai][bj][m][1] * sc;
;                     if (isy) {
; #pragma unroll
;                         for (int i = 0; i < 4; ++i) { v0[i] = gelu_tanh(v0[i]); v1[i] = gelu_tanh(v1[i]); } }
;                     u32x4 w; w.x = cvt_pk(v0[0], v0[1]); w.y = cvt_pk(v0[2], v0[3]); w.z = cvt_pk(v1[0], v1[1]); w.w = cvt_pk(v1[2], v1[3]);
;                     *(u32x4*)(rowp + bj * 128) = w; } }
.LBB0_526:
	v_lshl_add_u64 v[56:57], v[56:57], 0, s[14:15]
	v_cvt_pk_bf16_f32 v52, v52, v53
	v_cvt_pk_bf16_f32 v53, v54, v55
	v_cvt_pk_bf16_f32 v54, v48, v49
	v_cvt_pk_bf16_f32 v55, v50, v51
	global_store_dwordx4 v[56:57], v[52:55], off offset:256
	s_and_b64 vcc, exec, s[38:39]
	s_waitcnt vmcnt(12)
	v_mov_b32_e32 v48, v150
	v_pk_mul_f32 v[46:47], v[46:47], v[48:49] op_sel_hi:[1,0]
	v_pk_mul_f32 v[50:51], v[44:45], v[48:49] op_sel_hi:[1,0]
	v_pk_mul_f32 v[42:43], v[42:43], v[48:49] op_sel_hi:[1,0]
	v_pk_mul_f32 v[44:45], v[40:41], v[48:49] op_sel_hi:[1,0]
	s_cbranch_vccnz .LBB0_528
	v_mul_f32_e32 v49, 0x3d372713, v45
	v_fma_f32 v49, v45, v49, 1.0
	v_mul_f32_e32 v49, v45, v49
	v_mul_f32_e32 v49, 0x3fcc422a, v49
	v_mul_f32_e32 v49, 0xbfb8aa3b, v49
	v_exp_f32_e32 v49, v49
	v_mul_f32_e32 v41, 0x3d372713, v44
	v_fma_f32 v41, v44, v41, 1.0
	v_mul_f32_e32 v41, v44, v41
	v_mul_f32_e32 v41, 0x3fcc422a, v41
	v_add_f32_e32 v49, 1.0, v49
	v_mul_f32_e32 v41, 0xbfb8aa3b, v41
	v_rcp_f32_e32 v53, v49
	v_mul_f32_e32 v49, 0x3d372713, v46
	v_exp_f32_e32 v41, v41
	v_fma_f32 v49, v46, v49, 1.0
	v_mul_f32_e32 v49, v46, v49
	v_mul_f32_e32 v49, 0x3fcc422a, v49
	v_mul_f32_e32 v49, 0xbfb8aa3b, v49
	v_add_f32_e32 v41, 1.0, v41
	v_exp_f32_e32 v49, v49
	v_mul_f32_e32 v40, 0x3d372713, v50
	v_rcp_f32_e32 v52, v41
	v_mul_f32_e32 v41, 0x3d372713, v51
	v_fma_f32 v40, v50, v40, 1.0
	v_fma_f32 v41, v51, v41, 1.0
	v_mul_f32_e32 v40, v50, v40
	v_mul_f32_e32 v41, v51, v41
	v_mul_f32_e32 v40, 0x3fcc422a, v40
	v_mul_f32_e32 v41, 0x3fcc422a, v41
	v_add_f32_e32 v49, 1.0, v49
	v_mul_f32_e32 v40, 0xbfb8aa3b, v40
	v_mul_f32_e32 v41, 0xbfb8aa3b, v41
	v_rcp_f32_e32 v54, v49
	v_mul_f32_e32 v49, 0x3d372713, v42
	v_exp_f32_e32 v40, v40
	v_exp_f32_e32 v41, v41
	v_fma_f32 v49, v42, v49, 1.0
	v_mul_f32_e32 v49, v42, v49
	v_mul_f32_e32 v49, 0x3fcc422a, v49
	v_mul_f32_e32 v49, 0xbfb8aa3b, v49
	v_add_f32_e32 v40, 1.0, v40
	v_add_f32_e32 v41, 1.0, v41
	v_exp_f32_e32 v49, v49
	v_rcp_f32_e32 v40, v40
	v_rcp_f32_e32 v41, v41
	v_pk_mul_f32 v[44:45], v[44:45], v[52:53]
	v_add_f32_e32 v49, 1.0, v49
	v_rcp_f32_e32 v56, v49
	v_mul_f32_e32 v49, 0x3d372713, v47
	v_pk_mul_f32 v[50:51], v[50:51], v[40:41]
	v_mul_f32_e32 v40, 0x3d372713, v43
	v_fma_f32 v49, v47, v49, 1.0
	v_fma_f32 v40, v43, v40, 1.0
	v_mul_f32_e32 v49, v47, v49
	v_mul_f32_e32 v40, v43, v40
	v_mul_f32_e32 v49, 0x3fcc422a, v49
	v_mul_f32_e32 v40, 0x3fcc422a, v40
	v_mul_f32_e32 v49, 0xbfb8aa3b, v49
	v_mul_f32_e32 v40, 0xbfb8aa3b, v40
	v_exp_f32_e32 v49, v49
	v_exp_f32_e32 v40, v40
	v_add_f32_e32 v49, 1.0, v49
	v_add_f32_e32 v40, 1.0, v40
	v_rcp_f32_e32 v55, v49
	v_rcp_f32_e32 v57, v40
	v_pk_mul_f32 v[46:47], v[46:47], v[54:55]
	v_pk_mul_f32 v[42:43], v[42:43], v[56:57]

; __device__ __forceinline__ unsigned cvt_pk(float lo, float hi) { unsigned r; asm volatile("v_cvt_pk_bf16_f32 %0, %1, %2" : "=v"(r) : "v"(lo), "v"(hi)); return r; }
;     __device__ __forceinline__ void operator()(const f32x4 (&acc)[2][2][4][2], const pg8::Unit& u, int wr, int wc, int fr, int fq) const {
;     ...
;             for (int m = 0; m < 4; ++m) { bf16raw* rowp = base + (size_t)(row0 + ai * 128 + m * 16) * DM + col0; const float sc = rs[row0 + ai * 128 + m * 16];
; #pragma unroll
;                 for (int bj = 0; bj < 2; ++bj) { f32x4 v0 = acc[ai][bj][m][0] * sc, v1 = acc[ai][bj][m][1] * sc;
;                     if (isy) {
; #pragma unroll
;                         for (int i = 0; i < 4; ++i) { v0[i] = gelu_tanh(v0[i]); v1[i] = gelu_tanh(v1[i]); } }
;                     u32x4 w; w.x = cvt_pk(v0[0], v0[1]); w.y = cvt_pk(v0[2], v0[3]); w.z = cvt_pk(v1[0], v1[1]); w.w = cvt_pk(v1[2], v1[3]);
;                     *(u32x4*)(rowp + bj * 128) = w; } }
.LBB0_530:
	v_lshl_add_u64 v[40:41], v[40:41], 0, s[18:19]
	v_cvt_pk_bf16_f32 v36, v36, v37
	v_cvt_pk_bf16_f32 v37, v38, v39
	v_cvt_pk_bf16_f32 v38, v32, v33
	v_cvt_pk_bf16_f32 v39, v34, v35
	global_store_dwordx4 v[40:41], v[36:39], off offset:256
	s_and_b64 vcc, exec, s[38:39]
	s_waitcnt vmcnt(13)
	v_mov_b32_e32 v32, v151
	v_pk_mul_f32 v[30:31], v[30:31], v[32:33] op_sel_hi:[1,0]
	v_pk_mul_f32 v[34:35], v[28:29], v[32:33] op_sel_hi:[1,0]
	v_pk_mul_f32 v[26:27], v[26:27], v[32:33] op_sel_hi:[1,0]
	v_pk_mul_f32 v[28:29], v[24:25], v[32:33] op_sel_hi:[1,0]
	s_cbranch_vccnz .LBB0_532
	v_mul_f32_e32 v33, 0x3d372713, v29
	v_fma_f32 v33, v29, v33, 1.0
	v_mul_f32_e32 v33, v29, v33
	v_mul_f32_e32 v33, 0x3fcc422a, v33
	v_mul_f32_e32 v33, 0xbfb8aa3b, v33
	v_exp_f32_e32 v33, v33
	v_mul_f32_e32 v25, 0x3d372713, v28
	v_fma_f32 v25, v28, v25, 1.0
	v_mul_f32_e32 v25, v28, v25
	v_mul_f32_e32 v25, 0x3fcc422a, v25
	v_add_f32_e32 v33, 1.0, v33
	v_mul_f32_e32 v25, 0xbfb8aa3b, v25
	v_rcp_f32_e32 v37, v33
	v_mul_f32_e32 v33, 0x3d372713, v30
	v_exp_f32_e32 v25, v25
	v_fma_f32 v33, v30, v33, 1.0
	v_mul_f32_e32 v33, v30, v33
	v_mul_f32_e32 v33, 0x3fcc422a, v33
	v_mul_f32_e32 v33, 0xbfb8aa3b, v33
	v_add_f32_e32 v25, 1.0, v25
	v_exp_f32_e32 v33, v33
	v_mul_f32_e32 v24, 0x3d372713, v34
	v_rcp_f32_e32 v36, v25
	v_mul_f32_e32 v25, 0x3d372713, v35
	v_fma_f32 v24, v34, v24, 1.0
	v_fma_f32 v25, v35, v25, 1.0
	v_mul_f32_e32 v24, v34, v24
	v_mul_f32_e32 v25, v35, v25
	v_mul_f32_e32 v24, 0x3fcc422a, v24
	v_mul_f32_e32 v25, 0x3fcc422a, v25
	v_add_f32_e32 v33, 1.0, v33
	v_mul_f32_e32 v24, 0xbfb8aa3b, v24
	v_mul_f32_e32 v25, 0xbfb8aa3b, v25
	v_rcp_f32_e32 v38, v33
	v_mul_f32_e32 v33, 0x3d372713, v26
	v_exp_f32_e32 v24, v24
	v_exp_f32_e32 v25, v25
	v_fma_f32 v33, v26, v33, 1.0
	v_mul_f32_e32 v33, v26, v33
	v_mul_f32_e32 v33, 0x3fcc422a, v33
	v_mul_f32_e32 v33, 0xbfb8aa3b, v33
	v_add_f32_e32 v24, 1.0, v24
	v_add_f32_e32 v25, 1.0, v25
	v_exp_f32_e32 v33, v33
	v_rcp_f32_e32 v24, v24
	v_rcp_f32_e32 v25, v25
	v_pk_mul_f32 v[28:29], v[28:29], v[36:37]
	v_add_f32_e32 v33, 1.0, v33
	v_rcp_f32_e32 v40, v33
	v_mul_f32_e32 v33, 0x3d372713, v31
	v_pk_mul_f32 v[34:35], v[34:35], v[24:25]
	v_mul_f32_e32 v24, 0x3d372713, v27
	v_fma_f32 v33, v31, v33, 1.0
	v_fma_f32 v24, v27, v24, 1.0
	v_mul_f32_e32 v33, v31, v33
	v_mul_f32_e32 v24, v27, v24
	v_mul_f32_e32 v33, 0x3fcc422a, v33
	v_mul_f32_e32 v24, 0x3fcc422a, v24
	v_mul_f32_e32 v33, 0xbfb8aa3b, v33
	v_mul_f32_e32 v24, 0xbfb8aa3b, v24
	v_exp_f32_e32 v33, v33
	v_exp_f32_e32 v24, v24
	v_add_f32_e32 v33, 1.0, v33
	v_add_f32_e32 v24, 1.0, v24
	v_rcp_f32_e32 v39, v33
	v_rcp_f32_e32 v41, v24
	v_pk_mul_f32 v[30:31], v[30:31], v[38:39]
	v_pk_mul_f32 v[26:27], v[26:27], v[40:41]

; __device__ __forceinline__ unsigned cvt_pk(float lo, float hi) { unsigned r; asm volatile("v_cvt_pk_bf16_f32 %0, %1, %2" : "=v"(r) : "v"(lo), "v"(hi)); return r; }
;     __device__ __forceinline__ void operator()(const f32x4 (&acc)[2][2][4][2], const pg8::Unit& u, int wr, int wc, int fr, int fq) const {
;     ...
;             for (int m = 0; m < 4; ++m) { bf16raw* rowp = base + (size_t)(row0 + ai * 128 + m * 16) * DM + col0; const float sc = rs[row0 + ai * 128 + m * 16];
; #pragma unroll
;                 for (int bj = 0; bj < 2; ++bj) { f32x4 v0 = acc[ai][bj][m][0] * sc, v1 = acc[ai][bj][m][1] * sc;
;                     if (isy) {
; #pragma unroll
;                         for (int i = 0; i < 4; ++i) { v0[i] = gelu_tanh(v0[i]); v1[i] = gelu_tanh(v1[i]); } }
;                     u32x4 w; w.x = cvt_pk(v0[0], v0[1]); w.y = cvt_pk(v0[2], v0[3]); w.z = cvt_pk(v1[0], v1[1]); w.w = cvt_pk(v1[2], v1[3]);
;                     *(u32x4*)(rowp + bj * 128) = w; } }
.LBB0_534:
	v_lshl_add_u64 v[24:25], v[24:25], 0, s[20:21]
	v_cvt_pk_bf16_f32 v20, v20, v21
	v_cvt_pk_bf16_f32 v21, v22, v23
	v_cvt_pk_bf16_f32 v22, v16, v17
	v_cvt_pk_bf16_f32 v23, v18, v19
	global_store_dwordx4 v[24:25], v[20:23], off offset:256
	s_and_b64 vcc, exec, s[38:39]
	s_waitcnt vmcnt(14)
	v_mov_b32_e32 v16, v152
	v_pk_mul_f32 v[14:15], v[14:15], v[16:17] op_sel_hi:[1,0]
	v_pk_mul_f32 v[18:19], v[12:13], v[16:17] op_sel_hi:[1,0]
	v_pk_mul_f32 v[10:11], v[10:11], v[16:17] op_sel_hi:[1,0]
	v_pk_mul_f32 v[12:13], v[8:9], v[16:17] op_sel_hi:[1,0]
	s_cbranch_vccnz .LBB0_536
	v_mul_f32_e32 v17, 0x3d372713, v13
	v_fma_f32 v17, v13, v17, 1.0
	v_mul_f32_e32 v17, v13, v17
	v_mul_f32_e32 v17, 0x3fcc422a, v17
	v_mul_f32_e32 v17, 0xbfb8aa3b, v17
	v_exp_f32_e32 v17, v17
	v_mul_f32_e32 v9, 0x3d372713, v12
	v_fma_f32 v9, v12, v9, 1.0
	v_mul_f32_e32 v9, v12, v9
	v_mul_f32_e32 v9, 0x3fcc422a, v9
	v_add_f32_e32 v17, 1.0, v17
	v_mul_f32_e32 v9, 0xbfb8aa3b, v9
	v_rcp_f32_e32 v21, v17
	v_mul_f32_e32 v17, 0x3d372713, v14
	v_exp_f32_e32 v9, v9
	v_fma_f32 v17, v14, v17, 1.0
	v_mul_f32_e32 v17, v14, v17
	v_mul_f32_e32 v17, 0x3fcc422a, v17
	v_mul_f32_e32 v17, 0xbfb8aa3b, v17
	v_add_f32_e32 v9, 1.0, v9
	v_exp_f32_e32 v17, v17
	v_mul_f32_e32 v8, 0x3d372713, v18
	v_rcp_f32_e32 v20, v9
	v_mul_f32_e32 v9, 0x3d372713, v19
	v_fma_f32 v8, v18, v8, 1.0
	v_fma_f32 v9, v19, v9, 1.0
	v_mul_f32_e32 v8, v18, v8
	v_mul_f32_e32 v9, v19, v9
	v_mul_f32_e32 v8, 0x3fcc422a, v8
	v_mul_f32_e32 v9, 0x3fcc422a, v9
	v_add_f32_e32 v17, 1.0, v17
	v_mul_f32_e32 v8, 0xbfb8aa3b, v8
	v_mul_f32_e32 v9, 0xbfb8aa3b, v9
	v_rcp_f32_e32 v22, v17
	v_mul_f32_e32 v17, 0x3d372713, v10
	v_exp_f32_e32 v8, v8
	v_exp_f32_e32 v9, v9
	v_fma_f32 v17, v10, v17, 1.0
	v_mul_f32_e32 v17, v10, v17
	v_mul_f32_e32 v17, 0x3fcc422a, v17
	v_mul_f32_e32 v17, 0xbfb8aa3b, v17
	v_add_f32_e32 v8, 1.0, v8
	v_add_f32_e32 v9, 1.0, v9
	v_exp_f32_e32 v17, v17
	v_rcp_f32_e32 v8, v8
	v_rcp_f32_e32 v9, v9
	v_pk_mul_f32 v[12:13], v[12:13], v[20:21]
	v_add_f32_e32 v17, 1.0, v17
	v_rcp_f32_e32 v24, v17
	v_mul_f32_e32 v17, 0x3d372713, v15
	v_pk_mul_f32 v[18:19], v[18:19], v[8:9]
	v_mul_f32_e32 v8, 0x3d372713, v11
	v_fma_f32 v17, v15, v17, 1.0
	v_fma_f32 v8, v11, v8, 1.0
	v_mul_f32_e32 v17, v15, v17
	v_mul_f32_e32 v8, v11, v8
	v_mul_f32_e32 v17, 0x3fcc422a, v17
	v_mul_f32_e32 v8, 0x3fcc422a, v8
	v_mul_f32_e32 v17, 0xbfb8aa3b, v17
	v_mul_f32_e32 v8, 0xbfb8aa3b, v8
	v_exp_f32_e32 v17, v17
	v_exp_f32_e32 v8, v8
	v_add_f32_e32 v17, 1.0, v17
	v_add_f32_e32 v8, 1.0, v8
	v_rcp_f32_e32 v23, v17
	v_rcp_f32_e32 v25, v8
	v_pk_mul_f32 v[14:15], v[14:15], v[22:23]
	v_pk_mul_f32 v[10:11], v[10:11], v[24:25]

; __device__ __forceinline__ unsigned cvt_pk(float lo, float hi) { unsigned r; asm volatile("v_cvt_pk_bf16_f32 %0, %1, %2" : "=v"(r) : "v"(lo), "v"(hi)); return r; }
;     __device__ __forceinline__ void operator()(const f32x4 (&acc)[2][2][4][2], const pg8::Unit& u, int wr, int wc, int fr, int fq) const {
;         const int row0 = u.pm * 256 + wr * 64 + fr, col0 = u.pn * 128 + wc * 32 + 8 * fq;
; #pragma unroll
;         for (int ai = 0; ai < 2; ++ai)
; #pragma unroll
;             for (int m = 0; m < 4; ++m) { bf16raw* rowp = O + (size_t)(row0 + ai * 128 + m * 16) * DFF + col0; const float sc = rs[row0 + ai * 128 + m * 16];
;                 unsigned wv[4];
; #pragma unroll
;                 for (int n = 0; n < 2; ++n)
; #pragma unroll
;                     for (int ip = 0; ip < 4; ip += 2) {
;                         const f32x2 g = (f32x2){acc[ai][0][m][n][ip], acc[ai][0][m][n][ip + 1]} * sc, up = (f32x2){acc[ai][1][m][n][ip], acc[ai][1][m][n][ip + 1]} * sc;
;                         const f32x2 t = g * (-1.4426950408889634f);
;                         f32x2 ex; ex.x = __builtin_amdgcn_exp2f(t.x); ex.y = __builtin_amdgcn_exp2f(t.y);
;                         ex = ex + 1.0f;
;                         f32x2 rc; rc.x = __builtin_amdgcn_rcpf(ex.x); rc.y = __builtin_amdgcn_rcpf(ex.y);
;                         const f32x2 r = g * rc * up;
;                         wv[n * 2 + (ip >> 1)] = cvt_pk(r.x, r.y); }
;                 u32x4 w; w.x = wv[0]; w.y = wv[1]; w.z = wv[2]; w.w = wv[3];
;                 *(u32x4*)rowp = w; }
.LBB0_1085:
	v_add_u32_e32 v130, s89, v195
	v_ashrrev_i32_e32 v131, 31, v130
	v_lshl_add_u64 v[134:135], v[130:131], 2, s[20:21]
	global_load_dword v128, v[134:135], off
	global_load_dword v146, v[134:135], off offset:64
	global_load_dword v147, v[134:135], off offset:128
	global_load_dword v148, v[134:135], off offset:192
	global_load_dword v149, v[134:135], off offset:512
	global_load_dword v150, v[134:135], off offset:576
	global_load_dword v151, v[134:135], off offset:640
	global_load_dword v152, v[134:135], off offset:704
	v_readlane_b32 s2, v255, 42
	v_lshl_or_b32 v136, s80, 7, v227
	v_readlane_b32 s3, v255, 43
	v_ashrrev_i32_e32 v137, 31, v136
	s_mov_b64 s[28:29], -1
	v_mov_b64_e32 v[132:133], s[2:3]
	v_mad_i64_i32 v[138:139], s[2:3], v130, s10, v[132:133]
	s_andn2_b64 vcc, exec, s[36:37]
	s_waitcnt vmcnt(7)
	v_pk_mul_f32 v[124:125], v[124:125], v[128:129] op_sel_hi:[1,0]
	s_nop 0
	v_pk_mul_f32 v[140:141], v[124:125], s[14:15] op_sel_hi:[1,0]
	v_pk_mul_f32 v[116:117], v[116:117], v[128:129] op_sel_hi:[1,0]
	v_exp_f32_e32 v140, v140
	v_exp_f32_e32 v141, v141
	v_pk_mul_f32 v[118:119], v[118:119], v[128:129] op_sel_hi:[1,0]
	v_pk_mul_f32 v[112:113], v[112:113], v[128:129] op_sel_hi:[1,0]
	v_pk_mul_f32 v[114:115], v[114:115], v[128:129] op_sel_hi:[1,0]
	v_pk_add_f32 v[140:141], v[140:141], 1.0 op_sel_hi:[1,0]
	s_nop 0
	v_rcp_f32_e32 v140, v140
	v_rcp_f32_e32 v141, v141
	s_nop 0
	v_pk_mul_f32 v[124:125], v[124:125], v[140:141]
	s_nop 0
	v_pk_mul_f32 v[116:117], v[116:117], v[124:125]
	v_pk_mul_f32 v[124:125], v[126:127], v[128:129] op_sel_hi:[1,0]
	v_cvt_pk_bf16_f32 v116, v116, v117
	s_nop 0
	v_pk_mul_f32 v[126:127], v[124:125], s[14:15] op_sel_hi:[1,0]
	s_nop 0
	v_exp_f32_e32 v126, v126
	v_exp_f32_e32 v127, v127
	s_nop 0
	v_pk_add_f32 v[126:127], v[126:127], 1.0 op_sel_hi:[1,0]
	s_nop 0
	v_rcp_f32_e32 v126, v126
	v_rcp_f32_e32 v127, v127
	s_nop 0
	v_pk_mul_f32 v[124:125], v[124:125], v[126:127]
	s_nop 0
	v_pk_mul_f32 v[118:119], v[118:119], v[124:125]
	s_nop 0
	v_cvt_pk_bf16_f32 v117, v118, v119
	v_pk_mul_f32 v[118:119], v[120:121], v[128:129] op_sel_hi:[1,0]
	s_nop 0
	v_pk_mul_f32 v[120:121], v[118:119], s[14:15] op_sel_hi:[1,0]
	s_nop 0
	v_exp_f32_e32 v120, v120
	v_exp_f32_e32 v121, v121
	s_nop 0
	v_pk_add_f32 v[120:121], v[120:121], 1.0 op_sel_hi:[1,0]
	s_nop 0
	v_rcp_f32_e32 v120, v120
	v_rcp_f32_e32 v121, v121
	s_nop 0
	v_pk_mul_f32 v[118:119], v[118:119], v[120:121]
	s_nop 0
	v_pk_mul_f32 v[112:113], v[112:113], v[118:119]
	s_nop 0
	v_cvt_pk_bf16_f32 v118, v112, v113
	v_pk_mul_f32 v[112:113], v[122:123], v[128:129] op_sel_hi:[1,0]
	s_nop 0
	v_pk_mul_f32 v[120:121], v[112:113], s[14:15] op_sel_hi:[1,0]
	s_nop 0
	v_exp_f32_e32 v120, v120
	v_exp_f32_e32 v121, v121
	s_nop 0
	v_pk_add_f32 v[120:121], v[120:121], 1.0 op_sel_hi:[1,0]
	s_nop 0
	v_rcp_f32_e32 v120, v120
	v_rcp_f32_e32 v121, v121
	s_nop 0
	v_pk_mul_f32 v[112:113], v[112:113], v[120:121]
	s_nop 0
	v_pk_mul_f32 v[112:113], v[114:115], v[112:113]
	s_nop 0
	v_cvt_pk_bf16_f32 v119, v112, v113
	v_lshlrev_b64 v[112:113], 1, v[136:137]
	v_lshl_add_u64 v[114:115], v[138:139], 0, v[112:113]
	global_store_dwordx4 v[114:115], v[116:119], off
	v_or_b32_e32 v114, 16, v130
	v_mad_i64_i32 v[114:115], s[2:3], v114, s10, v[132:133]
	s_waitcnt vmcnt(7)
	v_mov_b32_e32 v116, v146
	v_pk_mul_f32 v[108:109], v[108:109], v[116:117] op_sel_hi:[1,0]
	s_nop 0
	v_pk_mul_f32 v[118:119], v[108:109], s[14:15] op_sel_hi:[1,0]
	v_pk_mul_f32 v[100:101], v[100:101], v[116:117] op_sel_hi:[1,0]
	v_exp_f32_e32 v118, v118
	v_exp_f32_e32 v119, v119
	v_pk_mul_f32 v[102:103], v[102:103], v[116:117] op_sel_hi:[1,0]
	v_pk_mul_f32 v[96:97], v[96:97], v[116:117] op_sel_hi:[1,0]
	v_pk_mul_f32 v[98:99], v[98:99], v[116:117] op_sel_hi:[1,0]
	v_pk_add_f32 v[118:119], v[118:119], 1.0 op_sel_hi:[1,0]
	s_nop 0
	v_rcp_f32_e32 v118, v118
	v_rcp_f32_e32 v119, v119
	s_nop 0
	v_pk_mul_f32 v[108:109], v[108:109], v[118:119]
	s_nop 0
	v_pk_mul_f32 v[100:101], v[100:101], v[108:109]
	v_pk_mul_f32 v[108:109], v[110:111], v[116:117] op_sel_hi:[1,0]
	v_cvt_pk_bf16_f32 v100, v100, v101
	s_nop 0
	v_pk_mul_f32 v[110:111], v[108:109], s[14:15] op_sel_hi:[1,0]
	s_nop 0
	v_exp_f32_e32 v110, v110
	v_exp_f32_e32 v111, v111
	s_nop 0
	v_pk_add_f32 v[110:111], v[110:111], 1.0 op_sel_hi:[1,0]
	s_nop 0
	v_rcp_f32_e32 v110, v110
	v_rcp_f32_e32 v111, v111
	s_nop 0
	v_pk_mul_f32 v[108:109], v[108:109], v[110:111]
	s_nop 0
	v_pk_mul_f32 v[102:103], v[102:103], v[108:109]
	s_nop 0
	v_cvt_pk_bf16_f32 v101, v102, v103
	v_pk_mul_f32 v[102:103], v[104:105], v[116:117] op_sel_hi:[1,0]
	s_nop 0
	v_pk_mul_f32 v[104:105], v[102:103], s[14:15] op_sel_hi:[1,0]
	s_nop 0
	v_exp_f32_e32 v104, v104
	v_exp_f32_e32 v105, v105
	s_nop 0
	v_pk_add_f32 v[104:105], v[104:105], 1.0 op_sel_hi:[1,0]
	s_nop 0
	v_rcp_f32_e32 v104, v104
	v_rcp_f32_e32 v105, v105
	s_nop 0
	v_pk_mul_f32 v[102:103], v[102:103], v[104:105]
	s_nop 0
	v_pk_mul_f32 v[96:97], v[96:97], v[102:103]
	s_nop 0
	v_cvt_pk_bf16_f32 v102, v96, v97
	v_pk_mul_f32 v[96:97], v[106:107], v[116:117] op_sel_hi:[1,0]
	s_nop 0
	v_pk_mul_f32 v[104:105], v[96:97], s[14:15] op_sel_hi:[1,0]
	s_nop 0
	v_exp_f32_e32 v104, v104
	v_exp_f32_e32 v105, v105
	s_nop 0
	v_pk_add_f32 v[104:105], v[104:105], 1.0 op_sel_hi:[1,0]
	s_nop 0
	v_rcp_f32_e32 v104, v104
	v_rcp_f32_e32 v105, v105
	s_nop 0
	v_pk_mul_f32 v[96:97], v[96:97], v[104:105]
	s_nop 0
	v_pk_mul_f32 v[96:97], v[98:99], v[96:97]
	s_nop 0
	v_cvt_pk_bf16_f32 v103, v96, v97
	v_lshl_add_u64 v[96:97], v[114:115], 0, v[112:113]
	global_store_dwordx4 v[96:97], v[100:103], off
	v_or_b32_e32 v96, 32, v130
	v_mad_i64_i32 v[96:97], s[2:3], v96, s10, v[132:133]
	s_waitcnt vmcnt(7)
; __device__ __forceinline__ unsigned cvt_pk(float lo, float hi) { unsigned r; asm volatile("v_cvt_pk_bf16_f32 %0, %1, %2" : "=v"(r) : "v"(lo), "v"(hi)); return r; }
;     __device__ __forceinline__ void operator()(const f32x4 (&acc)[2][2][4][2], const pg8::Unit& u, int wr, int wc, int fr, int fq) const {
;         const int row0 = u.pm * 256 + wr * 64 + fr, col0 = u.pn * 128 + wc * 32 + 8 * fq;
; #pragma unroll
;         for (int ai = 0; ai < 2; ++ai)
; #pragma unroll
;             for (int m = 0; m < 4; ++m) { bf16raw* rowp = O + (size_t)(row0 + ai * 128 + m * 16) * DFF + col0; const float sc = rs[row0 + ai * 128 + m * 16];
;                 unsigned wv[4];
; #pragma unroll
;                 for (int n = 0; n < 2; ++n)
; #pragma unroll
;                     for (int ip = 0; ip < 4; ip += 2) {
;                         const f32x2 g = (f32x2){acc[ai][0][m][n][ip], acc[ai][0][m][n][ip + 1]} * sc, up = (f32x2){acc[ai][1][m][n][ip], acc[ai][1][m][n][ip + 1]} * sc;
;                         const f32x2 t = g * (-1.4426950408889634f);
;                         f32x2 ex; ex.x = __builtin_amdgcn_exp2f(t.x); ex.y = __builtin_amdgcn_exp2f(t.y);
;                         ex = ex + 1.0f;
;                         f32x2 rc; rc.x = __builtin_amdgcn_rcpf(ex.x); rc.y = __builtin_amdgcn_rcpf(ex.y);
;                         const f32x2 r = g * rc * up;
;                         wv[n * 2 + (ip >> 1)] = cvt_pk(r.x, r.y); }
;                 u32x4 w; w.x = wv[0]; w.y = wv[1]; w.z = wv[2]; w.w = wv[3];
;                 *(u32x4*)rowp = w; }
	v_mov_b32_e32 v98, v147
	v_pk_mul_f32 v[92:93], v[92:93], v[98:99] op_sel_hi:[1,0]
	s_nop 0
	v_pk_mul_f32 v[100:101], v[92:93], s[14:15] op_sel_hi:[1,0]
	v_pk_mul_f32 v[84:85], v[84:85], v[98:99] op_sel_hi:[1,0]
	v_exp_f32_e32 v100, v100
	v_exp_f32_e32 v101, v101
	v_pk_mul_f32 v[86:87], v[86:87], v[98:99] op_sel_hi:[1,0]
	v_pk_mul_f32 v[80:81], v[80:81], v[98:99] op_sel_hi:[1,0]
	v_pk_mul_f32 v[82:83], v[82:83], v[98:99] op_sel_hi:[1,0]
	v_pk_add_f32 v[100:101], v[100:101], 1.0 op_sel_hi:[1,0]
	s_nop 0
	v_rcp_f32_e32 v100, v100
	v_rcp_f32_e32 v101, v101
	s_nop 0
	v_pk_mul_f32 v[92:93], v[92:93], v[100:101]
	s_nop 0
	v_pk_mul_f32 v[84:85], v[84:85], v[92:93]
	v_pk_mul_f32 v[92:93], v[94:95], v[98:99] op_sel_hi:[1,0]
	v_cvt_pk_bf16_f32 v84, v84, v85
	s_nop 0
	v_pk_mul_f32 v[94:95], v[92:93], s[14:15] op_sel_hi:[1,0]
	s_nop 0
	v_exp_f32_e32 v94, v94
	v_exp_f32_e32 v95, v95
	s_nop 0
	v_pk_add_f32 v[94:95], v[94:95], 1.0 op_sel_hi:[1,0]
	s_nop 0
	v_rcp_f32_e32 v94, v94
	v_rcp_f32_e32 v95, v95
	s_nop 0
	v_pk_mul_f32 v[92:93], v[92:93], v[94:95]
	s_nop 0
	v_pk_mul_f32 v[86:87], v[86:87], v[92:93]
	s_nop 0
	v_cvt_pk_bf16_f32 v85, v86, v87
	v_pk_mul_f32 v[86:87], v[88:89], v[98:99] op_sel_hi:[1,0]
	s_nop 0
	v_pk_mul_f32 v[88:89], v[86:87], s[14:15] op_sel_hi:[1,0]
	s_nop 0
	v_exp_f32_e32 v88, v88
	v_exp_f32_e32 v89, v89
	s_nop 0
	v_pk_add_f32 v[88:89], v[88:89], 1.0 op_sel_hi:[1,0]
	s_nop 0
	v_rcp_f32_e32 v88, v88
	v_rcp_f32_e32 v89, v89
	s_nop 0
	v_pk_mul_f32 v[86:87], v[86:87], v[88:89]
	s_nop 0
	v_pk_mul_f32 v[80:81], v[80:81], v[86:87]
	s_nop 0
	v_cvt_pk_bf16_f32 v86, v80, v81
	v_pk_mul_f32 v[80:81], v[90:91], v[98:99] op_sel_hi:[1,0]
	s_nop 0
	v_pk_mul_f32 v[88:89], v[80:81], s[14:15] op_sel_hi:[1,0]
	s_nop 0
	v_exp_f32_e32 v88, v88
	v_exp_f32_e32 v89, v89
	s_nop 0
	v_pk_add_f32 v[88:89], v[88:89], 1.0 op_sel_hi:[1,0]
	s_nop 0
	v_rcp_f32_e32 v88, v88
	v_rcp_f32_e32 v89, v89
	s_nop 0
	v_pk_mul_f32 v[80:81], v[80:81], v[88:89]
	s_nop 0
	v_pk_mul_f32 v[80:81], v[82:83], v[80:81]
	s_nop 0
	v_cvt_pk_bf16_f32 v87, v80, v81
	v_lshl_add_u64 v[80:81], v[96:97], 0, v[112:113]
	global_store_dwordx4 v[80:81], v[84:87], off
	v_or_b32_e32 v80, 48, v130
	v_mad_i64_i32 v[80:81], s[2:3], v80, s10, v[132:133]
	s_waitcnt vmcnt(7)
	v_mov_b32_e32 v82, v148
	v_pk_mul_f32 v[76:77], v[76:77], v[82:83] op_sel_hi:[1,0]
	s_nop 0
	v_pk_mul_f32 v[84:85], v[76:77], s[14:15] op_sel_hi:[1,0]
	v_pk_mul_f32 v[68:69], v[68:69], v[82:83] op_sel_hi:[1,0]
	v_exp_f32_e32 v84, v84
	v_exp_f32_e32 v85, v85
	v_pk_mul_f32 v[70:71], v[70:71], v[82:83] op_sel_hi:[1,0]
	v_pk_mul_f32 v[64:65], v[64:65], v[82:83] op_sel_hi:[1,0]
	v_pk_mul_f32 v[66:67], v[66:67], v[82:83] op_sel_hi:[1,0]
	v_pk_add_f32 v[84:85], v[84:85], 1.0 op_sel_hi:[1,0]
	s_nop 0
	v_rcp_f32_e32 v84, v84
	v_rcp_f32_e32 v85, v85
	s_nop 0
	v_pk_mul_f32 v[76:77], v[76:77], v[84:85]
	s_nop 0
	v_pk_mul_f32 v[68:69], v[68:69], v[76:77]
	v_pk_mul_f32 v[76:77], v[78:79], v[82:83] op_sel_hi:[1,0]
	v_cvt_pk_bf16_f32 v68, v68, v69
	s_nop 0
	v_pk_mul_f32 v[78:79], v[76:77], s[14:15] op_sel_hi:[1,0]
	s_nop 0
	v_exp_f32_e32 v78, v78
	v_exp_f32_e32 v79, v79
	s_nop 0
	v_pk_add_f32 v[78:79], v[78:79], 1.0 op_sel_hi:[1,0]
	s_nop 0
	v_rcp_f32_e32 v78, v78
	v_rcp_f32_e32 v79, v79
	s_nop 0
	v_pk_mul_f32 v[76:77], v[76:77], v[78:79]
	s_nop 0
	v_pk_mul_f32 v[70:71], v[70:71], v[76:77]
	s_nop 0
	v_cvt_pk_bf16_f32 v69, v70, v71
	v_pk_mul_f32 v[70:71], v[72:73], v[82:83] op_sel_hi:[1,0]
	s_nop 0
	v_pk_mul_f32 v[72:73], v[70:71], s[14:15] op_sel_hi:[1,0]
	s_nop 0
	v_exp_f32_e32 v72, v72
	v_exp_f32_e32 v73, v73
	s_nop 0
	v_pk_add_f32 v[72:73], v[72:73], 1.0 op_sel_hi:[1,0]
	s_nop 0
	v_rcp_f32_e32 v72, v72
	v_rcp_f32_e32 v73, v73
	s_nop 0
	v_pk_mul_f32 v[70:71], v[70:71], v[72:73]
	s_nop 0
	v_pk_mul_f32 v[64:65], v[64:65], v[70:71]
	s_nop 0
	v_cvt_pk_bf16_f32 v70, v64, v65
	v_pk_mul_f32 v[64:65], v[74:75], v[82:83] op_sel_hi:[1,0]
	s_nop 0
	v_pk_mul_f32 v[72:73], v[64:65], s[14:15] op_sel_hi:[1,0]
	s_nop 0
	v_exp_f32_e32 v72, v72
	v_exp_f32_e32 v73, v73
	s_nop 0
	v_pk_add_f32 v[72:73], v[72:73], 1.0 op_sel_hi:[1,0]
	s_nop 0
	v_rcp_f32_e32 v72, v72
	v_rcp_f32_e32 v73, v73
	s_nop 0
	v_pk_mul_f32 v[64:65], v[64:65], v[72:73]
	s_nop 0
	v_pk_mul_f32 v[64:65], v[66:67], v[64:65]
	s_nop 0
	v_cvt_pk_bf16_f32 v71, v64, v65
	v_lshl_add_u64 v[64:65], v[80:81], 0, v[112:113]
	global_store_dwordx4 v[64:65], v[68:71], off
	v_add_u32_e32 v64, 0x80, v130
	v_mad_i64_i32 v[64:65], s[2:3], v64, s10, v[132:133]
	s_waitcnt vmcnt(7)
	v_mov_b32_e32 v66, v149
	v_pk_mul_f32 v[60:61], v[60:61], v[66:67] op_sel_hi:[1,0]
	s_nop 0
	v_pk_mul_f32 v[68:69], v[60:61], s[14:15] op_sel_hi:[1,0]
	v_pk_mul_f32 v[56:57], v[56:57], v[66:67] op_sel_hi:[1,0]
	v_exp_f32_e32 v68, v68
	v_exp_f32_e32 v69, v69
	v_pk_mul_f32 v[58:59], v[58:59], v[66:67] op_sel_hi:[1,0]
	v_pk_mul_f32 v[52:53], v[52:53], v[66:67] op_sel_hi:[1,0]
	v_pk_mul_f32 v[48:49], v[48:49], v[66:67] op_sel_hi:[1,0]
	v_pk_add_f32 v[68:69], v[68:69], 1.0 op_sel_hi:[1,0]
	v_pk_mul_f32 v[50:51], v[50:51], v[66:67] op_sel_hi:[1,0]
	v_rcp_f32_e32 v68, v68
	v_rcp_f32_e32 v69, v69
	s_nop 0
	v_pk_mul_f32 v[60:61], v[60:61], v[68:69]
	s_nop 0
	v_pk_mul_f32 v[56:57], v[56:57], v[60:61]
	v_pk_mul_f32 v[60:61], v[62:63], v[66:67] op_sel_hi:[1,0]
	v_cvt_pk_bf16_f32 v56, v56, v57
	s_nop 0
	v_pk_mul_f32 v[62:63], v[60:61], s[14:15] op_sel_hi:[1,0]
	s_nop 0
	v_exp_f32_e32 v62, v62
	v_exp_f32_e32 v63, v63
	s_nop 0
	v_pk_add_f32 v[62:63], v[62:63], 1.0 op_sel_hi:[1,0]
	s_nop 0
	v_rcp_f32_e32 v62, v62
	v_rcp_f32_e32 v63, v63
	s_nop 0
	v_pk_mul_f32 v[60:61], v[60:61], v[62:63]
	s_nop 0
	v_pk_mul_f32 v[58:59], v[58:59], v[60:61]
	s_nop 0
	v_cvt_pk_bf16_f32 v57, v58, v59
	v_pk_mul_f32 v[58:59], v[52:53], s[14:15] op_sel_hi:[1,0]
	s_nop 0
	v_exp_f32_e32 v58, v58
	v_exp_f32_e32 v59, v59
	s_nop 0
	v_pk_add_f32 v[58:59], v[58:59], 1.0 op_sel_hi:[1,0]
	s_nop 0
	v_rcp_f32_e32 v58, v58
	v_rcp_f32_e32 v59, v59
	s_nop 0
	v_pk_mul_f32 v[52:53], v[52:53], v[58:59]
	s_nop 0
	v_pk_mul_f32 v[48:49], v[48:49], v[52:53]
	s_nop 0
	v_cvt_pk_bf16_f32 v58, v48, v49
	v_pk_mul_f32 v[48:49], v[54:55], v[66:67] op_sel_hi:[1,0]
	s_nop 0
	v_pk_mul_f32 v[52:53], v[48:49], s[14:15] op_sel_hi:[1,0]
	s_nop 0
	v_exp_f32_e32 v52, v52
	v_exp_f32_e32 v53, v53
	s_nop 0
	v_pk_add_f32 v[52:53], v[52:53], 1.0 op_sel_hi:[1,0]
	s_nop 0
	v_rcp_f32_e32 v52, v52
	v_rcp_f32_e32 v53, v53
	s_nop 0
	v_pk_mul_f32 v[48:49], v[48:49], v[52:53]
	s_nop 0
	v_pk_mul_f32 v[48:49], v[50:51], v[48:49]
	s_nop 0
	v_cvt_pk_bf16_f32 v59, v48, v49
	v_lshl_add_u64 v[48:49], v[64:65], 0, v[112:113]
	global_store_dwordx4 v[48:49], v[56:59], off
	v_add_u32_e32 v48, 0x90, v130
	v_mad_i64_i32 v[48:49], s[2:3], v48, s10, v[132:133]
	s_waitcnt vmcnt(7)
; __device__ __forceinline__ unsigned cvt_pk(float lo, float hi) { unsigned r; asm volatile("v_cvt_pk_bf16_f32 %0, %1, %2" : "=v"(r) : "v"(lo), "v"(hi)); return r; }
;     __device__ __forceinline__ void operator()(const f32x4 (&acc)[2][2][4][2], const pg8::Unit& u, int wr, int wc, int fr, int fq) const {
;         const int row0 = u.pm * 256 + wr * 64 + fr, col0 = u.pn * 128 + wc * 32 + 8 * fq;
; #pragma unroll
;         for (int ai = 0; ai < 2; ++ai)
; #pragma unroll
;             for (int m = 0; m < 4; ++m) { bf16raw* rowp = O + (size_t)(row0 + ai * 128 + m * 16) * DFF + col0; const float sc = rs[row0 + ai * 128 + m * 16];
;                 unsigned wv[4];
; #pragma unroll
;                 for (int n = 0; n < 2; ++n)
; #pragma unroll
;                     for (int ip = 0; ip < 4; ip += 2) {
;                         const f32x2 g = (f32x2){acc[ai][0][m][n][ip], acc[ai][0][m][n][ip + 1]} * sc, up = (f32x2){acc[ai][1][m][n][ip], acc[ai][1][m][n][ip + 1]} * sc;
;                         const f32x2 t = g * (-1.4426950408889634f);
;                         f32x2 ex; ex.x = __builtin_amdgcn_exp2f(t.x); ex.y = __builtin_amdgcn_exp2f(t.y);
;                         ex = ex + 1.0f;
;                         f32x2 rc; rc.x = __builtin_amdgcn_rcpf(ex.x); rc.y = __builtin_amdgcn_rcpf(ex.y);
;                         const f32x2 r = g * rc * up;
;                         wv[n * 2 + (ip >> 1)] = cvt_pk(r.x, r.y); }
;                 u32x4 w; w.x = wv[0]; w.y = wv[1]; w.z = wv[2]; w.w = wv[3];
;                 *(u32x4*)rowp = w; }
;     }
	v_mov_b32_e32 v50, v150
	v_pk_mul_f32 v[44:45], v[44:45], v[50:51] op_sel_hi:[1,0]
	s_nop 0
	v_pk_mul_f32 v[52:53], v[44:45], s[14:15] op_sel_hi:[1,0]
	v_pk_mul_f32 v[40:41], v[40:41], v[50:51] op_sel_hi:[1,0]
	v_exp_f32_e32 v52, v52
	v_exp_f32_e32 v53, v53
	v_pk_mul_f32 v[42:43], v[42:43], v[50:51] op_sel_hi:[1,0]
	v_pk_mul_f32 v[36:37], v[36:37], v[50:51] op_sel_hi:[1,0]
	v_pk_mul_f32 v[32:33], v[32:33], v[50:51] op_sel_hi:[1,0]
	v_pk_add_f32 v[52:53], v[52:53], 1.0 op_sel_hi:[1,0]
	v_pk_mul_f32 v[34:35], v[34:35], v[50:51] op_sel_hi:[1,0]
	v_rcp_f32_e32 v52, v52
	v_rcp_f32_e32 v53, v53
	s_nop 0
	v_pk_mul_f32 v[44:45], v[44:45], v[52:53]
	s_nop 0
	v_pk_mul_f32 v[40:41], v[40:41], v[44:45]
	v_pk_mul_f32 v[44:45], v[46:47], v[50:51] op_sel_hi:[1,0]
	v_cvt_pk_bf16_f32 v40, v40, v41
	s_nop 0
	v_pk_mul_f32 v[46:47], v[44:45], s[14:15] op_sel_hi:[1,0]
	s_nop 0
	v_exp_f32_e32 v46, v46
	v_exp_f32_e32 v47, v47
	s_nop 0
	v_pk_add_f32 v[46:47], v[46:47], 1.0 op_sel_hi:[1,0]
	s_nop 0
	v_rcp_f32_e32 v46, v46
	v_rcp_f32_e32 v47, v47
	s_nop 0
	v_pk_mul_f32 v[44:45], v[44:45], v[46:47]
	s_nop 0
	v_pk_mul_f32 v[42:43], v[42:43], v[44:45]
	s_nop 0
	v_cvt_pk_bf16_f32 v41, v42, v43
	v_pk_mul_f32 v[42:43], v[36:37], s[14:15] op_sel_hi:[1,0]
	s_nop 0
	v_exp_f32_e32 v42, v42
	v_exp_f32_e32 v43, v43
	s_nop 0
	v_pk_add_f32 v[42:43], v[42:43], 1.0 op_sel_hi:[1,0]
	s_nop 0
	v_rcp_f32_e32 v42, v42
	v_rcp_f32_e32 v43, v43
	s_nop 0
	v_pk_mul_f32 v[36:37], v[36:37], v[42:43]
	s_nop 0
	v_pk_mul_f32 v[32:33], v[32:33], v[36:37]
	s_nop 0
	v_cvt_pk_bf16_f32 v42, v32, v33
	v_pk_mul_f32 v[32:33], v[38:39], v[50:51] op_sel_hi:[1,0]
	s_nop 0
	v_pk_mul_f32 v[36:37], v[32:33], s[14:15] op_sel_hi:[1,0]
	s_nop 0
	v_exp_f32_e32 v36, v36
	v_exp_f32_e32 v37, v37
	s_nop 0
	v_pk_add_f32 v[36:37], v[36:37], 1.0 op_sel_hi:[1,0]
	s_nop 0
	v_rcp_f32_e32 v36, v36
	v_rcp_f32_e32 v37, v37
	s_nop 0
	v_pk_mul_f32 v[32:33], v[32:33], v[36:37]
	s_nop 0
	v_pk_mul_f32 v[32:33], v[34:35], v[32:33]
	s_nop 0
	v_cvt_pk_bf16_f32 v43, v32, v33
	v_lshl_add_u64 v[32:33], v[48:49], 0, v[112:113]
	global_store_dwordx4 v[32:33], v[40:43], off
	v_add_u32_e32 v32, 0xa0, v130
	v_mad_i64_i32 v[32:33], s[2:3], v32, s10, v[132:133]
	s_waitcnt vmcnt(7)
	v_mov_b32_e32 v34, v151
	v_pk_mul_f32 v[28:29], v[28:29], v[34:35] op_sel_hi:[1,0]
	s_nop 0
	v_pk_mul_f32 v[36:37], v[28:29], s[14:15] op_sel_hi:[1,0]
	v_pk_mul_f32 v[24:25], v[24:25], v[34:35] op_sel_hi:[1,0]
	v_exp_f32_e32 v36, v36
	v_exp_f32_e32 v37, v37
	v_pk_mul_f32 v[26:27], v[26:27], v[34:35] op_sel_hi:[1,0]
	v_pk_mul_f32 v[20:21], v[20:21], v[34:35] op_sel_hi:[1,0]
	v_pk_mul_f32 v[16:17], v[16:17], v[34:35] op_sel_hi:[1,0]
	v_pk_add_f32 v[36:37], v[36:37], 1.0 op_sel_hi:[1,0]
	v_pk_mul_f32 v[18:19], v[18:19], v[34:35] op_sel_hi:[1,0]
	v_rcp_f32_e32 v36, v36
	v_rcp_f32_e32 v37, v37
	s_nop 0
	v_pk_mul_f32 v[28:29], v[28:29], v[36:37]
	s_nop 0
	v_pk_mul_f32 v[24:25], v[24:25], v[28:29]
	v_pk_mul_f32 v[28:29], v[30:31], v[34:35] op_sel_hi:[1,0]
	v_cvt_pk_bf16_f32 v24, v24, v25
	s_nop 0
	v_pk_mul_f32 v[30:31], v[28:29], s[14:15] op_sel_hi:[1,0]
	s_nop 0
	v_exp_f32_e32 v30, v30
	v_exp_f32_e32 v31, v31
	s_nop 0
	v_pk_add_f32 v[30:31], v[30:31], 1.0 op_sel_hi:[1,0]
	s_nop 0
	v_rcp_f32_e32 v30, v30
	v_rcp_f32_e32 v31, v31
	s_nop 0
	v_pk_mul_f32 v[28:29], v[28:29], v[30:31]
	s_nop 0
	v_pk_mul_f32 v[26:27], v[26:27], v[28:29]
	s_nop 0
	v_cvt_pk_bf16_f32 v25, v26, v27
	v_pk_mul_f32 v[26:27], v[20:21], s[14:15] op_sel_hi:[1,0]
	s_nop 0
	v_exp_f32_e32 v26, v26
	v_exp_f32_e32 v27, v27
	s_nop 0
	v_pk_add_f32 v[26:27], v[26:27], 1.0 op_sel_hi:[1,0]
	s_nop 0
	v_rcp_f32_e32 v26, v26
	v_rcp_f32_e32 v27, v27
	s_nop 0
	v_pk_mul_f32 v[20:21], v[20:21], v[26:27]
	s_nop 0
	v_pk_mul_f32 v[16:17], v[16:17], v[20:21]
	s_nop 0
	v_cvt_pk_bf16_f32 v26, v16, v17
	v_pk_mul_f32 v[16:17], v[22:23], v[34:35] op_sel_hi:[1,0]
	s_nop 0
	v_pk_mul_f32 v[20:21], v[16:17], s[14:15] op_sel_hi:[1,0]
	s_nop 0
	v_exp_f32_e32 v20, v20
	v_exp_f32_e32 v21, v21
	s_nop 0
	v_pk_add_f32 v[20:21], v[20:21], 1.0 op_sel_hi:[1,0]
	s_nop 0
	v_rcp_f32_e32 v20, v20
	v_rcp_f32_e32 v21, v21
	s_nop 0
	v_pk_mul_f32 v[16:17], v[16:17], v[20:21]
	s_nop 0
	v_pk_mul_f32 v[16:17], v[18:19], v[16:17]
	s_nop 0
	v_cvt_pk_bf16_f32 v27, v16, v17
	v_lshl_add_u64 v[16:17], v[32:33], 0, v[112:113]
	global_store_dwordx4 v[16:17], v[24:27], off
	v_add_u32_e32 v16, 0xb0, v130
	v_mad_i64_i32 v[16:17], s[2:3], v16, s10, v[132:133]
	s_waitcnt vmcnt(7)
	v_mov_b32_e32 v18, v152
	v_pk_mul_f32 v[12:13], v[12:13], v[18:19] op_sel_hi:[1,0]
	s_nop 0
	v_pk_mul_f32 v[20:21], v[12:13], s[14:15] op_sel_hi:[1,0]
	v_pk_mul_f32 v[8:9], v[8:9], v[18:19] op_sel_hi:[1,0]
	v_exp_f32_e32 v20, v20
	v_exp_f32_e32 v21, v21
	v_pk_mul_f32 v[10:11], v[10:11], v[18:19] op_sel_hi:[1,0]
	v_pk_mul_f32 v[4:5], v[4:5], v[18:19] op_sel_hi:[1,0]
	v_pk_mul_f32 v[0:1], v[0:1], v[18:19] op_sel_hi:[1,0]
	v_pk_add_f32 v[20:21], v[20:21], 1.0 op_sel_hi:[1,0]
	v_pk_mul_f32 v[2:3], v[2:3], v[18:19] op_sel_hi:[1,0]
	v_rcp_f32_e32 v20, v20
	v_rcp_f32_e32 v21, v21
	s_nop 0
	v_pk_mul_f32 v[12:13], v[12:13], v[20:21]
	s_nop 0
	v_pk_mul_f32 v[8:9], v[8:9], v[12:13]
	v_pk_mul_f32 v[12:13], v[14:15], v[18:19] op_sel_hi:[1,0]
	v_cvt_pk_bf16_f32 v8, v8, v9
	s_nop 0
	v_pk_mul_f32 v[14:15], v[12:13], s[14:15] op_sel_hi:[1,0]
	s_nop 0
	v_exp_f32_e32 v14, v14
	v_exp_f32_e32 v15, v15
	s_nop 0
	v_pk_add_f32 v[14:15], v[14:15], 1.0 op_sel_hi:[1,0]
	s_nop 0
	v_rcp_f32_e32 v14, v14
	v_rcp_f32_e32 v15, v15
	s_nop 0
	v_pk_mul_f32 v[12:13], v[12:13], v[14:15]
	s_nop 0
	v_pk_mul_f32 v[10:11], v[10:11], v[12:13]
	s_nop 0
	v_cvt_pk_bf16_f32 v9, v10, v11
	v_pk_mul_f32 v[10:11], v[4:5], s[14:15] op_sel_hi:[1,0]
	s_nop 0
	v_exp_f32_e32 v10, v10
	v_exp_f32_e32 v11, v11
	s_nop 0
	v_pk_add_f32 v[10:11], v[10:11], 1.0 op_sel_hi:[1,0]
	s_nop 0
	v_rcp_f32_e32 v10, v10
	v_rcp_f32_e32 v11, v11
	s_nop 0
	v_pk_mul_f32 v[4:5], v[4:5], v[10:11]
	s_nop 0
	v_pk_mul_f32 v[0:1], v[0:1], v[4:5]
	s_nop 0
	v_cvt_pk_bf16_f32 v10, v0, v1
	v_pk_mul_f32 v[0:1], v[6:7], v[18:19] op_sel_hi:[1,0]
	s_nop 0
	v_pk_mul_f32 v[4:5], v[0:1], s[14:15] op_sel_hi:[1,0]
	s_nop 0
	v_exp_f32_e32 v4, v4
	v_exp_f32_e32 v5, v5
	s_nop 0
	v_pk_add_f32 v[4:5], v[4:5], 1.0 op_sel_hi:[1,0]
	s_nop 0
	v_rcp_f32_e32 v4, v4
	v_rcp_f32_e32 v5, v5
	s_nop 0
	v_pk_mul_f32 v[0:1], v[0:1], v[4:5]
	s_nop 0
	v_pk_mul_f32 v[0:1], v[2:3], v[0:1]
	s_nop 0
	v_cvt_pk_bf16_f32 v11, v0, v1
	v_lshl_add_u64 v[0:1], v[16:17], 0, v[112:113]
	global_store_dwordx4 v[0:1], v[8:11], off
	s_cbranch_vccnz .LBB0_1071
	s_andn2_b64 vcc, exec, s[40:41]
	s_cbranch_vccnz .LBB0_1070
	s_barrier
	s_branch .LBB0_1070
